# loop-edge edit: K-loop trip counter/pointer increments and exit compare hoisted in front of the trip's last barrier
# baseline (speedup 1.0000x reference)
.Lrlx2b_done:
	s_mov_b32 s99, 0
	s_waitcnt lgkmcnt(0)
	s_barrier
	s_setprio 1
	s_waitcnt lgkmcnt(0)
	v_mfma_f32_16x16x32_f16 v[60:63], v[132:135], v[186:189], v[60:63]
	v_mfma_f32_16x16x32_f16 v[56:59], v[140:143], v[186:189], v[56:59]
	v_mfma_f32_16x16x32_f16 v[44:47], v[132:135], v[194:197], v[44:47]
	v_mfma_f32_16x16x32_f16 v[40:43], v[140:143], v[194:197], v[40:43]
	v_mfma_f32_16x16x32_f16 v[28:31], v[132:135], v[202:205], v[28:31]
	v_mfma_f32_16x16x32_f16 v[24:27], v[140:143], v[202:205], v[24:27]
	v_mfma_f32_16x16x32_f16 v[12:15], v[132:135], v[212:215], v[12:15]
	v_mfma_f32_16x16x32_f16 v[8:11], v[140:143], v[212:215], v[8:11]
	v_mfma_f32_16x16x32_f16 v[60:63], v[136:139], v[190:193], v[60:63]
	v_mfma_f32_16x16x32_f16 v[56:59], v[160:163], v[190:193], v[56:59]
	v_mfma_f32_16x16x32_f16 v[44:47], v[136:139], v[198:201], v[44:47]
	v_mfma_f32_16x16x32_f16 v[40:43], v[160:163], v[198:201], v[40:43]
	v_mfma_f32_16x16x32_f16 v[28:31], v[136:139], v[206:209], v[28:31]
	v_mfma_f32_16x16x32_f16 v[24:27], v[160:163], v[206:209], v[24:27]
	v_mfma_f32_16x16x32_f16 v[12:15], v[136:139], v[216:219], v[12:15]
	v_mfma_f32_16x16x32_f16 v[8:11], v[160:163], v[216:219], v[8:11]
	s_setprio 0
	s_setprio 1
	v_mfma_f32_16x16x32_f16 v[52:55], v[164:167], v[186:189], v[52:55]
	v_mfma_f32_16x16x32_f16 v[48:51], v[178:181], v[186:189], v[48:51]
	v_mfma_f32_16x16x32_f16 v[36:39], v[164:167], v[194:197], v[36:39]
	v_mfma_f32_16x16x32_f16 v[32:35], v[178:181], v[194:197], v[32:35]
	v_mfma_f32_16x16x32_f16 v[20:23], v[164:167], v[202:205], v[20:23]
	v_mfma_f32_16x16x32_f16 v[16:19], v[178:181], v[202:205], v[16:19]
	v_mfma_f32_16x16x32_f16 v[4:7], v[164:167], v[212:215], v[4:7]
	v_mfma_f32_16x16x32_f16 v[0:3], v[178:181], v[212:215], v[0:3]
	v_mfma_f32_16x16x32_f16 v[52:55], v[174:177], v[190:193], v[52:55]
	v_mfma_f32_16x16x32_f16 v[48:51], v[182:185], v[190:193], v[48:51]
	v_mfma_f32_16x16x32_f16 v[36:39], v[174:177], v[198:201], v[36:39]
	v_mfma_f32_16x16x32_f16 v[32:35], v[182:185], v[198:201], v[32:35]
	v_mfma_f32_16x16x32_f16 v[20:23], v[174:177], v[206:209], v[20:23]
	v_mfma_f32_16x16x32_f16 v[16:19], v[182:185], v[206:209], v[16:19]
	v_mfma_f32_16x16x32_f16 v[4:7], v[174:177], v[216:219], v[4:7]
	v_mfma_f32_16x16x32_f16 v[0:3], v[182:185], v[216:219], v[0:3]
	s_setprio 0
	s_barrier
	s_add_i32 s91, 0, 0x18000
	s_add_i32 s92, 0, 0x1c000
	v_add_u32_e32 v160, s91, v170
	v_add_u32_e32 v173, s92, v170
	ds_read_b128 v[132:135], v160
	ds_read_b128 v[136:139], v160 offset:1024
	ds_read_b128 v[140:143], v160 offset:2048
	ds_read_b128 v[160:163], v160 offset:3072
	ds_read_b128 v[164:167], v173
	ds_read_b128 v[174:177], v173 offset:1024
	ds_read_b128 v[178:181], v173 offset:2048
	ds_read_b128 v[182:185], v173 offset:3072
	s_add_u32 s76, s76, 0x40000
	s_addc_u32 s77, s77, 0
	s_mov_b32 m0, s68
	v_lshl_add_u64 v[228:229], s[76:77], 0, v[144:145]
	ds_read_b128 v[186:189], v172 offset:32768
	ds_read_b128 v[190:193], v172 offset:33792
	ds_read_b128 v[194:197], v172 offset:34816
	ds_read_b128 v[198:201], v172 offset:35840
	ds_read_b128 v[202:205], v172 offset:36864
	ds_read_b128 v[206:209], v172 offset:37888
	ds_read_b128 v[212:215], v172 offset:38912
	ds_read_b128 v[216:219], v172 offset:39936
	global_load_lds_dwordx4 v[228:229], off
	v_lshl_add_u64 v[228:229], s[76:77], 0, v[148:149]
	s_mov_b32 m0, s69
	s_nop 0
	global_load_lds_dwordx4 v[228:229], off
	s_waitcnt vmcnt(8)
	s_waitcnt lgkmcnt(0)
	s_barrier
	s_setprio 1
	s_waitcnt lgkmcnt(0)
	v_mfma_f32_16x16x32_f16 v[124:127], v[132:135], v[186:189], v[124:127]
	v_mfma_f32_16x16x32_f16 v[120:123], v[140:143], v[186:189], v[120:123]
	v_mfma_f32_16x16x32_f16 v[108:111], v[132:135], v[194:197], v[108:111]
	v_mfma_f32_16x16x32_f16 v[104:107], v[140:143], v[194:197], v[104:107]
	v_mfma_f32_16x16x32_f16 v[92:95], v[132:135], v[202:205], v[92:95]
	v_mfma_f32_16x16x32_f16 v[88:91], v[140:143], v[202:205], v[88:91]
	v_mfma_f32_16x16x32_f16 v[76:79], v[132:135], v[212:215], v[76:79]
	v_mfma_f32_16x16x32_f16 v[72:75], v[140:143], v[212:215], v[72:75]
	v_mfma_f32_16x16x32_f16 v[124:127], v[136:139], v[190:193], v[124:127]
	v_mfma_f32_16x16x32_f16 v[120:123], v[160:163], v[190:193], v[120:123]
	v_mfma_f32_16x16x32_f16 v[108:111], v[136:139], v[198:201], v[108:111]
	v_mfma_f32_16x16x32_f16 v[104:107], v[160:163], v[198:201], v[104:107]
	v_mfma_f32_16x16x32_f16 v[92:95], v[136:139], v[206:209], v[92:95]
	v_mfma_f32_16x16x32_f16 v[88:91], v[160:163], v[206:209], v[88:91]
	v_mfma_f32_16x16x32_f16 v[76:79], v[136:139], v[216:219], v[76:79]
	v_mfma_f32_16x16x32_f16 v[72:75], v[160:163], v[216:219], v[72:75]
	s_setprio 0
	s_setprio 1
	v_mfma_f32_16x16x32_f16 v[116:119], v[164:167], v[186:189], v[116:119]
	v_mfma_f32_16x16x32_f16 v[112:115], v[178:181], v[186:189], v[112:115]
	v_mfma_f32_16x16x32_f16 v[100:103], v[164:167], v[194:197], v[100:103]
	v_mfma_f32_16x16x32_f16 v[96:99], v[178:181], v[194:197], v[96:99]
	v_mfma_f32_16x16x32_f16 v[84:87], v[164:167], v[202:205], v[84:87]
	v_mfma_f32_16x16x32_f16 v[80:83], v[178:181], v[202:205], v[80:83]
	v_mfma_f32_16x16x32_f16 v[68:71], v[164:167], v[212:215], v[68:71]
	v_mfma_f32_16x16x32_f16 v[64:67], v[178:181], v[212:215], v[64:67]
	v_mfma_f32_16x16x32_f16 v[116:119], v[174:177], v[190:193], v[116:119]
	v_mfma_f32_16x16x32_f16 v[112:115], v[182:185], v[190:193], v[112:115]
	v_mfma_f32_16x16x32_f16 v[100:103], v[174:177], v[198:201], v[100:103]
	v_mfma_f32_16x16x32_f16 v[96:99], v[182:185], v[198:201], v[96:99]
	v_mfma_f32_16x16x32_f16 v[84:87], v[174:177], v[206:209], v[84:87]
	v_mfma_f32_16x16x32_f16 v[80:83], v[182:185], v[206:209], v[80:83]
	v_mfma_f32_16x16x32_f16 v[68:71], v[174:177], v[216:219], v[68:71]
	v_mfma_f32_16x16x32_f16 v[64:67], v[182:185], v[216:219], v[64:67]
	s_setprio 0
	s_barrier
	s_add_i32 s76, s91, s35
	v_lshl_add_u64 v[220:221], v[220:221], 0, s[12:13]
	s_mov_b32 m0, s76
	ds_read_b128 v[186:189], v172 offset:49152
	ds_read_b128 v[190:193], v172 offset:50176
	ds_read_b128 v[194:197], v172 offset:51200
	ds_read_b128 v[198:201], v172 offset:52224
	ds_read_b128 v[202:205], v172 offset:53248
	ds_read_b128 v[206:209], v172 offset:54272
	ds_read_b128 v[212:215], v172 offset:55296
	ds_read_b128 v[216:219], v172 offset:56320
	global_load_lds_dwordx4 v[220:221], off
	s_add_i32 m0, s76, 0x2000
	s_add_u32 s74, s74, 0x40080
	v_lshl_add_u64 v[220:221], v[222:223], 0, s[12:13]
	s_addc_u32 s75, s75, 0
	s_add_i32 s76, s92, s35
	global_load_lds_dwordx4 v[220:221], off
	v_lshl_add_u64 v[220:221], s[74:75], 0, v[146:147]
	s_mov_b32 m0, s76
	s_nop 0
	global_load_lds_dwordx4 v[220:221], off
	v_lshl_add_u64 v[220:221], s[74:75], 0, v[150:151]
	s_add_i32 m0, s76, 0x2000
	s_nop 0
	global_load_lds_dwordx4 v[220:221], off
	v_lshl_add_u64 v[220:221], v[224:225], 0, s[12:13]
	s_mov_b32 m0, s80
	s_nop 0
	global_load_lds_dwordx4 v[220:221], off
	v_lshl_add_u64 v[220:221], v[226:227], 0, s[12:13]
	s_mov_b32 m0, s81
	s_nop 0
	global_load_lds_dwordx4 v[220:221], off
	s_waitcnt vmcnt(8)
	s_waitcnt lgkmcnt(0)
	s_barrier
	s_setprio 1
	s_waitcnt lgkmcnt(0)
	v_mfma_f32_16x16x32_f16 v[60:63], v[132:135], v[186:189], v[60:63]
	v_mfma_f32_16x16x32_f16 v[56:59], v[140:143], v[186:189], v[56:59]
	v_mfma_f32_16x16x32_f16 v[44:47], v[132:135], v[194:197], v[44:47]
	v_mfma_f32_16x16x32_f16 v[40:43], v[140:143], v[194:197], v[40:43]
	v_mfma_f32_16x16x32_f16 v[28:31], v[132:135], v[202:205], v[28:31]
	v_mfma_f32_16x16x32_f16 v[24:27], v[140:143], v[202:205], v[24:27]
	v_mfma_f32_16x16x32_f16 v[12:15], v[132:135], v[212:215], v[12:15]
	v_mfma_f32_16x16x32_f16 v[8:11], v[140:143], v[212:215], v[8:11]
	v_mfma_f32_16x16x32_f16 v[60:63], v[136:139], v[190:193], v[60:63]
	v_mfma_f32_16x16x32_f16 v[56:59], v[160:163], v[190:193], v[56:59]
	v_mfma_f32_16x16x32_f16 v[44:47], v[136:139], v[198:201], v[44:47]
	v_mfma_f32_16x16x32_f16 v[40:43], v[160:163], v[198:201], v[40:43]
	v_mfma_f32_16x16x32_f16 v[28:31], v[136:139], v[206:209], v[28:31]
	v_mfma_f32_16x16x32_f16 v[24:27], v[160:163], v[206:209], v[24:27]
	v_mfma_f32_16x16x32_f16 v[12:15], v[136:139], v[216:219], v[12:15]
	v_mfma_f32_16x16x32_f16 v[8:11], v[160:163], v[216:219], v[8:11]
	s_setprio 0
	s_setprio 1
	v_mfma_f32_16x16x32_f16 v[52:55], v[164:167], v[186:189], v[52:55]
	v_mfma_f32_16x16x32_f16 v[48:51], v[178:181], v[186:189], v[48:51]
	v_mfma_f32_16x16x32_f16 v[36:39], v[164:167], v[194:197], v[36:39]
	v_mfma_f32_16x16x32_f16 v[32:35], v[178:181], v[194:197], v[32:35]
	v_mfma_f32_16x16x32_f16 v[20:23], v[164:167], v[202:205], v[20:23]
	v_mfma_f32_16x16x32_f16 v[16:19], v[178:181], v[202:205], v[16:19]
	v_mfma_f32_16x16x32_f16 v[4:7], v[164:167], v[212:215], v[4:7]
	v_mfma_f32_16x16x32_f16 v[0:3], v[178:181], v[212:215], v[0:3]
	v_mfma_f32_16x16x32_f16 v[52:55], v[174:177], v[190:193], v[52:55]
	v_mfma_f32_16x16x32_f16 v[48:51], v[182:185], v[190:193], v[48:51]
	v_mfma_f32_16x16x32_f16 v[36:39], v[174:177], v[198:201], v[36:39]
	v_mfma_f32_16x16x32_f16 v[32:35], v[182:185], v[198:201], v[32:35]
	v_mfma_f32_16x16x32_f16 v[20:23], v[174:177], v[206:209], v[20:23]
	v_mfma_f32_16x16x32_f16 v[16:19], v[182:185], v[206:209], v[16:19]
	v_mfma_f32_16x16x32_f16 v[4:7], v[174:177], v[216:219], v[4:7]
	v_mfma_f32_16x16x32_f16 v[0:3], v[182:185], v[216:219], v[0:3]
	s_add_i32 s90, s90, 2
	s_add_u32 s46, s46, 0x100
	s_addc_u32 s47, s47, 0
	s_add_u32 s88, s88, 0x100
	s_addc_u32 s89, s89, 0
	s_cmp_gt_u32 s90, 13
	s_setprio 0
	s_barrier
	s_cbranch_scc1 .LBB0_209

.Lrlx5p0b_done:
	s_mov_b32 s99, 0
	s_waitcnt lgkmcnt(0)
	s_barrier
	s_setprio 1
	s_waitcnt lgkmcnt(0)
	v_mfma_f32_16x16x32_bf16 v[60:63], v[144:147], v[184:187], v[60:63]
	v_mfma_f32_16x16x32_bf16 v[56:59], v[160:163], v[184:187], v[56:59]
	v_mfma_f32_16x16x32_bf16 v[48:51], v[144:147], v[192:195], v[48:51]
	v_mfma_f32_16x16x32_bf16 v[40:43], v[160:163], v[192:195], v[40:43]
	v_mfma_f32_16x16x32_bf16 v[32:35], v[144:147], v[200:203], v[32:35]
	v_mfma_f32_16x16x32_bf16 v[24:27], v[160:163], v[200:203], v[24:27]
	v_mfma_f32_16x16x32_bf16 v[16:19], v[144:147], v[212:215], v[16:19]
	v_mfma_f32_16x16x32_bf16 v[8:11], v[160:163], v[212:215], v[8:11]
	v_mfma_f32_16x16x32_bf16 v[60:63], v[156:159], v[188:191], v[60:63]
	v_mfma_f32_16x16x32_bf16 v[56:59], v[164:167], v[188:191], v[56:59]
	v_mfma_f32_16x16x32_bf16 v[48:51], v[156:159], v[196:199], v[48:51]
	v_mfma_f32_16x16x32_bf16 v[40:43], v[164:167], v[196:199], v[40:43]
	v_mfma_f32_16x16x32_bf16 v[32:35], v[156:159], v[204:207], v[32:35]
	v_mfma_f32_16x16x32_bf16 v[24:27], v[164:167], v[204:207], v[24:27]
	v_mfma_f32_16x16x32_bf16 v[16:19], v[156:159], v[216:219], v[16:19]
	v_mfma_f32_16x16x32_bf16 v[8:11], v[164:167], v[216:219], v[8:11]
	s_setprio 0
	s_setprio 1
	v_mfma_f32_16x16x32_bf16 v[52:55], v[168:171], v[184:187], v[52:55]
	v_mfma_f32_16x16x32_bf16 v[44:47], v[176:179], v[184:187], v[44:47]
	v_mfma_f32_16x16x32_bf16 v[36:39], v[168:171], v[192:195], v[36:39]
	v_mfma_f32_16x16x32_bf16 v[28:31], v[176:179], v[192:195], v[28:31]
	v_mfma_f32_16x16x32_bf16 v[20:23], v[168:171], v[200:203], v[20:23]
	v_mfma_f32_16x16x32_bf16 v[12:15], v[176:179], v[200:203], v[12:15]
	v_mfma_f32_16x16x32_bf16 v[4:7], v[168:171], v[212:215], v[4:7]
	v_mfma_f32_16x16x32_bf16 v[0:3], v[176:179], v[212:215], v[0:3]
	v_mfma_f32_16x16x32_bf16 v[52:55], v[172:175], v[188:191], v[52:55]
	v_mfma_f32_16x16x32_bf16 v[44:47], v[180:183], v[188:191], v[44:47]
	v_mfma_f32_16x16x32_bf16 v[36:39], v[172:175], v[196:199], v[36:39]
	v_mfma_f32_16x16x32_bf16 v[28:31], v[180:183], v[196:199], v[28:31]
	v_mfma_f32_16x16x32_bf16 v[20:23], v[172:175], v[204:207], v[20:23]
	v_mfma_f32_16x16x32_bf16 v[12:15], v[180:183], v[204:207], v[12:15]
	v_mfma_f32_16x16x32_bf16 v[4:7], v[172:175], v[216:219], v[4:7]
	v_mfma_f32_16x16x32_bf16 v[0:3], v[180:183], v[216:219], v[0:3]
	s_setprio 0
	s_barrier
	s_add_i32 s83, 0, 0x18000
	s_add_i32 s84, 0, 0x1c000
	v_add_u32_e32 v164, s83, v152
	v_add_u32_e32 v180, s84, v152
	ds_read_b128 v[144:147], v164
	ds_read_b128 v[156:159], v164 offset:1024
	ds_read_b128 v[160:163], v164 offset:2048
	ds_read_b128 v[164:167], v164 offset:3072
	ds_read_b128 v[168:171], v180
	ds_read_b128 v[172:175], v180 offset:1024
	ds_read_b128 v[176:179], v180 offset:2048
	ds_read_b128 v[180:183], v180 offset:3072
	s_add_u32 s70, s70, 0x20000
	s_addc_u32 s71, s71, 0
	s_mov_b32 m0, s66
	v_lshl_add_u64 v[224:225], s[70:71], 0, v[128:129]
	ds_read_b128 v[184:187], v155 offset:32768
	ds_read_b128 v[188:191], v155 offset:33792
	ds_read_b128 v[192:195], v155 offset:34816
	ds_read_b128 v[196:199], v155 offset:35840
	ds_read_b128 v[200:203], v155 offset:36864
	ds_read_b128 v[204:207], v155 offset:37888
	ds_read_b128 v[212:215], v155 offset:38912
	ds_read_b128 v[216:219], v155 offset:39936
	global_load_lds_dwordx4 v[224:225], off
	v_lshl_add_u64 v[224:225], s[70:71], 0, v[132:133]
	s_mov_b32 m0, s67
	s_nop 0
	global_load_lds_dwordx4 v[224:225], off
	s_waitcnt vmcnt(8)
	s_waitcnt lgkmcnt(0)
	s_barrier
	s_setprio 1
	s_waitcnt lgkmcnt(0)
	v_mfma_f32_16x16x32_bf16 v[124:127], v[144:147], v[184:187], v[124:127]
	v_mfma_f32_16x16x32_bf16 v[120:123], v[160:163], v[184:187], v[120:123]
	v_mfma_f32_16x16x32_bf16 v[116:119], v[144:147], v[192:195], v[116:119]
	v_mfma_f32_16x16x32_bf16 v[108:111], v[160:163], v[192:195], v[108:111]
	v_mfma_f32_16x16x32_bf16 v[96:99], v[144:147], v[200:203], v[96:99]
	v_mfma_f32_16x16x32_bf16 v[88:91], v[160:163], v[200:203], v[88:91]
	v_mfma_f32_16x16x32_bf16 v[80:83], v[144:147], v[212:215], v[80:83]
	v_mfma_f32_16x16x32_bf16 v[72:75], v[160:163], v[212:215], v[72:75]
	v_mfma_f32_16x16x32_bf16 v[124:127], v[156:159], v[188:191], v[124:127]
	v_mfma_f32_16x16x32_bf16 v[120:123], v[164:167], v[188:191], v[120:123]
	v_mfma_f32_16x16x32_bf16 v[116:119], v[156:159], v[196:199], v[116:119]
	v_mfma_f32_16x16x32_bf16 v[108:111], v[164:167], v[196:199], v[108:111]
	v_mfma_f32_16x16x32_bf16 v[96:99], v[156:159], v[204:207], v[96:99]
	v_mfma_f32_16x16x32_bf16 v[88:91], v[164:167], v[204:207], v[88:91]
	v_mfma_f32_16x16x32_bf16 v[80:83], v[156:159], v[216:219], v[80:83]
	v_mfma_f32_16x16x32_bf16 v[72:75], v[164:167], v[216:219], v[72:75]
	s_setprio 0
	s_setprio 1
	v_mfma_f32_16x16x32_bf16 v[112:115], v[168:171], v[184:187], v[112:115]
	v_mfma_f32_16x16x32_bf16 v[104:107], v[176:179], v[184:187], v[104:107]
	v_mfma_f32_16x16x32_bf16 v[100:103], v[168:171], v[192:195], v[100:103]
	v_mfma_f32_16x16x32_bf16 v[92:95], v[176:179], v[192:195], v[92:95]
	v_mfma_f32_16x16x32_bf16 v[84:87], v[168:171], v[200:203], v[84:87]
	v_mfma_f32_16x16x32_bf16 v[76:79], v[176:179], v[200:203], v[76:79]
	v_mfma_f32_16x16x32_bf16 v[68:71], v[168:171], v[212:215], v[68:71]
	v_mfma_f32_16x16x32_bf16 v[64:67], v[176:179], v[212:215], v[64:67]
	v_mfma_f32_16x16x32_bf16 v[112:115], v[172:175], v[188:191], v[112:115]
	v_mfma_f32_16x16x32_bf16 v[104:107], v[180:183], v[188:191], v[104:107]
	v_mfma_f32_16x16x32_bf16 v[100:103], v[172:175], v[196:199], v[100:103]
	v_mfma_f32_16x16x32_bf16 v[92:95], v[180:183], v[196:199], v[92:95]
	v_mfma_f32_16x16x32_bf16 v[84:87], v[172:175], v[204:207], v[84:87]
	v_mfma_f32_16x16x32_bf16 v[76:79], v[180:183], v[204:207], v[76:79]
	v_mfma_f32_16x16x32_bf16 v[68:71], v[172:175], v[216:219], v[68:71]
	v_mfma_f32_16x16x32_bf16 v[64:67], v[180:183], v[216:219], v[64:67]
	s_setprio 0
	s_barrier
	s_add_i32 s70, s83, s64
	v_lshl_add_u64 v[148:149], v[148:149], 0, s[8:9]
	s_mov_b32 m0, s70
	ds_read_b128 v[184:187], v155 offset:49152
	ds_read_b128 v[188:191], v155 offset:50176
	ds_read_b128 v[192:195], v155 offset:51200
	ds_read_b128 v[196:199], v155 offset:52224
	ds_read_b128 v[200:203], v155 offset:53248
	ds_read_b128 v[204:207], v155 offset:54272
	ds_read_b128 v[212:215], v155 offset:55296
	ds_read_b128 v[216:219], v155 offset:56320
	global_load_lds_dwordx4 v[148:149], off
	s_add_i32 m0, s70, 0x2000
	s_add_u32 s62, s62, 0x20080
	v_lshl_add_u64 v[148:149], v[208:209], 0, s[8:9]
	s_addc_u32 s63, s63, 0
	s_add_i32 s70, s84, s64
	global_load_lds_dwordx4 v[148:149], off
	v_lshl_add_u64 v[148:149], s[62:63], 0, v[130:131]
	s_mov_b32 m0, s70
	s_nop 0
	global_load_lds_dwordx4 v[148:149], off
	v_lshl_add_u64 v[148:149], s[62:63], 0, v[134:135]
	s_add_i32 m0, s70, 0x2000
	s_nop 0
	global_load_lds_dwordx4 v[148:149], off
	v_lshl_add_u64 v[148:149], v[220:221], 0, s[8:9]
	s_mov_b32 m0, s73
	s_nop 0
	global_load_lds_dwordx4 v[148:149], off
	v_lshl_add_u64 v[148:149], v[222:223], 0, s[8:9]
	s_mov_b32 m0, s74
	s_nop 0
	global_load_lds_dwordx4 v[148:149], off
	s_waitcnt vmcnt(8)
	s_waitcnt lgkmcnt(0)
	s_barrier
	s_setprio 1
	s_waitcnt lgkmcnt(0)
	v_mfma_f32_16x16x32_bf16 v[60:63], v[144:147], v[184:187], v[60:63]
	v_mfma_f32_16x16x32_bf16 v[56:59], v[160:163], v[184:187], v[56:59]
	v_mfma_f32_16x16x32_bf16 v[48:51], v[144:147], v[192:195], v[48:51]
	v_mfma_f32_16x16x32_bf16 v[40:43], v[160:163], v[192:195], v[40:43]
	v_mfma_f32_16x16x32_bf16 v[32:35], v[144:147], v[200:203], v[32:35]
	v_mfma_f32_16x16x32_bf16 v[24:27], v[160:163], v[200:203], v[24:27]
	v_mfma_f32_16x16x32_bf16 v[16:19], v[144:147], v[212:215], v[16:19]
	v_mfma_f32_16x16x32_bf16 v[8:11], v[160:163], v[212:215], v[8:11]
	v_mfma_f32_16x16x32_bf16 v[60:63], v[156:159], v[188:191], v[60:63]
	v_mfma_f32_16x16x32_bf16 v[56:59], v[164:167], v[188:191], v[56:59]
	v_mfma_f32_16x16x32_bf16 v[48:51], v[156:159], v[196:199], v[48:51]
	v_mfma_f32_16x16x32_bf16 v[40:43], v[164:167], v[196:199], v[40:43]
	v_mfma_f32_16x16x32_bf16 v[32:35], v[156:159], v[204:207], v[32:35]
	v_mfma_f32_16x16x32_bf16 v[24:27], v[164:167], v[204:207], v[24:27]
	v_mfma_f32_16x16x32_bf16 v[16:19], v[156:159], v[216:219], v[16:19]
	v_mfma_f32_16x16x32_bf16 v[8:11], v[164:167], v[216:219], v[8:11]
	s_setprio 0
	s_setprio 1
	v_mfma_f32_16x16x32_bf16 v[52:55], v[168:171], v[184:187], v[52:55]
	v_mfma_f32_16x16x32_bf16 v[44:47], v[176:179], v[184:187], v[44:47]
	v_mfma_f32_16x16x32_bf16 v[36:39], v[168:171], v[192:195], v[36:39]
	v_mfma_f32_16x16x32_bf16 v[28:31], v[176:179], v[192:195], v[28:31]
	v_mfma_f32_16x16x32_bf16 v[20:23], v[168:171], v[200:203], v[20:23]
	v_mfma_f32_16x16x32_bf16 v[12:15], v[176:179], v[200:203], v[12:15]
	v_mfma_f32_16x16x32_bf16 v[4:7], v[168:171], v[212:215], v[4:7]
	v_mfma_f32_16x16x32_bf16 v[0:3], v[176:179], v[212:215], v[0:3]
	v_mfma_f32_16x16x32_bf16 v[52:55], v[172:175], v[188:191], v[52:55]
	v_mfma_f32_16x16x32_bf16 v[44:47], v[180:183], v[188:191], v[44:47]
	v_mfma_f32_16x16x32_bf16 v[36:39], v[172:175], v[196:199], v[36:39]
	v_mfma_f32_16x16x32_bf16 v[28:31], v[180:183], v[196:199], v[28:31]
	v_mfma_f32_16x16x32_bf16 v[20:23], v[172:175], v[204:207], v[20:23]
	v_mfma_f32_16x16x32_bf16 v[12:15], v[180:183], v[204:207], v[12:15]
	v_mfma_f32_16x16x32_bf16 v[4:7], v[172:175], v[216:219], v[4:7]
	v_mfma_f32_16x16x32_bf16 v[0:3], v[180:183], v[216:219], v[0:3]
	s_add_i32 s82, s82, 2
	s_add_u32 s46, s46, 0x100
	s_addc_u32 s47, s47, 0
	s_add_u32 s80, s80, 0x100
	s_addc_u32 s81, s81, 0
	s_cmp_gt_u32 s82, 5
	s_setprio 0
	s_barrier
	s_cbranch_scc0 .LBB0_553
	s_and_b64 vcc, exec, s[10:11]
	s_cbranch_vccz .LBB0_556
	s_barrier

.LBB0_653:
	v_add_u32_e32 v149, s69, v160
	ds_read_b128 v[108:111], v149
	ds_read_b128 v[120:123], v149 offset:1024
	ds_read_b128 v[124:127], v149 offset:2048
	ds_read_b128 v[164:167], v149 offset:3072
	v_add_u32_e32 v149, s6, v160
	ds_read_b128 v[168:171], v149
	ds_read_b128 v[172:175], v149 offset:1024
	ds_read_b128 v[176:179], v149 offset:2048
	ds_read_b128 v[180:183], v149 offset:3072
	s_add_u32 s11, s96, 0xfffc0080
	s_addc_u32 s12, s97, -1
	s_cmp_eq_u32 s10, 12
	s_cselect_b32 vcc_hi, s66, s12
	s_cselect_b32 vcc_lo, s67, s11
	s_cselect_b32 s47, s81, s70
	s_cselect_b32 s46, s83, s93
	v_lshl_add_u64 v[208:209], s[96:97], 0, v[150:151]
	s_add_i32 m0, s85, 0xc000
	ds_read_b128 v[184:187], v161
	ds_read_b128 v[188:191], v161 offset:1024
	ds_read_b128 v[192:195], v161 offset:2048
	ds_read_b128 v[196:199], v161 offset:3072
	ds_read_b128 v[200:203], v161 offset:4096
	ds_read_b128 v[204:207], v161 offset:5120
	ds_read_b128 v[212:215], v161 offset:6144
	ds_read_b128 v[216:219], v161 offset:7168
	global_load_lds_dwordx4 v[208:209], off
	v_lshl_add_u64 v[208:209], s[96:97], 0, v[152:153]
	s_add_i32 m0, s85, 0xe000
	s_nop 0
	global_load_lds_dwordx4 v[208:209], off
	s_waitcnt vmcnt(8)
	s_waitcnt lgkmcnt(0)
	s_barrier
	s_setprio 1
	s_waitcnt lgkmcnt(0)
	v_mfma_f32_16x16x32_bf16 v[56:59], v[108:111], v[184:187], v[56:59]
	v_mfma_f32_16x16x32_bf16 v[60:63], v[124:127], v[184:187], v[60:63]
	v_mfma_f32_16x16x32_bf16 v[76:79], v[108:111], v[192:195], v[76:79]
	v_mfma_f32_16x16x32_bf16 v[84:87], v[124:127], v[192:195], v[84:87]
	v_mfma_f32_16x16x32_bf16 v[88:91], v[108:111], v[200:203], v[88:91]
	v_mfma_f32_16x16x32_bf16 v[92:95], v[124:127], v[200:203], v[92:95]
	v_mfma_f32_16x16x32_bf16 v[96:99], v[108:111], v[212:215], v[96:99]
	v_mfma_f32_16x16x32_bf16 v[100:103], v[124:127], v[212:215], v[100:103]
	v_mfma_f32_16x16x32_bf16 v[56:59], v[120:123], v[188:191], v[56:59]
	v_mfma_f32_16x16x32_bf16 v[60:63], v[164:167], v[188:191], v[60:63]
	v_mfma_f32_16x16x32_bf16 v[76:79], v[120:123], v[196:199], v[76:79]
	v_mfma_f32_16x16x32_bf16 v[84:87], v[164:167], v[196:199], v[84:87]
	v_mfma_f32_16x16x32_bf16 v[88:91], v[120:123], v[204:207], v[88:91]
	v_mfma_f32_16x16x32_bf16 v[92:95], v[164:167], v[204:207], v[92:95]
	v_mfma_f32_16x16x32_bf16 v[96:99], v[120:123], v[216:219], v[96:99]
	v_mfma_f32_16x16x32_bf16 v[100:103], v[164:167], v[216:219], v[100:103]
	s_setprio 0
	s_setprio 1
	v_mfma_f32_16x16x32_bf16 v[136:139], v[168:171], v[184:187], v[136:139]
	v_mfma_f32_16x16x32_bf16 v[132:135], v[176:179], v[184:187], v[132:135]
	v_mfma_f32_16x16x32_bf16 v[128:131], v[168:171], v[192:195], v[128:131]
	v_mfma_f32_16x16x32_bf16 v[112:115], v[176:179], v[192:195], v[112:115]
	v_mfma_f32_16x16x32_bf16 v[116:119], v[168:171], v[200:203], v[116:119]
	v_mfma_f32_16x16x32_bf16 v[104:107], v[176:179], v[200:203], v[104:107]
	v_mfma_f32_16x16x32_bf16 v[68:71], v[168:171], v[212:215], v[68:71]
	v_mfma_f32_16x16x32_bf16 v[64:67], v[176:179], v[212:215], v[64:67]
	v_mfma_f32_16x16x32_bf16 v[136:139], v[172:175], v[188:191], v[136:139]
	v_mfma_f32_16x16x32_bf16 v[132:135], v[180:183], v[188:191], v[132:135]
	v_mfma_f32_16x16x32_bf16 v[128:131], v[172:175], v[196:199], v[128:131]
	v_mfma_f32_16x16x32_bf16 v[112:115], v[180:183], v[196:199], v[112:115]
	v_mfma_f32_16x16x32_bf16 v[116:119], v[172:175], v[204:207], v[116:119]
	v_mfma_f32_16x16x32_bf16 v[104:107], v[180:183], v[204:207], v[104:107]
	v_mfma_f32_16x16x32_bf16 v[68:71], v[172:175], v[216:219], v[68:71]
	v_mfma_f32_16x16x32_bf16 v[64:67], v[180:183], v[216:219], v[64:67]
	s_setprio 0
	s_barrier
	s_add_i32 s11, s69, s64
	v_lshl_add_u64 v[208:209], s[46:47], 0, v[142:143]
	s_mov_b32 m0, s11
	ds_read_b128 v[184:187], v161 offset:16384
	ds_read_b128 v[188:191], v161 offset:17408
	ds_read_b128 v[192:195], v161 offset:18432
	ds_read_b128 v[196:199], v161 offset:19456
	ds_read_b128 v[200:203], v161 offset:20480
	ds_read_b128 v[204:207], v161 offset:21504
	ds_read_b128 v[212:215], v161 offset:22528
	ds_read_b128 v[216:219], v161 offset:23552
	global_load_lds_dwordx4 v[208:209], off
	s_add_i32 m0, s11, 0x2000
	s_add_u32 s12, s46, 0x40000
	v_lshl_add_u64 v[210:211], s[46:47], 0, v[146:147]
	s_addc_u32 s13, s47, 0
	s_add_i32 s11, s6, s64
	global_load_lds_dwordx4 v[210:211], off
	v_lshl_add_u64 v[220:221], s[12:13], 0, v[142:143]
	s_mov_b32 m0, s11
	v_lshl_add_u64 v[222:223], vcc, 0, v[144:145]
	global_load_lds_dwordx4 v[220:221], off
	v_lshl_add_u64 v[220:221], s[12:13], 0, v[146:147]
	s_add_i32 m0, s11, 0x2000
	s_nop 0
	global_load_lds_dwordx4 v[220:221], off
	v_lshl_add_u64 v[220:221], vcc, 0, v[140:141]
	s_mov_b32 m0, s85
	s_nop 0
	global_load_lds_dwordx4 v[220:221], off
	s_mov_b32 m0, s95
	s_nop 0
	global_load_lds_dwordx4 v[222:223], off
	s_waitcnt vmcnt(8)
	s_waitcnt lgkmcnt(0)
	s_barrier
	s_setprio 1
	s_waitcnt lgkmcnt(0)
	v_mfma_f32_16x16x32_bf16 v[80:83], v[108:111], v[184:187], v[80:83]
	v_mfma_f32_16x16x32_bf16 v[72:75], v[124:127], v[184:187], v[72:75]
	v_mfma_f32_16x16x32_bf16 v[52:55], v[108:111], v[192:195], v[52:55]
	v_mfma_f32_16x16x32_bf16 v[48:51], v[124:127], v[192:195], v[48:51]
	v_mfma_f32_16x16x32_bf16 v[36:39], v[108:111], v[200:203], v[36:39]
	v_mfma_f32_16x16x32_bf16 v[32:35], v[124:127], v[200:203], v[32:35]
	v_mfma_f32_16x16x32_bf16 v[20:23], v[108:111], v[212:215], v[20:23]
	v_mfma_f32_16x16x32_bf16 v[16:19], v[124:127], v[212:215], v[16:19]
	v_mfma_f32_16x16x32_bf16 v[80:83], v[120:123], v[188:191], v[80:83]
	v_mfma_f32_16x16x32_bf16 v[72:75], v[164:167], v[188:191], v[72:75]
	v_mfma_f32_16x16x32_bf16 v[52:55], v[120:123], v[196:199], v[52:55]
	v_mfma_f32_16x16x32_bf16 v[48:51], v[164:167], v[196:199], v[48:51]
	v_mfma_f32_16x16x32_bf16 v[36:39], v[120:123], v[204:207], v[36:39]
	v_mfma_f32_16x16x32_bf16 v[32:35], v[164:167], v[204:207], v[32:35]
	v_mfma_f32_16x16x32_bf16 v[20:23], v[120:123], v[216:219], v[20:23]
	v_mfma_f32_16x16x32_bf16 v[16:19], v[164:167], v[216:219], v[16:19]
	s_setprio 0
	s_setprio 1
	v_mfma_f32_16x16x32_bf16 v[44:47], v[168:171], v[184:187], v[44:47]
	v_mfma_f32_16x16x32_bf16 v[40:43], v[176:179], v[184:187], v[40:43]
	v_mfma_f32_16x16x32_bf16 v[28:31], v[168:171], v[192:195], v[28:31]
	v_mfma_f32_16x16x32_bf16 v[24:27], v[176:179], v[192:195], v[24:27]
	v_mfma_f32_16x16x32_bf16 v[12:15], v[168:171], v[200:203], v[12:15]
	v_mfma_f32_16x16x32_bf16 v[8:11], v[176:179], v[200:203], v[8:11]
	v_mfma_f32_16x16x32_bf16 v[4:7], v[168:171], v[212:215], v[4:7]
	v_mfma_f32_16x16x32_bf16 v[0:3], v[176:179], v[212:215], v[0:3]
	v_mfma_f32_16x16x32_bf16 v[44:47], v[172:175], v[188:191], v[44:47]
	v_mfma_f32_16x16x32_bf16 v[40:43], v[180:183], v[188:191], v[40:43]
	v_mfma_f32_16x16x32_bf16 v[28:31], v[172:175], v[196:199], v[28:31]
	v_mfma_f32_16x16x32_bf16 v[24:27], v[180:183], v[196:199], v[24:27]
	v_mfma_f32_16x16x32_bf16 v[12:15], v[172:175], v[204:207], v[12:15]
	v_mfma_f32_16x16x32_bf16 v[8:11], v[180:183], v[204:207], v[8:11]
	v_mfma_f32_16x16x32_bf16 v[4:7], v[172:175], v[216:219], v[4:7]
	v_mfma_f32_16x16x32_bf16 v[0:3], v[180:183], v[216:219], v[0:3]
	s_setprio 0
	s_barrier
	s_add_i32 s11, 0, 0x18000
	v_add_u32_e32 v149, s11, v160
	s_add_i32 s71, 0, 0x1c000
	ds_read_b128 v[108:111], v149
	ds_read_b128 v[120:123], v149 offset:1024
	ds_read_b128 v[124:127], v149 offset:2048
	ds_read_b128 v[164:167], v149 offset:3072
	v_add_u32_e32 v149, s71, v160
	ds_read_b128 v[168:171], v149
	ds_read_b128 v[172:175], v149 offset:1024
	ds_read_b128 v[176:179], v149 offset:2048
	ds_read_b128 v[180:183], v149 offset:3072
	s_add_u32 s12, vcc_lo, 0x40000
	s_addc_u32 s13, vcc_hi, 0
	s_mov_b32 m0, s86
	v_lshl_add_u64 v[224:225], s[12:13], 0, v[140:141]
	ds_read_b128 v[184:187], v161 offset:32768
	ds_read_b128 v[188:191], v161 offset:33792
	ds_read_b128 v[192:195], v161 offset:34816
	ds_read_b128 v[196:199], v161 offset:35840
	ds_read_b128 v[200:203], v161 offset:36864
	ds_read_b128 v[204:207], v161 offset:37888
	ds_read_b128 v[212:215], v161 offset:38912
	ds_read_b128 v[216:219], v161 offset:39936
	global_load_lds_dwordx4 v[224:225], off
	v_lshl_add_u64 v[224:225], s[12:13], 0, v[144:145]
	s_mov_b32 m0, s87
	s_nop 0
	global_load_lds_dwordx4 v[224:225], off
	s_waitcnt vmcnt(8)
	s_waitcnt lgkmcnt(0)
	s_barrier
	s_setprio 1
	s_waitcnt lgkmcnt(0)
	v_mfma_f32_16x16x32_bf16 v[56:59], v[108:111], v[184:187], v[56:59]
	v_mfma_f32_16x16x32_bf16 v[60:63], v[124:127], v[184:187], v[60:63]
	v_mfma_f32_16x16x32_bf16 v[76:79], v[108:111], v[192:195], v[76:79]
	v_mfma_f32_16x16x32_bf16 v[84:87], v[124:127], v[192:195], v[84:87]
	v_mfma_f32_16x16x32_bf16 v[88:91], v[108:111], v[200:203], v[88:91]
	v_mfma_f32_16x16x32_bf16 v[92:95], v[124:127], v[200:203], v[92:95]
	v_mfma_f32_16x16x32_bf16 v[96:99], v[108:111], v[212:215], v[96:99]
	v_mfma_f32_16x16x32_bf16 v[100:103], v[124:127], v[212:215], v[100:103]
	v_mfma_f32_16x16x32_bf16 v[56:59], v[120:123], v[188:191], v[56:59]
	v_mfma_f32_16x16x32_bf16 v[60:63], v[164:167], v[188:191], v[60:63]
	v_mfma_f32_16x16x32_bf16 v[76:79], v[120:123], v[196:199], v[76:79]
	v_mfma_f32_16x16x32_bf16 v[84:87], v[164:167], v[196:199], v[84:87]
	v_mfma_f32_16x16x32_bf16 v[88:91], v[120:123], v[204:207], v[88:91]
	v_mfma_f32_16x16x32_bf16 v[92:95], v[164:167], v[204:207], v[92:95]
	v_mfma_f32_16x16x32_bf16 v[96:99], v[120:123], v[216:219], v[96:99]
	v_mfma_f32_16x16x32_bf16 v[100:103], v[164:167], v[216:219], v[100:103]
	s_setprio 0
	s_setprio 1
	v_mfma_f32_16x16x32_bf16 v[136:139], v[168:171], v[184:187], v[136:139]
	v_mfma_f32_16x16x32_bf16 v[132:135], v[176:179], v[184:187], v[132:135]
	v_mfma_f32_16x16x32_bf16 v[128:131], v[168:171], v[192:195], v[128:131]
	v_mfma_f32_16x16x32_bf16 v[112:115], v[176:179], v[192:195], v[112:115]
	v_mfma_f32_16x16x32_bf16 v[116:119], v[168:171], v[200:203], v[116:119]
	v_mfma_f32_16x16x32_bf16 v[104:107], v[176:179], v[200:203], v[104:107]
	v_mfma_f32_16x16x32_bf16 v[68:71], v[168:171], v[212:215], v[68:71]
	v_mfma_f32_16x16x32_bf16 v[64:67], v[176:179], v[212:215], v[64:67]
	v_mfma_f32_16x16x32_bf16 v[136:139], v[172:175], v[188:191], v[136:139]
	v_mfma_f32_16x16x32_bf16 v[132:135], v[180:183], v[188:191], v[132:135]
	v_mfma_f32_16x16x32_bf16 v[128:131], v[172:175], v[196:199], v[128:131]
	v_mfma_f32_16x16x32_bf16 v[112:115], v[180:183], v[196:199], v[112:115]
	v_mfma_f32_16x16x32_bf16 v[116:119], v[172:175], v[204:207], v[116:119]
	v_mfma_f32_16x16x32_bf16 v[104:107], v[180:183], v[204:207], v[104:107]
	v_mfma_f32_16x16x32_bf16 v[68:71], v[172:175], v[216:219], v[68:71]
	v_mfma_f32_16x16x32_bf16 v[64:67], v[180:183], v[216:219], v[64:67]
	s_setprio 0
	s_barrier
	s_add_i32 s11, s11, s64
	v_lshl_add_u64 v[208:209], v[208:209], 0, s[74:75]
	s_mov_b32 m0, s11
	ds_read_b128 v[184:187], v161 offset:49152
	ds_read_b128 v[188:191], v161 offset:50176
	ds_read_b128 v[192:195], v161 offset:51200
	ds_read_b128 v[196:199], v161 offset:52224
	ds_read_b128 v[200:203], v161 offset:53248
	ds_read_b128 v[204:207], v161 offset:54272
	ds_read_b128 v[212:215], v161 offset:55296
	ds_read_b128 v[216:219], v161 offset:56320
	global_load_lds_dwordx4 v[208:209], off
	s_add_i32 m0, s11, 0x2000
	s_add_u32 s12, s46, 0x40080
	v_lshl_add_u64 v[208:209], v[210:211], 0, s[74:75]
	s_addc_u32 s13, s47, 0
	s_add_i32 s11, s71, s64
	global_load_lds_dwordx4 v[208:209], off
	v_lshl_add_u64 v[208:209], s[12:13], 0, v[142:143]
	s_mov_b32 m0, s11
	s_nop 0
	global_load_lds_dwordx4 v[208:209], off
	v_lshl_add_u64 v[208:209], s[12:13], 0, v[146:147]
	s_add_i32 m0, s11, 0x2000
	s_nop 0
	global_load_lds_dwordx4 v[208:209], off
	v_lshl_add_u64 v[208:209], v[220:221], 0, s[74:75]
	s_mov_b32 m0, s4
	s_nop 0
	global_load_lds_dwordx4 v[208:209], off
	v_lshl_add_u64 v[208:209], v[222:223], 0, s[74:75]
	s_mov_b32 m0, s5
	s_nop 0
	global_load_lds_dwordx4 v[208:209], off
	s_waitcnt vmcnt(8)
	s_waitcnt lgkmcnt(0)
	s_barrier
	s_setprio 1
	s_waitcnt lgkmcnt(0)
	v_mfma_f32_16x16x32_bf16 v[80:83], v[108:111], v[184:187], v[80:83]
	v_mfma_f32_16x16x32_bf16 v[72:75], v[124:127], v[184:187], v[72:75]
	v_mfma_f32_16x16x32_bf16 v[52:55], v[108:111], v[192:195], v[52:55]
	v_mfma_f32_16x16x32_bf16 v[48:51], v[124:127], v[192:195], v[48:51]
	v_mfma_f32_16x16x32_bf16 v[36:39], v[108:111], v[200:203], v[36:39]
	v_mfma_f32_16x16x32_bf16 v[32:35], v[124:127], v[200:203], v[32:35]
	v_mfma_f32_16x16x32_bf16 v[20:23], v[108:111], v[212:215], v[20:23]
	v_mfma_f32_16x16x32_bf16 v[16:19], v[124:127], v[212:215], v[16:19]
	v_mfma_f32_16x16x32_bf16 v[80:83], v[120:123], v[188:191], v[80:83]
	v_mfma_f32_16x16x32_bf16 v[72:75], v[164:167], v[188:191], v[72:75]
	v_mfma_f32_16x16x32_bf16 v[52:55], v[120:123], v[196:199], v[52:55]
	v_mfma_f32_16x16x32_bf16 v[48:51], v[164:167], v[196:199], v[48:51]
	v_mfma_f32_16x16x32_bf16 v[36:39], v[120:123], v[204:207], v[36:39]
	v_mfma_f32_16x16x32_bf16 v[32:35], v[164:167], v[204:207], v[32:35]
	v_mfma_f32_16x16x32_bf16 v[20:23], v[120:123], v[216:219], v[20:23]
	v_mfma_f32_16x16x32_bf16 v[16:19], v[164:167], v[216:219], v[16:19]
	s_setprio 0
	s_setprio 1
	v_mfma_f32_16x16x32_bf16 v[44:47], v[168:171], v[184:187], v[44:47]
	v_mfma_f32_16x16x32_bf16 v[40:43], v[176:179], v[184:187], v[40:43]
	v_mfma_f32_16x16x32_bf16 v[28:31], v[168:171], v[192:195], v[28:31]
	v_mfma_f32_16x16x32_bf16 v[24:27], v[176:179], v[192:195], v[24:27]
	v_mfma_f32_16x16x32_bf16 v[12:15], v[168:171], v[200:203], v[12:15]
	v_mfma_f32_16x16x32_bf16 v[8:11], v[176:179], v[200:203], v[8:11]
	v_mfma_f32_16x16x32_bf16 v[4:7], v[168:171], v[212:215], v[4:7]
	v_mfma_f32_16x16x32_bf16 v[0:3], v[176:179], v[212:215], v[0:3]
	v_mfma_f32_16x16x32_bf16 v[44:47], v[172:175], v[188:191], v[44:47]
	v_mfma_f32_16x16x32_bf16 v[40:43], v[180:183], v[188:191], v[40:43]
	v_mfma_f32_16x16x32_bf16 v[28:31], v[172:175], v[196:199], v[28:31]
	v_mfma_f32_16x16x32_bf16 v[24:27], v[180:183], v[196:199], v[24:27]
	v_mfma_f32_16x16x32_bf16 v[12:15], v[172:175], v[204:207], v[12:15]
	v_mfma_f32_16x16x32_bf16 v[8:11], v[180:183], v[204:207], v[8:11]
	v_mfma_f32_16x16x32_bf16 v[4:7], v[172:175], v[216:219], v[4:7]
	v_mfma_f32_16x16x32_bf16 v[0:3], v[180:183], v[216:219], v[0:3]
	s_add_i32 s10, s10, 2
	s_add_u32 s96, s96, 0x100
	s_addc_u32 s97, s97, 0
	s_add_u32 s93, s93, 0x100
	s_addc_u32 s70, s70, 0
	s_cmp_gt_u32 s10, 13
	s_setprio 0
	s_barrier
	s_cbranch_scc0 .LBB0_653
	s_and_b64 vcc, exec, s[76:77]
	s_cbranch_vccz .LBB0_656
	s_barrier

.Lrlx7b_done:
	s_mov_b32 s99, 0
	s_waitcnt lgkmcnt(0)
	s_barrier
	s_setprio 1
	s_waitcnt lgkmcnt(0)
	v_mfma_f32_16x16x32_f16 v[80:83], v[56:59], v[164:167], v[80:83]
	v_mfma_f32_16x16x32_f16 v[60:63], v[72:75], v[164:167], v[60:63]
	v_mfma_f32_16x16x32_f16 v[44:47], v[56:59], v[188:191], v[44:47]
	v_mfma_f32_16x16x32_f16 v[36:39], v[72:75], v[188:191], v[36:39]
	v_mfma_f32_16x16x32_f16 v[28:31], v[56:59], v[204:207], v[28:31]
	v_mfma_f32_16x16x32_f16 v[20:23], v[72:75], v[204:207], v[20:23]
	v_mfma_f32_16x16x32_f16 v[12:15], v[56:59], v[216:219], v[12:15]
	v_mfma_f32_16x16x32_f16 v[4:7], v[72:75], v[216:219], v[4:7]
	v_mfma_f32_16x16x32_f16 v[80:83], v[64:67], v[184:187], v[80:83]
	v_mfma_f32_16x16x32_f16 v[60:63], v[76:79], v[184:187], v[60:63]
	v_mfma_f32_16x16x32_f16 v[44:47], v[64:67], v[200:203], v[44:47]
	v_mfma_f32_16x16x32_f16 v[36:39], v[76:79], v[200:203], v[36:39]
	v_mfma_f32_16x16x32_f16 v[28:31], v[64:67], v[212:215], v[28:31]
	v_mfma_f32_16x16x32_f16 v[20:23], v[76:79], v[212:215], v[20:23]
	v_mfma_f32_16x16x32_f16 v[12:15], v[64:67], v[220:223], v[12:15]
	v_mfma_f32_16x16x32_f16 v[4:7], v[76:79], v[220:223], v[4:7]
	s_setprio 0
	s_setprio 1
	v_mfma_f32_16x16x32_f16 v[48:51], v[156:159], v[164:167], v[48:51]
	v_mfma_f32_16x16x32_f16 v[40:43], v[100:103], v[188:191], v[40:43]
	v_mfma_f32_16x16x32_f16 v[32:35], v[156:159], v[188:191], v[32:35]
	v_mfma_f32_16x16x32_f16 v[24:27], v[100:103], v[204:207], v[24:27]
	v_mfma_f32_16x16x32_f16 v[16:19], v[156:159], v[204:207], v[16:19]
	v_mfma_f32_16x16x32_f16 v[8:11], v[100:103], v[216:219], v[8:11]
	v_mfma_f32_16x16x32_f16 v[0:3], v[156:159], v[216:219], v[0:3]
	v_mfma_f32_16x16x32_f16 v[56:59], v[100:103], v[164:167], v[68:71]
	v_mfma_f32_16x16x32_f16 v[48:51], v[160:163], v[184:187], v[48:51]
	v_mfma_f32_16x16x32_f16 v[40:43], v[136:139], v[200:203], v[40:43]
	v_mfma_f32_16x16x32_f16 v[32:35], v[160:163], v[200:203], v[32:35]
	v_mfma_f32_16x16x32_f16 v[24:27], v[136:139], v[212:215], v[24:27]
	v_mfma_f32_16x16x32_f16 v[16:19], v[160:163], v[212:215], v[16:19]
	v_mfma_f32_16x16x32_f16 v[8:11], v[136:139], v[220:223], v[8:11]
	v_mfma_f32_16x16x32_f16 v[0:3], v[160:163], v[220:223], v[0:3]
	v_mfma_f32_16x16x32_f16 v[56:59], v[136:139], v[184:187], v[56:59]
	s_setprio 0
	s_barrier
	s_add_i32 s93, 0, 0x18000
	s_add_i32 s94, 0, 0x1c000
	v_add_u32_e32 v76, s93, v196
	v_add_u32_e32 v160, s94, v196
	ds_read_b128 v[64:67], v76
	ds_read_b128 v[68:71], v76 offset:1024
	ds_read_b128 v[72:75], v76 offset:2048
	ds_read_b128 v[76:79], v76 offset:3072
	ds_read_b128 v[100:103], v160
	ds_read_b128 v[136:139], v160 offset:1024
	ds_read_b128 v[156:159], v160 offset:2048
	ds_read_b128 v[160:163], v160 offset:3072
	s_add_u32 s76, s76, 0x40000
	s_addc_u32 s77, s77, 0
	s_mov_b32 m0, s70
	v_lshl_add_u64 v[226:227], s[76:77], 0, v[174:175]
	ds_read_b128 v[164:167], v198 offset:32768
	ds_read_b128 v[184:187], v198 offset:33792
	ds_read_b128 v[188:191], v198 offset:34816
	ds_read_b128 v[200:203], v198 offset:35840
	ds_read_b128 v[204:207], v198 offset:36864
	ds_read_b128 v[212:215], v198 offset:37888
	ds_read_b128 v[216:219], v198 offset:38912
	ds_read_b128 v[220:223], v198 offset:39936
	global_load_lds_dwordx4 v[226:227], off
	v_lshl_add_u64 v[226:227], s[76:77], 0, v[170:171]
	s_mov_b32 m0, s71
	s_nop 0
	global_load_lds_dwordx4 v[226:227], off
	s_waitcnt vmcnt(8)
	s_waitcnt lgkmcnt(0)
	s_barrier
	s_setprio 1
	s_waitcnt lgkmcnt(0)
	v_mfma_f32_16x16x32_f16 v[152:155], v[64:67], v[164:167], v[152:155]
	v_mfma_f32_16x16x32_f16 v[144:147], v[72:75], v[164:167], v[144:147]
	v_mfma_f32_16x16x32_f16 v[132:135], v[64:67], v[188:191], v[132:135]
	v_mfma_f32_16x16x32_f16 v[124:127], v[72:75], v[188:191], v[124:127]
	v_mfma_f32_16x16x32_f16 v[116:119], v[64:67], v[204:207], v[116:119]
	v_mfma_f32_16x16x32_f16 v[108:111], v[72:75], v[204:207], v[108:111]
	v_mfma_f32_16x16x32_f16 v[96:99], v[64:67], v[216:219], v[96:99]
	v_mfma_f32_16x16x32_f16 v[88:91], v[72:75], v[216:219], v[88:91]
	v_mfma_f32_16x16x32_f16 v[152:155], v[68:71], v[184:187], v[152:155]
	v_mfma_f32_16x16x32_f16 v[144:147], v[76:79], v[184:187], v[144:147]
	v_mfma_f32_16x16x32_f16 v[132:135], v[68:71], v[200:203], v[132:135]
	v_mfma_f32_16x16x32_f16 v[124:127], v[76:79], v[200:203], v[124:127]
	v_mfma_f32_16x16x32_f16 v[116:119], v[68:71], v[212:215], v[116:119]
	v_mfma_f32_16x16x32_f16 v[108:111], v[76:79], v[212:215], v[108:111]
	v_mfma_f32_16x16x32_f16 v[96:99], v[68:71], v[220:223], v[96:99]
	v_mfma_f32_16x16x32_f16 v[88:91], v[76:79], v[220:223], v[88:91]
	s_setprio 0
	s_setprio 1
	v_mfma_f32_16x16x32_f16 v[148:151], v[100:103], v[164:167], v[148:151]
	v_mfma_f32_16x16x32_f16 v[140:143], v[156:159], v[164:167], v[140:143]
	v_mfma_f32_16x16x32_f16 v[128:131], v[100:103], v[188:191], v[128:131]
	v_mfma_f32_16x16x32_f16 v[120:123], v[156:159], v[188:191], v[120:123]
	v_mfma_f32_16x16x32_f16 v[112:115], v[100:103], v[204:207], v[112:115]
	v_mfma_f32_16x16x32_f16 v[104:107], v[156:159], v[204:207], v[104:107]
	v_mfma_f32_16x16x32_f16 v[92:95], v[100:103], v[216:219], v[92:95]
	v_mfma_f32_16x16x32_f16 v[84:87], v[156:159], v[216:219], v[84:87]
	v_mfma_f32_16x16x32_f16 v[148:151], v[136:139], v[184:187], v[148:151]
	v_mfma_f32_16x16x32_f16 v[140:143], v[160:163], v[184:187], v[140:143]
	v_mfma_f32_16x16x32_f16 v[128:131], v[136:139], v[200:203], v[128:131]
	v_mfma_f32_16x16x32_f16 v[120:123], v[160:163], v[200:203], v[120:123]
	v_mfma_f32_16x16x32_f16 v[112:115], v[136:139], v[212:215], v[112:115]
	v_mfma_f32_16x16x32_f16 v[104:107], v[160:163], v[212:215], v[104:107]
	v_mfma_f32_16x16x32_f16 v[92:95], v[136:139], v[220:223], v[92:95]
	v_mfma_f32_16x16x32_f16 v[84:87], v[160:163], v[220:223], v[84:87]
	s_setprio 0
	s_barrier
	s_add_i32 s76, s93, s67
	v_lshl_add_u64 v[192:193], v[192:193], 0, s[10:11]
	s_mov_b32 m0, s76
	ds_read_b128 v[164:167], v198 offset:49152
	ds_read_b128 v[184:187], v198 offset:50176
	ds_read_b128 v[188:191], v198 offset:51200
	ds_read_b128 v[200:203], v198 offset:52224
	ds_read_b128 v[204:207], v198 offset:53248
	ds_read_b128 v[212:215], v198 offset:54272
	ds_read_b128 v[216:219], v198 offset:55296
	ds_read_b128 v[220:223], v198 offset:56320
	global_load_lds_dwordx4 v[192:193], off
	s_add_i32 m0, s76, 0x2000
	s_add_u32 s74, s74, 0x40080
	v_lshl_add_u64 v[192:193], v[208:209], 0, s[10:11]
	s_addc_u32 s75, s75, 0
	s_add_i32 s76, s94, s67
	global_load_lds_dwordx4 v[192:193], off
	v_lshl_add_u64 v[192:193], s[74:75], 0, v[172:173]
	s_mov_b32 m0, s76
	s_nop 0
	global_load_lds_dwordx4 v[192:193], off
	v_lshl_add_u64 v[192:193], s[74:75], 0, v[168:169]
	s_add_i32 m0, s76, 0x2000
	s_nop 0
	global_load_lds_dwordx4 v[192:193], off
	v_lshl_add_u64 v[192:193], v[210:211], 0, s[10:11]
	s_mov_b32 m0, s79
	s_nop 0
	global_load_lds_dwordx4 v[192:193], off
	v_lshl_add_u64 v[192:193], v[224:225], 0, s[10:11]
	s_mov_b32 m0, s80
	s_nop 0
	global_load_lds_dwordx4 v[192:193], off
	s_waitcnt vmcnt(8)
	s_waitcnt lgkmcnt(0)
	s_barrier
	s_setprio 1
	s_waitcnt lgkmcnt(0)
	v_mfma_f32_16x16x32_f16 v[80:83], v[64:67], v[164:167], v[80:83]
	v_mfma_f32_16x16x32_f16 v[60:63], v[72:75], v[164:167], v[60:63]
	v_mfma_f32_16x16x32_f16 v[44:47], v[64:67], v[188:191], v[44:47]
	v_mfma_f32_16x16x32_f16 v[36:39], v[72:75], v[188:191], v[36:39]
	v_mfma_f32_16x16x32_f16 v[28:31], v[64:67], v[204:207], v[28:31]
	v_mfma_f32_16x16x32_f16 v[20:23], v[72:75], v[204:207], v[20:23]
	v_mfma_f32_16x16x32_f16 v[12:15], v[64:67], v[216:219], v[12:15]
	v_mfma_f32_16x16x32_f16 v[4:7], v[72:75], v[216:219], v[4:7]
	v_mfma_f32_16x16x32_f16 v[80:83], v[68:71], v[184:187], v[80:83]
	v_mfma_f32_16x16x32_f16 v[60:63], v[76:79], v[184:187], v[60:63]
	v_mfma_f32_16x16x32_f16 v[44:47], v[68:71], v[200:203], v[44:47]
	v_mfma_f32_16x16x32_f16 v[36:39], v[76:79], v[200:203], v[36:39]
	v_mfma_f32_16x16x32_f16 v[28:31], v[68:71], v[212:215], v[28:31]
	v_mfma_f32_16x16x32_f16 v[20:23], v[76:79], v[212:215], v[20:23]
	v_mfma_f32_16x16x32_f16 v[12:15], v[68:71], v[220:223], v[12:15]
	v_mfma_f32_16x16x32_f16 v[4:7], v[76:79], v[220:223], v[4:7]
	s_setprio 0
	s_setprio 1
	v_mfma_f32_16x16x32_f16 v[56:59], v[100:103], v[164:167], v[56:59]
	v_mfma_f32_16x16x32_f16 v[48:51], v[156:159], v[164:167], v[48:51]
	v_mfma_f32_16x16x32_f16 v[40:43], v[100:103], v[188:191], v[40:43]
	v_mfma_f32_16x16x32_f16 v[32:35], v[156:159], v[188:191], v[32:35]
	v_mfma_f32_16x16x32_f16 v[24:27], v[100:103], v[204:207], v[24:27]
	v_mfma_f32_16x16x32_f16 v[16:19], v[156:159], v[204:207], v[16:19]
	v_mfma_f32_16x16x32_f16 v[8:11], v[100:103], v[216:219], v[8:11]
	v_mfma_f32_16x16x32_f16 v[0:3], v[156:159], v[216:219], v[0:3]
	v_mfma_f32_16x16x32_f16 v[68:71], v[136:139], v[184:187], v[56:59]
	v_mfma_f32_16x16x32_f16 v[48:51], v[160:163], v[184:187], v[48:51]
	v_mfma_f32_16x16x32_f16 v[40:43], v[136:139], v[200:203], v[40:43]
	v_mfma_f32_16x16x32_f16 v[32:35], v[160:163], v[200:203], v[32:35]
	v_mfma_f32_16x16x32_f16 v[24:27], v[136:139], v[212:215], v[24:27]
	v_mfma_f32_16x16x32_f16 v[16:19], v[160:163], v[212:215], v[16:19]
	v_mfma_f32_16x16x32_f16 v[8:11], v[136:139], v[220:223], v[8:11]
	v_mfma_f32_16x16x32_f16 v[0:3], v[160:163], v[220:223], v[0:3]
	s_add_i32 s92, s92, 2
	s_add_u32 s46, s46, 0x100
	s_addc_u32 s47, s47, 0
	s_add_u32 s90, s90, 0x100
	s_addc_u32 s91, s91, 0
	s_cmp_gt_u32 s92, 13
	s_setprio 0
	s_barrier
	s_cbranch_scc1 .LBB0_749

.Lrlx10b_done:
	s_mov_b32 s99, 0
	s_waitcnt lgkmcnt(0)
	s_barrier
	s_setprio 1
	s_waitcnt lgkmcnt(0)
	v_mfma_f32_16x16x32_f16 v[96:99], v[40:43], v[144:147], v[96:99]
	v_mfma_f32_16x16x32_f16 v[92:95], v[48:51], v[144:147], v[92:95]
	v_mfma_f32_16x16x32_f16 v[80:83], v[40:43], v[172:175], v[80:83]
	v_mfma_f32_16x16x32_f16 v[76:79], v[48:51], v[172:175], v[76:79]
	v_mfma_f32_16x16x32_f16 v[28:31], v[40:43], v[202:205], v[28:31]
	v_mfma_f32_16x16x32_f16 v[24:27], v[48:51], v[202:205], v[24:27]
	v_mfma_f32_16x16x32_f16 v[12:15], v[40:43], v[212:215], v[12:15]
	v_mfma_f32_16x16x32_f16 v[8:11], v[48:51], v[212:215], v[8:11]
	v_mfma_f32_16x16x32_f16 v[96:99], v[44:47], v[156:159], v[96:99]
	v_mfma_f32_16x16x32_f16 v[92:95], v[56:59], v[156:159], v[92:95]
	v_mfma_f32_16x16x32_f16 v[80:83], v[44:47], v[198:201], v[80:83]
	v_mfma_f32_16x16x32_f16 v[76:79], v[56:59], v[198:201], v[76:79]
	v_mfma_f32_16x16x32_f16 v[28:31], v[44:47], v[206:209], v[28:31]
	v_mfma_f32_16x16x32_f16 v[24:27], v[56:59], v[206:209], v[24:27]
	v_mfma_f32_16x16x32_f16 v[12:15], v[44:47], v[216:219], v[12:15]
	v_mfma_f32_16x16x32_f16 v[8:11], v[56:59], v[216:219], v[8:11]
	s_setprio 0
	s_setprio 1
	v_mfma_f32_16x16x32_f16 v[36:39], v[68:71], v[172:175], v[36:39]
	v_mfma_f32_16x16x32_f16 v[20:23], v[60:63], v[202:205], v[20:23]
	v_mfma_f32_16x16x32_f16 v[16:19], v[68:71], v[202:205], v[16:19]
	v_mfma_f32_16x16x32_f16 v[4:7], v[60:63], v[212:215], v[4:7]
	v_mfma_f32_16x16x32_f16 v[0:3], v[68:71], v[212:215], v[0:3]
	v_mfma_f32_16x16x32_f16 v[40:43], v[60:63], v[144:147], v[88:91]
	v_mfma_f32_16x16x32_f16 v[44:47], v[68:71], v[144:147], v[84:87]
	v_mfma_f32_16x16x32_f16 v[48:51], v[60:63], v[172:175], v[52:55]
	v_mfma_f32_16x16x32_f16 v[36:39], v[72:75], v[198:201], v[36:39]
	v_mfma_f32_16x16x32_f16 v[20:23], v[64:67], v[206:209], v[20:23]
	v_mfma_f32_16x16x32_f16 v[16:19], v[72:75], v[206:209], v[16:19]
	v_mfma_f32_16x16x32_f16 v[4:7], v[64:67], v[216:219], v[4:7]
	v_mfma_f32_16x16x32_f16 v[0:3], v[72:75], v[216:219], v[0:3]
	v_mfma_f32_16x16x32_f16 v[40:43], v[64:67], v[156:159], v[40:43]
	v_mfma_f32_16x16x32_f16 v[44:47], v[72:75], v[156:159], v[44:47]
	v_mfma_f32_16x16x32_f16 v[48:51], v[64:67], v[198:201], v[48:51]
	s_setprio 0
	s_barrier
	s_add_i32 vcc_lo, 0, 0x18000
	s_add_i32 vcc_hi, 0, 0x1c000
	v_add_u32_e32 v64, vcc_lo, v194
	v_add_u32_e32 v84, vcc_hi, v194
	ds_read_b128 v[52:55], v64
	ds_read_b128 v[56:59], v64 offset:1024
	ds_read_b128 v[60:63], v64 offset:2048
	ds_read_b128 v[64:67], v64 offset:3072
	ds_read_b128 v[68:71], v84
	ds_read_b128 v[72:75], v84 offset:1024
	ds_read_b128 v[172:175], v84 offset:2048
	ds_read_b128 v[198:201], v84 offset:3072
	s_add_u32 s86, s96, 0x40000
	s_addc_u32 s87, s97, 0
	s_mov_b32 m0, s64
	v_lshl_add_u64 v[144:145], s[86:87], 0, v[176:177]
	ds_read_b128 v[84:87], v196 offset:32768
	ds_read_b128 v[88:91], v196 offset:33792
	ds_read_b128 v[202:205], v196 offset:34816
	ds_read_b128 v[206:209], v196 offset:35840
	ds_read_b128 v[212:215], v196 offset:36864
	ds_read_b128 v[216:219], v196 offset:37888
	ds_read_b128 v[220:223], v196 offset:38912
	ds_read_b128 v[224:227], v196 offset:39936
	global_load_lds_dwordx4 v[144:145], off
	v_lshl_add_u64 v[144:145], s[86:87], 0, v[180:181]
	s_mov_b32 m0, s65
	s_nop 0
	global_load_lds_dwordx4 v[144:145], off
	s_waitcnt vmcnt(8)
	s_waitcnt lgkmcnt(0)
	s_barrier
	s_setprio 1
	s_waitcnt lgkmcnt(0)
	v_mfma_f32_16x16x32_f16 v[144:147], v[52:55], v[84:87], v[168:171]
	v_mfma_f32_16x16x32_f16 v[168:171], v[56:59], v[88:91], v[144:147]
	v_mfma_f32_16x16x32_f16 v[144:147], v[60:63], v[84:87], v[164:167]
	v_mfma_f32_16x16x32_f16 v[164:167], v[64:67], v[88:91], v[144:147]
	v_mfma_f32_16x16x32_f16 v[144:147], v[52:55], v[202:205], v[152:155]
	v_mfma_f32_16x16x32_f16 v[152:155], v[56:59], v[206:209], v[144:147]
	v_mfma_f32_16x16x32_f16 v[144:147], v[60:63], v[202:205], v[148:151]
	v_mfma_f32_16x16x32_f16 v[132:135], v[52:55], v[212:215], v[132:135]
	v_mfma_f32_16x16x32_f16 v[128:131], v[60:63], v[212:215], v[128:131]
	v_mfma_f32_16x16x32_f16 v[116:119], v[52:55], v[220:223], v[116:119]
	v_mfma_f32_16x16x32_f16 v[112:115], v[60:63], v[220:223], v[112:115]
	v_mfma_f32_16x16x32_f16 v[148:151], v[64:67], v[206:209], v[144:147]
	v_mfma_f32_16x16x32_f16 v[132:135], v[56:59], v[216:219], v[132:135]
	v_mfma_f32_16x16x32_f16 v[128:131], v[64:67], v[216:219], v[128:131]
	v_mfma_f32_16x16x32_f16 v[116:119], v[56:59], v[224:227], v[116:119]
	v_mfma_f32_16x16x32_f16 v[112:115], v[64:67], v[224:227], v[112:115]
	s_setprio 0
	s_setprio 1
	v_mfma_f32_16x16x32_f16 v[144:147], v[68:71], v[84:87], v[160:163]
	v_mfma_f32_16x16x32_f16 v[84:87], v[172:175], v[84:87], v[100:103]
	v_mfma_f32_16x16x32_f16 v[156:159], v[198:201], v[88:91], v[84:87]
	v_mfma_f32_16x16x32_f16 v[84:87], v[68:71], v[202:205], v[136:139]
	v_mfma_f32_16x16x32_f16 v[160:163], v[72:75], v[88:91], v[144:147]
	v_mfma_f32_16x16x32_f16 v[144:147], v[72:75], v[206:209], v[84:87]
	v_mfma_f32_16x16x32_f16 v[84:87], v[172:175], v[202:205], v[140:143]
	v_mfma_f32_16x16x32_f16 v[140:143], v[198:201], v[206:209], v[84:87]
	v_mfma_f32_16x16x32_f16 v[84:87], v[68:71], v[212:215], v[124:127]
	v_mfma_f32_16x16x32_f16 v[124:127], v[72:75], v[216:219], v[84:87]
	v_mfma_f32_16x16x32_f16 v[84:87], v[172:175], v[212:215], v[120:123]
	v_mfma_f32_16x16x32_f16 v[120:123], v[198:201], v[216:219], v[84:87]
	v_mfma_f32_16x16x32_f16 v[84:87], v[68:71], v[220:223], v[108:111]
	v_mfma_f32_16x16x32_f16 v[108:111], v[72:75], v[224:227], v[84:87]
	v_mfma_f32_16x16x32_f16 v[84:87], v[172:175], v[220:223], v[104:107]
	v_mfma_f32_16x16x32_f16 v[104:107], v[198:201], v[224:227], v[84:87]
	s_setprio 0
	s_barrier
	s_add_i32 s86, vcc_lo, s90
	v_lshl_add_u64 v[88:89], v[210:211], 0, s[12:13]
	s_mov_b32 m0, s86
	s_nop 1
	ds_read_b128 v[84:87], v196 offset:49152
	ds_read_b128 v[100:103], v196 offset:50176
	ds_read_b128 v[136:139], v196 offset:51200
	ds_read_b128 v[202:205], v196 offset:52224
	ds_read_b128 v[206:209], v196 offset:53248
	ds_read_b128 v[212:215], v196 offset:54272
	ds_read_b128 v[216:219], v196 offset:55296
	ds_read_b128 v[220:223], v196 offset:56320
	global_load_lds_dwordx4 v[88:89], off
	s_add_i32 m0, s86, 0x2000
	s_add_u32 s86, s94, 0x40080
	v_lshl_add_u64 v[88:89], v[228:229], 0, s[12:13]
	s_addc_u32 s87, s95, 0
	s_add_i32 s94, vcc_hi, s90
	global_load_lds_dwordx4 v[88:89], off
	v_lshl_add_u64 v[88:89], s[86:87], 0, v[178:179]
	s_mov_b32 m0, s94
	s_nop 0
	global_load_lds_dwordx4 v[88:89], off
	v_lshl_add_u64 v[88:89], s[86:87], 0, v[182:183]
	s_add_i32 m0, s94, 0x2000
	s_nop 0
	global_load_lds_dwordx4 v[88:89], off
	v_lshl_add_u64 v[88:89], v[230:231], 0, s[12:13]
	s_mov_b32 m0, s72
	s_nop 0
	global_load_lds_dwordx4 v[88:89], off
	v_lshl_add_u64 v[88:89], v[232:233], 0, s[12:13]
	s_mov_b32 m0, s73
	s_nop 0
	global_load_lds_dwordx4 v[88:89], off
	s_waitcnt vmcnt(8)
	s_waitcnt lgkmcnt(0)
	s_barrier
	s_setprio 1
	s_waitcnt lgkmcnt(0)
	v_mfma_f32_16x16x32_f16 v[88:91], v[52:55], v[84:87], v[96:99]
	v_mfma_f32_16x16x32_f16 v[96:99], v[56:59], v[100:103], v[88:91]
	v_mfma_f32_16x16x32_f16 v[88:91], v[60:63], v[84:87], v[92:95]
	v_mfma_f32_16x16x32_f16 v[80:83], v[52:55], v[136:139], v[80:83]
	v_mfma_f32_16x16x32_f16 v[76:79], v[60:63], v[136:139], v[76:79]
	v_mfma_f32_16x16x32_f16 v[28:31], v[52:55], v[206:209], v[28:31]
	v_mfma_f32_16x16x32_f16 v[24:27], v[60:63], v[206:209], v[24:27]
	v_mfma_f32_16x16x32_f16 v[12:15], v[52:55], v[216:219], v[12:15]
	v_mfma_f32_16x16x32_f16 v[8:11], v[60:63], v[216:219], v[8:11]
	v_mfma_f32_16x16x32_f16 v[92:95], v[64:67], v[100:103], v[88:91]
	v_mfma_f32_16x16x32_f16 v[80:83], v[56:59], v[202:205], v[80:83]
	v_mfma_f32_16x16x32_f16 v[76:79], v[64:67], v[202:205], v[76:79]
	v_mfma_f32_16x16x32_f16 v[28:31], v[56:59], v[212:215], v[28:31]
	v_mfma_f32_16x16x32_f16 v[24:27], v[64:67], v[212:215], v[24:27]
	v_mfma_f32_16x16x32_f16 v[12:15], v[56:59], v[220:223], v[12:15]
	v_mfma_f32_16x16x32_f16 v[8:11], v[64:67], v[220:223], v[8:11]
	s_setprio 0
	s_setprio 1
	v_mfma_f32_16x16x32_f16 v[40:43], v[68:71], v[84:87], v[40:43]
	v_mfma_f32_16x16x32_f16 v[88:91], v[72:75], v[100:103], v[40:43]
	v_mfma_f32_16x16x32_f16 v[40:43], v[172:175], v[84:87], v[44:47]
	v_mfma_f32_16x16x32_f16 v[84:87], v[198:201], v[100:103], v[40:43]
	v_mfma_f32_16x16x32_f16 v[40:43], v[68:71], v[136:139], v[48:51]
	v_mfma_f32_16x16x32_f16 v[36:39], v[172:175], v[136:139], v[36:39]
	v_mfma_f32_16x16x32_f16 v[20:23], v[68:71], v[206:209], v[20:23]
	v_mfma_f32_16x16x32_f16 v[16:19], v[172:175], v[206:209], v[16:19]
	v_mfma_f32_16x16x32_f16 v[4:7], v[68:71], v[216:219], v[4:7]
	v_mfma_f32_16x16x32_f16 v[0:3], v[172:175], v[216:219], v[0:3]
	v_mfma_f32_16x16x32_f16 v[52:55], v[72:75], v[202:205], v[40:43]
	v_mfma_f32_16x16x32_f16 v[36:39], v[198:201], v[202:205], v[36:39]
	v_mfma_f32_16x16x32_f16 v[20:23], v[72:75], v[212:215], v[20:23]
	v_mfma_f32_16x16x32_f16 v[16:19], v[198:201], v[212:215], v[16:19]
	v_mfma_f32_16x16x32_f16 v[4:7], v[72:75], v[220:223], v[4:7]
	v_mfma_f32_16x16x32_f16 v[0:3], v[198:201], v[220:223], v[0:3]
	s_add_i32 s83, s83, 2
	s_add_u32 s46, s46, 0x100
	s_addc_u32 s47, s47, 0
	s_add_u32 s67, s67, 0x100
	s_addc_u32 s75, s75, 0
	s_cmp_gt_u32 s83, 13
	s_setprio 0
	s_barrier
	s_cbranch_scc1 .LBB0_1069

.Lrlx13p0b_done:
	s_mov_b32 s99, 0
	s_waitcnt lgkmcnt(0)
	s_barrier
	s_setprio 1
	s_waitcnt lgkmcnt(0)
	v_mfma_f32_16x16x32_bf16 v[60:63], v[128:131], v[184:187], v[60:63]
	v_mfma_f32_16x16x32_bf16 v[56:59], v[136:139], v[184:187], v[56:59]
	v_mfma_f32_16x16x32_bf16 v[48:51], v[128:131], v[192:195], v[48:51]
	v_mfma_f32_16x16x32_bf16 v[40:43], v[136:139], v[192:195], v[40:43]
	v_mfma_f32_16x16x32_bf16 v[32:35], v[128:131], v[200:203], v[32:35]
	v_mfma_f32_16x16x32_bf16 v[24:27], v[136:139], v[200:203], v[24:27]
	v_mfma_f32_16x16x32_bf16 v[16:19], v[128:131], v[212:215], v[16:19]
	v_mfma_f32_16x16x32_bf16 v[8:11], v[136:139], v[212:215], v[8:11]
	v_mfma_f32_16x16x32_bf16 v[60:63], v[132:135], v[188:191], v[60:63]
	v_mfma_f32_16x16x32_bf16 v[56:59], v[140:143], v[188:191], v[56:59]
	v_mfma_f32_16x16x32_bf16 v[48:51], v[132:135], v[196:199], v[48:51]
	v_mfma_f32_16x16x32_bf16 v[40:43], v[140:143], v[196:199], v[40:43]
	v_mfma_f32_16x16x32_bf16 v[32:35], v[132:135], v[204:207], v[32:35]
	v_mfma_f32_16x16x32_bf16 v[24:27], v[140:143], v[204:207], v[24:27]
	v_mfma_f32_16x16x32_bf16 v[16:19], v[132:135], v[216:219], v[16:19]
	v_mfma_f32_16x16x32_bf16 v[8:11], v[140:143], v[216:219], v[8:11]
	s_setprio 0
	s_setprio 1
	v_mfma_f32_16x16x32_bf16 v[52:55], v[144:147], v[184:187], v[52:55]
	v_mfma_f32_16x16x32_bf16 v[44:47], v[168:171], v[184:187], v[44:47]
	v_mfma_f32_16x16x32_bf16 v[36:39], v[144:147], v[192:195], v[36:39]
	v_mfma_f32_16x16x32_bf16 v[28:31], v[168:171], v[192:195], v[28:31]
	v_mfma_f32_16x16x32_bf16 v[20:23], v[144:147], v[200:203], v[20:23]
	v_mfma_f32_16x16x32_bf16 v[12:15], v[168:171], v[200:203], v[12:15]
	v_mfma_f32_16x16x32_bf16 v[4:7], v[144:147], v[212:215], v[4:7]
	v_mfma_f32_16x16x32_bf16 v[0:3], v[168:171], v[212:215], v[0:3]
	v_mfma_f32_16x16x32_bf16 v[52:55], v[148:151], v[188:191], v[52:55]
	v_mfma_f32_16x16x32_bf16 v[44:47], v[172:175], v[188:191], v[44:47]
	v_mfma_f32_16x16x32_bf16 v[36:39], v[148:151], v[196:199], v[36:39]
	v_mfma_f32_16x16x32_bf16 v[28:31], v[172:175], v[196:199], v[28:31]
	v_mfma_f32_16x16x32_bf16 v[20:23], v[148:151], v[204:207], v[20:23]
	v_mfma_f32_16x16x32_bf16 v[12:15], v[172:175], v[204:207], v[12:15]
	v_mfma_f32_16x16x32_bf16 v[4:7], v[148:151], v[216:219], v[4:7]
	v_mfma_f32_16x16x32_bf16 v[0:3], v[172:175], v[216:219], v[0:3]
	s_setprio 0
	s_barrier
	s_add_i32 s83, 0, 0x18000
	s_add_i32 s84, 0, 0x1c000
	v_add_u32_e32 v140, s83, v180
	v_add_u32_e32 v172, s84, v180
	ds_read_b128 v[128:131], v140
	ds_read_b128 v[132:135], v140 offset:1024
	ds_read_b128 v[136:139], v140 offset:2048
	ds_read_b128 v[140:143], v140 offset:3072
	ds_read_b128 v[144:147], v172
	ds_read_b128 v[148:151], v172 offset:1024
	ds_read_b128 v[168:171], v172 offset:2048
	ds_read_b128 v[172:175], v172 offset:3072
	s_add_u32 s60, s60, 0x20000
	s_addc_u32 s61, s61, 0
	s_mov_b32 m0, s67
	v_lshl_add_u64 v[222:223], s[60:61], 0, v[152:153]
	ds_read_b128 v[184:187], v183 offset:32768
	ds_read_b128 v[188:191], v183 offset:33792
	ds_read_b128 v[192:195], v183 offset:34816
	ds_read_b128 v[196:199], v183 offset:35840
	ds_read_b128 v[200:203], v183 offset:36864
	ds_read_b128 v[204:207], v183 offset:37888
	ds_read_b128 v[212:215], v183 offset:38912
	ds_read_b128 v[216:219], v183 offset:39936
	global_load_lds_dwordx4 v[222:223], off
	v_lshl_add_u64 v[222:223], s[60:61], 0, v[156:157]
	s_mov_b32 m0, s68
	s_nop 0
	global_load_lds_dwordx4 v[222:223], off
	s_waitcnt vmcnt(8)
	s_waitcnt lgkmcnt(0)
	s_barrier
	s_setprio 1
	s_waitcnt lgkmcnt(0)
	v_mfma_f32_16x16x32_bf16 v[124:127], v[128:131], v[184:187], v[124:127]
	v_mfma_f32_16x16x32_bf16 v[120:123], v[136:139], v[184:187], v[120:123]
	v_mfma_f32_16x16x32_bf16 v[108:111], v[128:131], v[192:195], v[108:111]
	v_mfma_f32_16x16x32_bf16 v[104:107], v[136:139], v[192:195], v[104:107]
	v_mfma_f32_16x16x32_bf16 v[96:99], v[128:131], v[200:203], v[96:99]
	v_mfma_f32_16x16x32_bf16 v[88:91], v[136:139], v[200:203], v[88:91]
	v_mfma_f32_16x16x32_bf16 v[80:83], v[128:131], v[212:215], v[80:83]
	v_mfma_f32_16x16x32_bf16 v[72:75], v[136:139], v[212:215], v[72:75]
	v_mfma_f32_16x16x32_bf16 v[124:127], v[132:135], v[188:191], v[124:127]
	v_mfma_f32_16x16x32_bf16 v[120:123], v[140:143], v[188:191], v[120:123]
	v_mfma_f32_16x16x32_bf16 v[108:111], v[132:135], v[196:199], v[108:111]
	v_mfma_f32_16x16x32_bf16 v[104:107], v[140:143], v[196:199], v[104:107]
	v_mfma_f32_16x16x32_bf16 v[96:99], v[132:135], v[204:207], v[96:99]
	v_mfma_f32_16x16x32_bf16 v[88:91], v[140:143], v[204:207], v[88:91]
	v_mfma_f32_16x16x32_bf16 v[80:83], v[132:135], v[216:219], v[80:83]
	v_mfma_f32_16x16x32_bf16 v[72:75], v[140:143], v[216:219], v[72:75]
	s_setprio 0
	s_setprio 1
	v_mfma_f32_16x16x32_bf16 v[116:119], v[144:147], v[184:187], v[116:119]
	v_mfma_f32_16x16x32_bf16 v[112:115], v[168:171], v[184:187], v[112:115]
	v_mfma_f32_16x16x32_bf16 v[100:103], v[144:147], v[192:195], v[100:103]
	v_mfma_f32_16x16x32_bf16 v[92:95], v[168:171], v[192:195], v[92:95]
	v_mfma_f32_16x16x32_bf16 v[84:87], v[144:147], v[200:203], v[84:87]
	v_mfma_f32_16x16x32_bf16 v[76:79], v[168:171], v[200:203], v[76:79]
	v_mfma_f32_16x16x32_bf16 v[68:71], v[144:147], v[212:215], v[68:71]
	v_mfma_f32_16x16x32_bf16 v[64:67], v[168:171], v[212:215], v[64:67]
	v_mfma_f32_16x16x32_bf16 v[116:119], v[148:151], v[188:191], v[116:119]
	v_mfma_f32_16x16x32_bf16 v[112:115], v[172:175], v[188:191], v[112:115]
	v_mfma_f32_16x16x32_bf16 v[100:103], v[148:151], v[196:199], v[100:103]
	v_mfma_f32_16x16x32_bf16 v[92:95], v[172:175], v[196:199], v[92:95]
	v_mfma_f32_16x16x32_bf16 v[84:87], v[148:151], v[204:207], v[84:87]
	v_mfma_f32_16x16x32_bf16 v[76:79], v[172:175], v[204:207], v[76:79]
	v_mfma_f32_16x16x32_bf16 v[68:71], v[148:151], v[216:219], v[68:71]
	v_mfma_f32_16x16x32_bf16 v[64:67], v[172:175], v[216:219], v[64:67]
	s_setprio 0
	s_barrier
	s_add_i32 s60, s83, s64
	v_lshl_add_u64 v[176:177], v[176:177], 0, s[4:5]
	s_mov_b32 m0, s60
	ds_read_b128 v[184:187], v183 offset:49152
	ds_read_b128 v[188:191], v183 offset:50176
	ds_read_b128 v[192:195], v183 offset:51200
	ds_read_b128 v[196:199], v183 offset:52224
	ds_read_b128 v[200:203], v183 offset:53248
	ds_read_b128 v[204:207], v183 offset:54272
	ds_read_b128 v[212:215], v183 offset:55296
	ds_read_b128 v[216:219], v183 offset:56320
	global_load_lds_dwordx4 v[176:177], off
	s_add_i32 m0, s60, 0x2000
	s_add_u32 s46, s46, 0x20080
	v_lshl_add_u64 v[176:177], v[208:209], 0, s[4:5]
	s_addc_u32 s47, s47, 0
	s_add_i32 s60, s84, s64
	global_load_lds_dwordx4 v[176:177], off
	v_lshl_add_u64 v[176:177], s[46:47], 0, v[154:155]
	s_mov_b32 m0, s60
	s_nop 0
	global_load_lds_dwordx4 v[176:177], off
	v_lshl_add_u64 v[176:177], s[46:47], 0, v[158:159]
	s_add_i32 m0, s60, 0x2000
	s_nop 0
	global_load_lds_dwordx4 v[176:177], off
	v_lshl_add_u64 v[176:177], v[210:211], 0, s[4:5]
	s_mov_b32 m0, s72
	s_nop 0
	global_load_lds_dwordx4 v[176:177], off
	v_lshl_add_u64 v[176:177], v[220:221], 0, s[4:5]
	s_mov_b32 m0, s73
	s_nop 0
	global_load_lds_dwordx4 v[176:177], off
	s_waitcnt vmcnt(8)
	s_waitcnt lgkmcnt(0)
	s_barrier
	s_setprio 1
	s_waitcnt lgkmcnt(0)
	v_mfma_f32_16x16x32_bf16 v[60:63], v[128:131], v[184:187], v[60:63]
	v_mfma_f32_16x16x32_bf16 v[56:59], v[136:139], v[184:187], v[56:59]
	v_mfma_f32_16x16x32_bf16 v[48:51], v[128:131], v[192:195], v[48:51]
	v_mfma_f32_16x16x32_bf16 v[40:43], v[136:139], v[192:195], v[40:43]
	v_mfma_f32_16x16x32_bf16 v[32:35], v[128:131], v[200:203], v[32:35]
	v_mfma_f32_16x16x32_bf16 v[24:27], v[136:139], v[200:203], v[24:27]
	v_mfma_f32_16x16x32_bf16 v[16:19], v[128:131], v[212:215], v[16:19]
	v_mfma_f32_16x16x32_bf16 v[8:11], v[136:139], v[212:215], v[8:11]
	v_mfma_f32_16x16x32_bf16 v[60:63], v[132:135], v[188:191], v[60:63]
	v_mfma_f32_16x16x32_bf16 v[56:59], v[140:143], v[188:191], v[56:59]
	v_mfma_f32_16x16x32_bf16 v[48:51], v[132:135], v[196:199], v[48:51]
	v_mfma_f32_16x16x32_bf16 v[40:43], v[140:143], v[196:199], v[40:43]
	v_mfma_f32_16x16x32_bf16 v[32:35], v[132:135], v[204:207], v[32:35]
	v_mfma_f32_16x16x32_bf16 v[24:27], v[140:143], v[204:207], v[24:27]
	v_mfma_f32_16x16x32_bf16 v[16:19], v[132:135], v[216:219], v[16:19]
	v_mfma_f32_16x16x32_bf16 v[8:11], v[140:143], v[216:219], v[8:11]
	s_setprio 0
	s_setprio 1
	v_mfma_f32_16x16x32_bf16 v[52:55], v[144:147], v[184:187], v[52:55]
	v_mfma_f32_16x16x32_bf16 v[44:47], v[168:171], v[184:187], v[44:47]
	v_mfma_f32_16x16x32_bf16 v[36:39], v[144:147], v[192:195], v[36:39]
	v_mfma_f32_16x16x32_bf16 v[28:31], v[168:171], v[192:195], v[28:31]
	v_mfma_f32_16x16x32_bf16 v[20:23], v[144:147], v[200:203], v[20:23]
	v_mfma_f32_16x16x32_bf16 v[12:15], v[168:171], v[200:203], v[12:15]
	v_mfma_f32_16x16x32_bf16 v[4:7], v[144:147], v[212:215], v[4:7]
	v_mfma_f32_16x16x32_bf16 v[0:3], v[168:171], v[212:215], v[0:3]
	v_mfma_f32_16x16x32_bf16 v[52:55], v[148:151], v[188:191], v[52:55]
	v_mfma_f32_16x16x32_bf16 v[44:47], v[172:175], v[188:191], v[44:47]
	v_mfma_f32_16x16x32_bf16 v[36:39], v[148:151], v[196:199], v[36:39]
	v_mfma_f32_16x16x32_bf16 v[28:31], v[172:175], v[196:199], v[28:31]
	v_mfma_f32_16x16x32_bf16 v[20:23], v[148:151], v[204:207], v[20:23]
	v_mfma_f32_16x16x32_bf16 v[12:15], v[172:175], v[204:207], v[12:15]
	v_mfma_f32_16x16x32_bf16 v[4:7], v[148:151], v[216:219], v[4:7]
	v_mfma_f32_16x16x32_bf16 v[0:3], v[172:175], v[216:219], v[0:3]
	s_add_i32 s82, s82, 2
	s_add_u32 s40, s40, 0x100
	s_addc_u32 s41, s41, 0
	s_add_u32 s80, s80, 0x100
	s_addc_u32 s81, s81, 0
	s_cmp_gt_u32 s82, 5
	s_setprio 0
	s_barrier
	s_cbranch_scc0 .LBB0_1413
	s_and_b64 vcc, exec, s[6:7]
	s_cbranch_vccz .LBB0_1416
	s_barrier

.LBB0_1513:
	v_add_u32_e32 v137, s70, v159
	ds_read_b128 v[146:149], v137
	ds_read_b128 v[162:165], v137 offset:1024
	ds_read_b128 v[166:169], v137 offset:2048
	ds_read_b128 v[170:173], v137 offset:3072
	v_add_u32_e32 v137, s71, v159
	ds_read_b128 v[174:177], v137
	ds_read_b128 v[178:181], v137 offset:1024
	ds_read_b128 v[182:185], v137 offset:2048
	ds_read_b128 v[186:189], v137 offset:3072
	s_add_u32 s40, s46, 0xfffc0080
	s_addc_u32 s41, s47, -1
	s_cmp_eq_u32 s81, 12
	s_cselect_b32 s75, s37, s41
	s_cselect_b32 s74, s73, s40
	s_cselect_b32 s41, s35, s80
	s_cselect_b32 s40, s78, s79
	v_lshl_add_u64 v[210:211], s[46:47], 0, v[138:139]
	s_add_i32 m0, s67, 0xc000
	ds_read_b128 v[190:193], v161
	ds_read_b128 v[194:197], v161 offset:1024
	ds_read_b128 v[198:201], v161 offset:2048
	ds_read_b128 v[202:205], v161 offset:3072
	ds_read_b128 v[206:209], v161 offset:4096
	ds_read_b128 v[212:215], v161 offset:5120
	ds_read_b128 v[216:219], v161 offset:6144
	ds_read_b128 v[220:223], v161 offset:7168
	global_load_lds_dwordx4 v[210:211], off
	v_lshl_add_u64 v[210:211], s[46:47], 0, v[140:141]
	s_add_i32 m0, s67, 0xe000
	s_nop 0
	global_load_lds_dwordx4 v[210:211], off
	s_waitcnt vmcnt(8)
	s_waitcnt lgkmcnt(0)
	s_barrier
	s_setprio 1
	s_waitcnt lgkmcnt(0)
	v_mfma_f32_16x16x32_bf16 v[64:67], v[146:149], v[190:193], v[64:67]
	v_mfma_f32_16x16x32_bf16 v[68:71], v[166:169], v[190:193], v[68:71]
	v_mfma_f32_16x16x32_bf16 v[48:51], v[146:149], v[198:201], v[48:51]
	v_mfma_f32_16x16x32_bf16 v[52:55], v[166:169], v[198:201], v[52:55]
	v_mfma_f32_16x16x32_bf16 v[40:43], v[146:149], v[206:209], v[40:43]
	v_mfma_f32_16x16x32_bf16 v[44:47], v[166:169], v[206:209], v[44:47]
	v_mfma_f32_16x16x32_bf16 v[32:35], v[146:149], v[216:219], v[32:35]
	v_mfma_f32_16x16x32_bf16 v[36:39], v[166:169], v[216:219], v[36:39]
	v_mfma_f32_16x16x32_bf16 v[64:67], v[162:165], v[194:197], v[64:67]
	v_mfma_f32_16x16x32_bf16 v[68:71], v[170:173], v[194:197], v[68:71]
	v_mfma_f32_16x16x32_bf16 v[48:51], v[162:165], v[202:205], v[48:51]
	v_mfma_f32_16x16x32_bf16 v[52:55], v[170:173], v[202:205], v[52:55]
	v_mfma_f32_16x16x32_bf16 v[40:43], v[162:165], v[212:215], v[40:43]
	v_mfma_f32_16x16x32_bf16 v[44:47], v[170:173], v[212:215], v[44:47]
	v_mfma_f32_16x16x32_bf16 v[32:35], v[162:165], v[220:223], v[32:35]
	v_mfma_f32_16x16x32_bf16 v[36:39], v[170:173], v[220:223], v[36:39]
	s_setprio 0
	s_setprio 1
	v_mfma_f32_16x16x32_bf16 v[120:123], v[174:177], v[190:193], v[120:123]
	v_mfma_f32_16x16x32_bf16 v[124:127], v[182:185], v[190:193], v[124:127]
	v_mfma_f32_16x16x32_bf16 v[112:115], v[174:177], v[198:201], v[112:115]
	v_mfma_f32_16x16x32_bf16 v[116:119], v[182:185], v[198:201], v[116:119]
	v_mfma_f32_16x16x32_bf16 v[104:107], v[174:177], v[206:209], v[104:107]
	v_mfma_f32_16x16x32_bf16 v[108:111], v[182:185], v[206:209], v[108:111]
	v_mfma_f32_16x16x32_bf16 v[96:99], v[174:177], v[216:219], v[96:99]
	v_mfma_f32_16x16x32_bf16 v[100:103], v[182:185], v[216:219], v[100:103]
	v_mfma_f32_16x16x32_bf16 v[120:123], v[178:181], v[194:197], v[120:123]
	v_mfma_f32_16x16x32_bf16 v[124:127], v[186:189], v[194:197], v[124:127]
	v_mfma_f32_16x16x32_bf16 v[112:115], v[178:181], v[202:205], v[112:115]
	v_mfma_f32_16x16x32_bf16 v[116:119], v[186:189], v[202:205], v[116:119]
	v_mfma_f32_16x16x32_bf16 v[104:107], v[178:181], v[212:215], v[104:107]
	v_mfma_f32_16x16x32_bf16 v[108:111], v[186:189], v[212:215], v[108:111]
	v_mfma_f32_16x16x32_bf16 v[96:99], v[178:181], v[220:223], v[96:99]
	v_mfma_f32_16x16x32_bf16 v[100:103], v[186:189], v[220:223], v[100:103]
	s_setprio 0
	s_barrier
	s_add_i32 s84, s70, s7
	v_lshl_add_u64 v[210:211], s[40:41], 0, v[130:131]
	s_mov_b32 m0, s84
	ds_read_b128 v[190:193], v161 offset:16384
	ds_read_b128 v[194:197], v161 offset:17408
	ds_read_b128 v[198:201], v161 offset:18432
	ds_read_b128 v[202:205], v161 offset:19456
	ds_read_b128 v[206:209], v161 offset:20480
	ds_read_b128 v[212:215], v161 offset:21504
	ds_read_b128 v[216:219], v161 offset:22528
	ds_read_b128 v[220:223], v161 offset:23552
	global_load_lds_dwordx4 v[210:211], off
	s_add_i32 m0, s84, 0x2000
	s_add_u32 s84, s40, 0x40000
	v_lshl_add_u64 v[224:225], s[40:41], 0, v[134:135]
	s_addc_u32 s85, s41, 0
	s_add_i32 s86, s71, s7
	global_load_lds_dwordx4 v[224:225], off
	v_lshl_add_u64 v[226:227], s[84:85], 0, v[130:131]
	s_mov_b32 m0, s86
	v_lshl_add_u64 v[228:229], s[74:75], 0, v[132:133]
	global_load_lds_dwordx4 v[226:227], off
	v_lshl_add_u64 v[226:227], s[84:85], 0, v[134:135]
	s_add_i32 m0, s86, 0x2000
	s_nop 0
	global_load_lds_dwordx4 v[226:227], off
	v_lshl_add_u64 v[226:227], s[74:75], 0, v[128:129]
	s_mov_b32 m0, s67
	s_nop 0
	global_load_lds_dwordx4 v[226:227], off
	s_mov_b32 m0, s68
	s_nop 0
	global_load_lds_dwordx4 v[228:229], off
	s_waitcnt vmcnt(8)
	s_waitcnt lgkmcnt(0)
	s_barrier
	s_setprio 1
	s_waitcnt lgkmcnt(0)
	v_mfma_f32_16x16x32_bf16 v[24:27], v[146:149], v[190:193], v[24:27]
	v_mfma_f32_16x16x32_bf16 v[28:31], v[166:169], v[190:193], v[28:31]
	v_mfma_f32_16x16x32_bf16 v[16:19], v[146:149], v[198:201], v[16:19]
	v_mfma_f32_16x16x32_bf16 v[20:23], v[166:169], v[198:201], v[20:23]
	v_mfma_f32_16x16x32_bf16 v[8:11], v[146:149], v[206:209], v[8:11]
	v_mfma_f32_16x16x32_bf16 v[12:15], v[166:169], v[206:209], v[12:15]
	v_mfma_f32_16x16x32_bf16 v[0:3], v[146:149], v[216:219], v[0:3]
	v_mfma_f32_16x16x32_bf16 v[4:7], v[166:169], v[216:219], v[4:7]
	v_mfma_f32_16x16x32_bf16 v[24:27], v[162:165], v[194:197], v[24:27]
	v_mfma_f32_16x16x32_bf16 v[28:31], v[170:173], v[194:197], v[28:31]
	v_mfma_f32_16x16x32_bf16 v[16:19], v[162:165], v[202:205], v[16:19]
	v_mfma_f32_16x16x32_bf16 v[20:23], v[170:173], v[202:205], v[20:23]
	v_mfma_f32_16x16x32_bf16 v[8:11], v[162:165], v[212:215], v[8:11]
	v_mfma_f32_16x16x32_bf16 v[12:15], v[170:173], v[212:215], v[12:15]
	v_mfma_f32_16x16x32_bf16 v[0:3], v[162:165], v[220:223], v[0:3]
	v_mfma_f32_16x16x32_bf16 v[4:7], v[170:173], v[220:223], v[4:7]
	s_setprio 0
	s_setprio 1
	v_mfma_f32_16x16x32_bf16 v[80:83], v[174:177], v[190:193], v[80:83]
	v_mfma_f32_16x16x32_bf16 v[84:87], v[182:185], v[190:193], v[84:87]
	v_mfma_f32_16x16x32_bf16 v[88:91], v[174:177], v[198:201], v[88:91]
	v_mfma_f32_16x16x32_bf16 v[92:95], v[182:185], v[198:201], v[92:95]
	v_mfma_f32_16x16x32_bf16 v[72:75], v[174:177], v[206:209], v[72:75]
	v_mfma_f32_16x16x32_bf16 v[76:79], v[182:185], v[206:209], v[76:79]
	v_mfma_f32_16x16x32_bf16 v[56:59], v[174:177], v[216:219], v[56:59]
	v_mfma_f32_16x16x32_bf16 v[60:63], v[182:185], v[216:219], v[60:63]
	v_mfma_f32_16x16x32_bf16 v[80:83], v[178:181], v[194:197], v[80:83]
	v_mfma_f32_16x16x32_bf16 v[84:87], v[186:189], v[194:197], v[84:87]
	v_mfma_f32_16x16x32_bf16 v[88:91], v[178:181], v[202:205], v[88:91]
	v_mfma_f32_16x16x32_bf16 v[92:95], v[186:189], v[202:205], v[92:95]
	v_mfma_f32_16x16x32_bf16 v[72:75], v[178:181], v[212:215], v[72:75]
	v_mfma_f32_16x16x32_bf16 v[76:79], v[186:189], v[212:215], v[76:79]
	v_mfma_f32_16x16x32_bf16 v[56:59], v[178:181], v[220:223], v[56:59]
	v_mfma_f32_16x16x32_bf16 v[60:63], v[186:189], v[220:223], v[60:63]
	s_setprio 0
	s_barrier
	s_add_i32 s84, 0, 0x18000
	v_add_u32_e32 v137, s84, v159
	s_add_i32 s85, 0, 0x1c000
	ds_read_b128 v[146:149], v137
	ds_read_b128 v[162:165], v137 offset:1024
	ds_read_b128 v[166:169], v137 offset:2048
	ds_read_b128 v[170:173], v137 offset:3072
	v_add_u32_e32 v137, s85, v159
	ds_read_b128 v[174:177], v137
	ds_read_b128 v[178:181], v137 offset:1024
	ds_read_b128 v[182:185], v137 offset:2048
	ds_read_b128 v[186:189], v137 offset:3072
	s_add_u32 s74, s74, 0x40000
	s_addc_u32 s75, s75, 0
	s_mov_b32 m0, s69
	v_lshl_add_u64 v[230:231], s[74:75], 0, v[128:129]
	ds_read_b128 v[190:193], v161 offset:32768
	ds_read_b128 v[194:197], v161 offset:33792
	ds_read_b128 v[198:201], v161 offset:34816
	ds_read_b128 v[202:205], v161 offset:35840
	ds_read_b128 v[206:209], v161 offset:36864
	ds_read_b128 v[212:215], v161 offset:37888
	ds_read_b128 v[216:219], v161 offset:38912
	ds_read_b128 v[220:223], v161 offset:39936
	global_load_lds_dwordx4 v[230:231], off
	v_lshl_add_u64 v[230:231], s[74:75], 0, v[132:133]
	s_mov_b32 m0, s89
	s_nop 0
	global_load_lds_dwordx4 v[230:231], off
	s_waitcnt vmcnt(8)
	s_waitcnt lgkmcnt(0)
	s_barrier
	s_setprio 1
	s_waitcnt lgkmcnt(0)
	v_mfma_f32_16x16x32_bf16 v[64:67], v[146:149], v[190:193], v[64:67]
	v_mfma_f32_16x16x32_bf16 v[68:71], v[166:169], v[190:193], v[68:71]
	v_mfma_f32_16x16x32_bf16 v[48:51], v[146:149], v[198:201], v[48:51]
	v_mfma_f32_16x16x32_bf16 v[52:55], v[166:169], v[198:201], v[52:55]
	v_mfma_f32_16x16x32_bf16 v[40:43], v[146:149], v[206:209], v[40:43]
	v_mfma_f32_16x16x32_bf16 v[44:47], v[166:169], v[206:209], v[44:47]
	v_mfma_f32_16x16x32_bf16 v[32:35], v[146:149], v[216:219], v[32:35]
	v_mfma_f32_16x16x32_bf16 v[36:39], v[166:169], v[216:219], v[36:39]
	v_mfma_f32_16x16x32_bf16 v[64:67], v[162:165], v[194:197], v[64:67]
	v_mfma_f32_16x16x32_bf16 v[68:71], v[170:173], v[194:197], v[68:71]
	v_mfma_f32_16x16x32_bf16 v[48:51], v[162:165], v[202:205], v[48:51]
	v_mfma_f32_16x16x32_bf16 v[52:55], v[170:173], v[202:205], v[52:55]
	v_mfma_f32_16x16x32_bf16 v[40:43], v[162:165], v[212:215], v[40:43]
	v_mfma_f32_16x16x32_bf16 v[44:47], v[170:173], v[212:215], v[44:47]
	v_mfma_f32_16x16x32_bf16 v[32:35], v[162:165], v[220:223], v[32:35]
	v_mfma_f32_16x16x32_bf16 v[36:39], v[170:173], v[220:223], v[36:39]
	s_setprio 0
	s_setprio 1
	v_mfma_f32_16x16x32_bf16 v[120:123], v[174:177], v[190:193], v[120:123]
	v_mfma_f32_16x16x32_bf16 v[124:127], v[182:185], v[190:193], v[124:127]
	v_mfma_f32_16x16x32_bf16 v[112:115], v[174:177], v[198:201], v[112:115]
	v_mfma_f32_16x16x32_bf16 v[116:119], v[182:185], v[198:201], v[116:119]
	v_mfma_f32_16x16x32_bf16 v[104:107], v[174:177], v[206:209], v[104:107]
	v_mfma_f32_16x16x32_bf16 v[108:111], v[182:185], v[206:209], v[108:111]
	v_mfma_f32_16x16x32_bf16 v[96:99], v[174:177], v[216:219], v[96:99]
	v_mfma_f32_16x16x32_bf16 v[100:103], v[182:185], v[216:219], v[100:103]
	v_mfma_f32_16x16x32_bf16 v[120:123], v[178:181], v[194:197], v[120:123]
	v_mfma_f32_16x16x32_bf16 v[124:127], v[186:189], v[194:197], v[124:127]
	v_mfma_f32_16x16x32_bf16 v[112:115], v[178:181], v[202:205], v[112:115]
	v_mfma_f32_16x16x32_bf16 v[116:119], v[186:189], v[202:205], v[116:119]
	v_mfma_f32_16x16x32_bf16 v[104:107], v[178:181], v[212:215], v[104:107]
	v_mfma_f32_16x16x32_bf16 v[108:111], v[186:189], v[212:215], v[108:111]
	v_mfma_f32_16x16x32_bf16 v[96:99], v[178:181], v[220:223], v[96:99]
	v_mfma_f32_16x16x32_bf16 v[100:103], v[186:189], v[220:223], v[100:103]
	s_setprio 0
	s_barrier
	s_add_i32 s74, s84, s7
	v_lshl_add_u64 v[210:211], v[210:211], 0, s[12:13]
	s_mov_b32 m0, s74
	ds_read_b128 v[190:193], v161 offset:49152
	ds_read_b128 v[194:197], v161 offset:50176
	ds_read_b128 v[198:201], v161 offset:51200
	ds_read_b128 v[202:205], v161 offset:52224
	ds_read_b128 v[206:209], v161 offset:53248
	ds_read_b128 v[212:215], v161 offset:54272
	ds_read_b128 v[216:219], v161 offset:55296
	ds_read_b128 v[220:223], v161 offset:56320
	global_load_lds_dwordx4 v[210:211], off
	s_add_i32 m0, s74, 0x2000
	s_add_u32 s40, s40, 0x40080
	v_lshl_add_u64 v[210:211], v[224:225], 0, s[12:13]
	s_addc_u32 s41, s41, 0
	s_add_i32 s74, s85, s7
	global_load_lds_dwordx4 v[210:211], off
	v_lshl_add_u64 v[210:211], s[40:41], 0, v[130:131]
	s_mov_b32 m0, s74
	s_nop 0
	global_load_lds_dwordx4 v[210:211], off
	v_lshl_add_u64 v[210:211], s[40:41], 0, v[134:135]
	s_add_i32 m0, s74, 0x2000
	s_nop 0
	global_load_lds_dwordx4 v[210:211], off
	v_lshl_add_u64 v[210:211], v[226:227], 0, s[12:13]
	s_mov_b32 m0, s64
	s_nop 0
	global_load_lds_dwordx4 v[210:211], off
	v_lshl_add_u64 v[210:211], v[228:229], 0, s[12:13]
	s_mov_b32 m0, s65
	s_nop 0
	global_load_lds_dwordx4 v[210:211], off
	s_waitcnt vmcnt(8)
	s_waitcnt lgkmcnt(0)
	s_barrier
	s_setprio 1
	s_waitcnt lgkmcnt(0)
	v_mfma_f32_16x16x32_bf16 v[24:27], v[146:149], v[190:193], v[24:27]
	v_mfma_f32_16x16x32_bf16 v[28:31], v[166:169], v[190:193], v[28:31]
	v_mfma_f32_16x16x32_bf16 v[16:19], v[146:149], v[198:201], v[16:19]
	v_mfma_f32_16x16x32_bf16 v[20:23], v[166:169], v[198:201], v[20:23]
	v_mfma_f32_16x16x32_bf16 v[8:11], v[146:149], v[206:209], v[8:11]
	v_mfma_f32_16x16x32_bf16 v[12:15], v[166:169], v[206:209], v[12:15]
	v_mfma_f32_16x16x32_bf16 v[0:3], v[146:149], v[216:219], v[0:3]
	v_mfma_f32_16x16x32_bf16 v[4:7], v[166:169], v[216:219], v[4:7]
	v_mfma_f32_16x16x32_bf16 v[24:27], v[162:165], v[194:197], v[24:27]
	v_mfma_f32_16x16x32_bf16 v[28:31], v[170:173], v[194:197], v[28:31]
	v_mfma_f32_16x16x32_bf16 v[16:19], v[162:165], v[202:205], v[16:19]
	v_mfma_f32_16x16x32_bf16 v[20:23], v[170:173], v[202:205], v[20:23]
	v_mfma_f32_16x16x32_bf16 v[8:11], v[162:165], v[212:215], v[8:11]
	v_mfma_f32_16x16x32_bf16 v[12:15], v[170:173], v[212:215], v[12:15]
	v_mfma_f32_16x16x32_bf16 v[0:3], v[162:165], v[220:223], v[0:3]
	v_mfma_f32_16x16x32_bf16 v[4:7], v[170:173], v[220:223], v[4:7]
	s_setprio 0
	s_setprio 1
	v_mfma_f32_16x16x32_bf16 v[80:83], v[174:177], v[190:193], v[80:83]
	v_mfma_f32_16x16x32_bf16 v[84:87], v[182:185], v[190:193], v[84:87]
	v_mfma_f32_16x16x32_bf16 v[88:91], v[174:177], v[198:201], v[88:91]
	v_mfma_f32_16x16x32_bf16 v[92:95], v[182:185], v[198:201], v[92:95]
	v_mfma_f32_16x16x32_bf16 v[72:75], v[174:177], v[206:209], v[72:75]
	v_mfma_f32_16x16x32_bf16 v[76:79], v[182:185], v[206:209], v[76:79]
	v_mfma_f32_16x16x32_bf16 v[56:59], v[174:177], v[216:219], v[56:59]
	v_mfma_f32_16x16x32_bf16 v[60:63], v[182:185], v[216:219], v[60:63]
	v_mfma_f32_16x16x32_bf16 v[80:83], v[178:181], v[194:197], v[80:83]
	v_mfma_f32_16x16x32_bf16 v[84:87], v[186:189], v[194:197], v[84:87]
	v_mfma_f32_16x16x32_bf16 v[88:91], v[178:181], v[202:205], v[88:91]
	v_mfma_f32_16x16x32_bf16 v[92:95], v[186:189], v[202:205], v[92:95]
	v_mfma_f32_16x16x32_bf16 v[72:75], v[178:181], v[212:215], v[72:75]
	v_mfma_f32_16x16x32_bf16 v[76:79], v[186:189], v[212:215], v[76:79]
	v_mfma_f32_16x16x32_bf16 v[56:59], v[178:181], v[220:223], v[56:59]
	v_mfma_f32_16x16x32_bf16 v[60:63], v[186:189], v[220:223], v[60:63]
	s_add_i32 s81, s81, 2
	s_add_u32 s46, s46, 0x100
	s_addc_u32 s47, s47, 0
	s_add_u32 s79, s79, 0x100
	s_addc_u32 s80, s80, 0
	s_cmp_gt_u32 s81, 13
	s_setprio 0
	s_barrier
	s_cbranch_scc0 .LBB0_1513
	s_and_b64 vcc, exec, s[14:15]
	s_cbranch_vccz .LBB0_1516
	s_barrier

.Lrlx15b_done:
	s_mov_b32 s99, 0
	s_waitcnt lgkmcnt(0)
	s_barrier
	s_setprio 1
	s_waitcnt lgkmcnt(0)
	v_mfma_f32_16x16x32_f16 v[80:83], v[56:59], v[164:167], v[80:83]
	v_mfma_f32_16x16x32_f16 v[60:63], v[72:75], v[164:167], v[60:63]
	v_mfma_f32_16x16x32_f16 v[44:47], v[56:59], v[188:191], v[44:47]
	v_mfma_f32_16x16x32_f16 v[36:39], v[72:75], v[188:191], v[36:39]
	v_mfma_f32_16x16x32_f16 v[28:31], v[56:59], v[204:207], v[28:31]
	v_mfma_f32_16x16x32_f16 v[20:23], v[72:75], v[204:207], v[20:23]
	v_mfma_f32_16x16x32_f16 v[12:15], v[56:59], v[216:219], v[12:15]
	v_mfma_f32_16x16x32_f16 v[4:7], v[72:75], v[216:219], v[4:7]
	v_mfma_f32_16x16x32_f16 v[80:83], v[64:67], v[184:187], v[80:83]
	v_mfma_f32_16x16x32_f16 v[60:63], v[76:79], v[184:187], v[60:63]
	v_mfma_f32_16x16x32_f16 v[44:47], v[64:67], v[200:203], v[44:47]
	v_mfma_f32_16x16x32_f16 v[36:39], v[76:79], v[200:203], v[36:39]
	v_mfma_f32_16x16x32_f16 v[28:31], v[64:67], v[212:215], v[28:31]
	v_mfma_f32_16x16x32_f16 v[20:23], v[76:79], v[212:215], v[20:23]
	v_mfma_f32_16x16x32_f16 v[12:15], v[64:67], v[220:223], v[12:15]
	v_mfma_f32_16x16x32_f16 v[4:7], v[76:79], v[220:223], v[4:7]
	s_setprio 0
	s_setprio 1
	v_mfma_f32_16x16x32_f16 v[48:51], v[156:159], v[164:167], v[48:51]
	v_mfma_f32_16x16x32_f16 v[40:43], v[100:103], v[188:191], v[40:43]
	v_mfma_f32_16x16x32_f16 v[32:35], v[156:159], v[188:191], v[32:35]
	v_mfma_f32_16x16x32_f16 v[24:27], v[100:103], v[204:207], v[24:27]
	v_mfma_f32_16x16x32_f16 v[16:19], v[156:159], v[204:207], v[16:19]
	v_mfma_f32_16x16x32_f16 v[8:11], v[100:103], v[216:219], v[8:11]
	v_mfma_f32_16x16x32_f16 v[0:3], v[156:159], v[216:219], v[0:3]
	v_mfma_f32_16x16x32_f16 v[56:59], v[100:103], v[164:167], v[68:71]
	v_mfma_f32_16x16x32_f16 v[48:51], v[160:163], v[184:187], v[48:51]
	v_mfma_f32_16x16x32_f16 v[40:43], v[136:139], v[200:203], v[40:43]
	v_mfma_f32_16x16x32_f16 v[32:35], v[160:163], v[200:203], v[32:35]
	v_mfma_f32_16x16x32_f16 v[24:27], v[136:139], v[212:215], v[24:27]
	v_mfma_f32_16x16x32_f16 v[16:19], v[160:163], v[212:215], v[16:19]
	v_mfma_f32_16x16x32_f16 v[8:11], v[136:139], v[220:223], v[8:11]
	v_mfma_f32_16x16x32_f16 v[0:3], v[160:163], v[220:223], v[0:3]
	v_mfma_f32_16x16x32_f16 v[56:59], v[136:139], v[184:187], v[56:59]
	s_setprio 0
	s_barrier
	s_add_i32 s95, 0, 0x18000
	s_add_i32 s96, 0, 0x1c000
	v_add_u32_e32 v76, s95, v196
	v_add_u32_e32 v160, s96, v196
	ds_read_b128 v[64:67], v76
	ds_read_b128 v[68:71], v76 offset:1024
	ds_read_b128 v[72:75], v76 offset:2048
	ds_read_b128 v[76:79], v76 offset:3072
	ds_read_b128 v[100:103], v160
	ds_read_b128 v[136:139], v160 offset:1024
	ds_read_b128 v[156:159], v160 offset:2048
	ds_read_b128 v[160:163], v160 offset:3072
	s_add_u32 s82, s82, 0x40000
	s_addc_u32 s83, s83, 0
	s_mov_b32 m0, s71
	v_lshl_add_u64 v[226:227], s[82:83], 0, v[174:175]
	ds_read_b128 v[164:167], v198 offset:32768
	ds_read_b128 v[184:187], v198 offset:33792
	ds_read_b128 v[188:191], v198 offset:34816
	ds_read_b128 v[200:203], v198 offset:35840
	ds_read_b128 v[204:207], v198 offset:36864
	ds_read_b128 v[212:215], v198 offset:37888
	ds_read_b128 v[216:219], v198 offset:38912
	ds_read_b128 v[220:223], v198 offset:39936
	global_load_lds_dwordx4 v[226:227], off
	v_lshl_add_u64 v[226:227], s[82:83], 0, v[170:171]
	s_mov_b32 m0, s72
	s_nop 0
	global_load_lds_dwordx4 v[226:227], off
	s_waitcnt vmcnt(8)
	s_waitcnt lgkmcnt(0)
	s_barrier
	s_setprio 1
	s_waitcnt lgkmcnt(0)
	v_mfma_f32_16x16x32_f16 v[152:155], v[64:67], v[164:167], v[152:155]
	v_mfma_f32_16x16x32_f16 v[144:147], v[72:75], v[164:167], v[144:147]
	v_mfma_f32_16x16x32_f16 v[132:135], v[64:67], v[188:191], v[132:135]
	v_mfma_f32_16x16x32_f16 v[124:127], v[72:75], v[188:191], v[124:127]
	v_mfma_f32_16x16x32_f16 v[116:119], v[64:67], v[204:207], v[116:119]
	v_mfma_f32_16x16x32_f16 v[108:111], v[72:75], v[204:207], v[108:111]
	v_mfma_f32_16x16x32_f16 v[96:99], v[64:67], v[216:219], v[96:99]
	v_mfma_f32_16x16x32_f16 v[88:91], v[72:75], v[216:219], v[88:91]
	v_mfma_f32_16x16x32_f16 v[152:155], v[68:71], v[184:187], v[152:155]
	v_mfma_f32_16x16x32_f16 v[144:147], v[76:79], v[184:187], v[144:147]
	v_mfma_f32_16x16x32_f16 v[132:135], v[68:71], v[200:203], v[132:135]
	v_mfma_f32_16x16x32_f16 v[124:127], v[76:79], v[200:203], v[124:127]
	v_mfma_f32_16x16x32_f16 v[116:119], v[68:71], v[212:215], v[116:119]
	v_mfma_f32_16x16x32_f16 v[108:111], v[76:79], v[212:215], v[108:111]
	v_mfma_f32_16x16x32_f16 v[96:99], v[68:71], v[220:223], v[96:99]
	v_mfma_f32_16x16x32_f16 v[88:91], v[76:79], v[220:223], v[88:91]
	s_setprio 0
	s_setprio 1
	v_mfma_f32_16x16x32_f16 v[148:151], v[100:103], v[164:167], v[148:151]
	v_mfma_f32_16x16x32_f16 v[140:143], v[156:159], v[164:167], v[140:143]
	v_mfma_f32_16x16x32_f16 v[128:131], v[100:103], v[188:191], v[128:131]
	v_mfma_f32_16x16x32_f16 v[120:123], v[156:159], v[188:191], v[120:123]
	v_mfma_f32_16x16x32_f16 v[112:115], v[100:103], v[204:207], v[112:115]
	v_mfma_f32_16x16x32_f16 v[104:107], v[156:159], v[204:207], v[104:107]
	v_mfma_f32_16x16x32_f16 v[92:95], v[100:103], v[216:219], v[92:95]
	v_mfma_f32_16x16x32_f16 v[84:87], v[156:159], v[216:219], v[84:87]
	v_mfma_f32_16x16x32_f16 v[148:151], v[136:139], v[184:187], v[148:151]
	v_mfma_f32_16x16x32_f16 v[140:143], v[160:163], v[184:187], v[140:143]
	v_mfma_f32_16x16x32_f16 v[128:131], v[136:139], v[200:203], v[128:131]
	v_mfma_f32_16x16x32_f16 v[120:123], v[160:163], v[200:203], v[120:123]
	v_mfma_f32_16x16x32_f16 v[112:115], v[136:139], v[212:215], v[112:115]
	v_mfma_f32_16x16x32_f16 v[104:107], v[160:163], v[212:215], v[104:107]
	v_mfma_f32_16x16x32_f16 v[92:95], v[136:139], v[220:223], v[92:95]
	v_mfma_f32_16x16x32_f16 v[84:87], v[160:163], v[220:223], v[84:87]
	s_setprio 0
	s_barrier
	s_add_i32 s82, s95, s67
	v_lshl_add_u64 v[192:193], v[192:193], 0, s[8:9]
	s_mov_b32 m0, s82
	ds_read_b128 v[164:167], v198 offset:49152
	ds_read_b128 v[184:187], v198 offset:50176
	ds_read_b128 v[188:191], v198 offset:51200
	ds_read_b128 v[200:203], v198 offset:52224
	ds_read_b128 v[204:207], v198 offset:53248
	ds_read_b128 v[212:215], v198 offset:54272
	ds_read_b128 v[216:219], v198 offset:55296
	ds_read_b128 v[220:223], v198 offset:56320
	global_load_lds_dwordx4 v[192:193], off
	s_add_i32 m0, s82, 0x2000
	s_add_u32 s74, s74, 0x40080
	v_lshl_add_u64 v[192:193], v[208:209], 0, s[8:9]
	s_addc_u32 s75, s75, 0
	s_add_i32 s82, s96, s67
	global_load_lds_dwordx4 v[192:193], off
	v_lshl_add_u64 v[192:193], s[74:75], 0, v[172:173]
	s_mov_b32 m0, s82
	s_nop 0
	global_load_lds_dwordx4 v[192:193], off
	v_lshl_add_u64 v[192:193], s[74:75], 0, v[168:169]
	s_add_i32 m0, s82, 0x2000
	s_nop 0
	global_load_lds_dwordx4 v[192:193], off
	v_lshl_add_u64 v[192:193], v[210:211], 0, s[8:9]
	s_mov_b32 m0, s80
	s_nop 0
	global_load_lds_dwordx4 v[192:193], off
	v_lshl_add_u64 v[192:193], v[224:225], 0, s[8:9]
	s_mov_b32 m0, s81
	s_nop 0
	global_load_lds_dwordx4 v[192:193], off
	s_waitcnt vmcnt(8)
	s_waitcnt lgkmcnt(0)
	s_barrier
	s_setprio 1
	s_waitcnt lgkmcnt(0)
	v_mfma_f32_16x16x32_f16 v[80:83], v[64:67], v[164:167], v[80:83]
	v_mfma_f32_16x16x32_f16 v[60:63], v[72:75], v[164:167], v[60:63]
	v_mfma_f32_16x16x32_f16 v[44:47], v[64:67], v[188:191], v[44:47]
	v_mfma_f32_16x16x32_f16 v[36:39], v[72:75], v[188:191], v[36:39]
	v_mfma_f32_16x16x32_f16 v[28:31], v[64:67], v[204:207], v[28:31]
	v_mfma_f32_16x16x32_f16 v[20:23], v[72:75], v[204:207], v[20:23]
	v_mfma_f32_16x16x32_f16 v[12:15], v[64:67], v[216:219], v[12:15]
	v_mfma_f32_16x16x32_f16 v[4:7], v[72:75], v[216:219], v[4:7]
	v_mfma_f32_16x16x32_f16 v[80:83], v[68:71], v[184:187], v[80:83]
	v_mfma_f32_16x16x32_f16 v[60:63], v[76:79], v[184:187], v[60:63]
	v_mfma_f32_16x16x32_f16 v[44:47], v[68:71], v[200:203], v[44:47]
	v_mfma_f32_16x16x32_f16 v[36:39], v[76:79], v[200:203], v[36:39]
	v_mfma_f32_16x16x32_f16 v[28:31], v[68:71], v[212:215], v[28:31]
	v_mfma_f32_16x16x32_f16 v[20:23], v[76:79], v[212:215], v[20:23]
	v_mfma_f32_16x16x32_f16 v[12:15], v[68:71], v[220:223], v[12:15]
	v_mfma_f32_16x16x32_f16 v[4:7], v[76:79], v[220:223], v[4:7]
	s_setprio 0
	s_setprio 1
	v_mfma_f32_16x16x32_f16 v[56:59], v[100:103], v[164:167], v[56:59]
	v_mfma_f32_16x16x32_f16 v[48:51], v[156:159], v[164:167], v[48:51]
	v_mfma_f32_16x16x32_f16 v[40:43], v[100:103], v[188:191], v[40:43]
	v_mfma_f32_16x16x32_f16 v[32:35], v[156:159], v[188:191], v[32:35]
	v_mfma_f32_16x16x32_f16 v[24:27], v[100:103], v[204:207], v[24:27]
	v_mfma_f32_16x16x32_f16 v[16:19], v[156:159], v[204:207], v[16:19]
	v_mfma_f32_16x16x32_f16 v[8:11], v[100:103], v[216:219], v[8:11]
	v_mfma_f32_16x16x32_f16 v[0:3], v[156:159], v[216:219], v[0:3]
	v_mfma_f32_16x16x32_f16 v[68:71], v[136:139], v[184:187], v[56:59]
	v_mfma_f32_16x16x32_f16 v[48:51], v[160:163], v[184:187], v[48:51]
	v_mfma_f32_16x16x32_f16 v[40:43], v[136:139], v[200:203], v[40:43]
	v_mfma_f32_16x16x32_f16 v[32:35], v[160:163], v[200:203], v[32:35]
	v_mfma_f32_16x16x32_f16 v[24:27], v[136:139], v[212:215], v[24:27]
	v_mfma_f32_16x16x32_f16 v[16:19], v[160:163], v[212:215], v[16:19]
	v_mfma_f32_16x16x32_f16 v[8:11], v[136:139], v[220:223], v[8:11]
	v_mfma_f32_16x16x32_f16 v[0:3], v[160:163], v[220:223], v[0:3]
	s_add_i32 s94, s94, 2
	s_add_u32 s46, s46, 0x100
	s_addc_u32 s47, s47, 0
	s_add_u32 s92, s92, 0x100
	s_addc_u32 s93, s93, 0
	s_cmp_gt_u32 s94, 13
	s_setprio 0
	s_barrier
	s_cbranch_scc1 .LBB0_1609

.Lrlx18b_done:
	s_mov_b32 s99, 0
	s_waitcnt lgkmcnt(0)
	s_barrier
	s_setprio 1
	s_waitcnt lgkmcnt(0)
	v_mfma_f32_16x16x32_f16 v[96:99], v[40:43], v[144:147], v[96:99]
	v_mfma_f32_16x16x32_f16 v[92:95], v[48:51], v[144:147], v[92:95]
	v_mfma_f32_16x16x32_f16 v[80:83], v[40:43], v[172:175], v[80:83]
	v_mfma_f32_16x16x32_f16 v[76:79], v[48:51], v[172:175], v[76:79]
	v_mfma_f32_16x16x32_f16 v[28:31], v[40:43], v[202:205], v[28:31]
	v_mfma_f32_16x16x32_f16 v[24:27], v[48:51], v[202:205], v[24:27]
	v_mfma_f32_16x16x32_f16 v[12:15], v[40:43], v[212:215], v[12:15]
	v_mfma_f32_16x16x32_f16 v[8:11], v[48:51], v[212:215], v[8:11]
	v_mfma_f32_16x16x32_f16 v[96:99], v[44:47], v[156:159], v[96:99]
	v_mfma_f32_16x16x32_f16 v[92:95], v[56:59], v[156:159], v[92:95]
	v_mfma_f32_16x16x32_f16 v[80:83], v[44:47], v[198:201], v[80:83]
	v_mfma_f32_16x16x32_f16 v[76:79], v[56:59], v[198:201], v[76:79]
	v_mfma_f32_16x16x32_f16 v[28:31], v[44:47], v[206:209], v[28:31]
	v_mfma_f32_16x16x32_f16 v[24:27], v[56:59], v[206:209], v[24:27]
	v_mfma_f32_16x16x32_f16 v[12:15], v[44:47], v[216:219], v[12:15]
	v_mfma_f32_16x16x32_f16 v[8:11], v[56:59], v[216:219], v[8:11]
	s_setprio 0
	s_setprio 1
	v_mfma_f32_16x16x32_f16 v[36:39], v[68:71], v[172:175], v[36:39]
	v_mfma_f32_16x16x32_f16 v[20:23], v[60:63], v[202:205], v[20:23]
	v_mfma_f32_16x16x32_f16 v[16:19], v[68:71], v[202:205], v[16:19]
	v_mfma_f32_16x16x32_f16 v[4:7], v[60:63], v[212:215], v[4:7]
	v_mfma_f32_16x16x32_f16 v[0:3], v[68:71], v[212:215], v[0:3]
	v_mfma_f32_16x16x32_f16 v[40:43], v[60:63], v[144:147], v[88:91]
	v_mfma_f32_16x16x32_f16 v[44:47], v[68:71], v[144:147], v[84:87]
	v_mfma_f32_16x16x32_f16 v[48:51], v[60:63], v[172:175], v[52:55]
	v_mfma_f32_16x16x32_f16 v[36:39], v[72:75], v[198:201], v[36:39]
	v_mfma_f32_16x16x32_f16 v[20:23], v[64:67], v[206:209], v[20:23]
	v_mfma_f32_16x16x32_f16 v[16:19], v[72:75], v[206:209], v[16:19]
	v_mfma_f32_16x16x32_f16 v[4:7], v[64:67], v[216:219], v[4:7]
	v_mfma_f32_16x16x32_f16 v[0:3], v[72:75], v[216:219], v[0:3]
	v_mfma_f32_16x16x32_f16 v[40:43], v[64:67], v[156:159], v[40:43]
	v_mfma_f32_16x16x32_f16 v[44:47], v[72:75], v[156:159], v[44:47]
	v_mfma_f32_16x16x32_f16 v[48:51], v[64:67], v[198:201], v[48:51]
	s_setprio 0
	s_barrier
	s_add_i32 s92, 0, 0x18000
	s_add_i32 s93, 0, 0x1c000
	v_add_u32_e32 v64, s92, v194
	v_add_u32_e32 v84, s93, v194
	ds_read_b128 v[52:55], v64
	ds_read_b128 v[56:59], v64 offset:1024
	ds_read_b128 v[60:63], v64 offset:2048
	ds_read_b128 v[64:67], v64 offset:3072
	ds_read_b128 v[68:71], v84
	ds_read_b128 v[72:75], v84 offset:1024
	ds_read_b128 v[172:175], v84 offset:2048
	ds_read_b128 v[198:201], v84 offset:3072
	s_add_u32 s86, vcc_lo, 0x40000
	s_addc_u32 s87, vcc_hi, 0
	s_mov_b32 m0, s64
	v_lshl_add_u64 v[144:145], s[86:87], 0, v[176:177]
	ds_read_b128 v[84:87], v196 offset:32768
	ds_read_b128 v[88:91], v196 offset:33792
	ds_read_b128 v[202:205], v196 offset:34816
	ds_read_b128 v[206:209], v196 offset:35840
	ds_read_b128 v[212:215], v196 offset:36864
	ds_read_b128 v[216:219], v196 offset:37888
	ds_read_b128 v[220:223], v196 offset:38912
	ds_read_b128 v[224:227], v196 offset:39936
	global_load_lds_dwordx4 v[144:145], off
	v_lshl_add_u64 v[144:145], s[86:87], 0, v[180:181]
	s_mov_b32 m0, s65
	s_nop 0
	global_load_lds_dwordx4 v[144:145], off
	s_waitcnt vmcnt(8)
	s_waitcnt lgkmcnt(0)
	s_barrier
	s_setprio 1
	s_waitcnt lgkmcnt(0)
	v_mfma_f32_16x16x32_f16 v[144:147], v[52:55], v[84:87], v[168:171]
	v_mfma_f32_16x16x32_f16 v[168:171], v[56:59], v[88:91], v[144:147]
	v_mfma_f32_16x16x32_f16 v[144:147], v[60:63], v[84:87], v[164:167]
	v_mfma_f32_16x16x32_f16 v[164:167], v[64:67], v[88:91], v[144:147]
	v_mfma_f32_16x16x32_f16 v[144:147], v[52:55], v[202:205], v[152:155]
	v_mfma_f32_16x16x32_f16 v[152:155], v[56:59], v[206:209], v[144:147]
	v_mfma_f32_16x16x32_f16 v[144:147], v[60:63], v[202:205], v[148:151]
	v_mfma_f32_16x16x32_f16 v[132:135], v[52:55], v[212:215], v[132:135]
	v_mfma_f32_16x16x32_f16 v[128:131], v[60:63], v[212:215], v[128:131]
	v_mfma_f32_16x16x32_f16 v[116:119], v[52:55], v[220:223], v[116:119]
	v_mfma_f32_16x16x32_f16 v[112:115], v[60:63], v[220:223], v[112:115]
	v_mfma_f32_16x16x32_f16 v[148:151], v[64:67], v[206:209], v[144:147]
	v_mfma_f32_16x16x32_f16 v[132:135], v[56:59], v[216:219], v[132:135]
	v_mfma_f32_16x16x32_f16 v[128:131], v[64:67], v[216:219], v[128:131]
	v_mfma_f32_16x16x32_f16 v[116:119], v[56:59], v[224:227], v[116:119]
	v_mfma_f32_16x16x32_f16 v[112:115], v[64:67], v[224:227], v[112:115]
	s_setprio 0
	s_setprio 1
	v_mfma_f32_16x16x32_f16 v[144:147], v[68:71], v[84:87], v[160:163]
	v_mfma_f32_16x16x32_f16 v[84:87], v[172:175], v[84:87], v[100:103]
	v_mfma_f32_16x16x32_f16 v[156:159], v[198:201], v[88:91], v[84:87]
	v_mfma_f32_16x16x32_f16 v[84:87], v[68:71], v[202:205], v[136:139]
	v_mfma_f32_16x16x32_f16 v[160:163], v[72:75], v[88:91], v[144:147]
	v_mfma_f32_16x16x32_f16 v[144:147], v[72:75], v[206:209], v[84:87]
	v_mfma_f32_16x16x32_f16 v[84:87], v[172:175], v[202:205], v[140:143]
	v_mfma_f32_16x16x32_f16 v[140:143], v[198:201], v[206:209], v[84:87]
	v_mfma_f32_16x16x32_f16 v[84:87], v[68:71], v[212:215], v[124:127]
	v_mfma_f32_16x16x32_f16 v[124:127], v[72:75], v[216:219], v[84:87]
	v_mfma_f32_16x16x32_f16 v[84:87], v[172:175], v[212:215], v[120:123]
	v_mfma_f32_16x16x32_f16 v[120:123], v[198:201], v[216:219], v[84:87]
	v_mfma_f32_16x16x32_f16 v[84:87], v[68:71], v[220:223], v[108:111]
	v_mfma_f32_16x16x32_f16 v[108:111], v[72:75], v[224:227], v[84:87]
	v_mfma_f32_16x16x32_f16 v[84:87], v[172:175], v[220:223], v[104:107]
	v_mfma_f32_16x16x32_f16 v[104:107], v[198:201], v[224:227], v[84:87]
	s_setprio 0
	s_barrier
	s_add_i32 s86, s92, s90
	v_lshl_add_u64 v[88:89], v[210:211], 0, s[12:13]
	s_mov_b32 m0, s86
	s_nop 1
	ds_read_b128 v[84:87], v196 offset:49152
	ds_read_b128 v[100:103], v196 offset:50176
	ds_read_b128 v[136:139], v196 offset:51200
	ds_read_b128 v[202:205], v196 offset:52224
	ds_read_b128 v[206:209], v196 offset:53248
	ds_read_b128 v[212:215], v196 offset:54272
	ds_read_b128 v[216:219], v196 offset:55296
	ds_read_b128 v[220:223], v196 offset:56320
	global_load_lds_dwordx4 v[88:89], off
	s_add_i32 m0, s86, 0x2000
	s_add_u32 s86, s96, 0x40080
	v_lshl_add_u64 v[88:89], v[228:229], 0, s[12:13]
	s_addc_u32 s87, s97, 0
	s_add_i32 s92, s93, s90
	global_load_lds_dwordx4 v[88:89], off
	v_lshl_add_u64 v[88:89], s[86:87], 0, v[178:179]
	s_mov_b32 m0, s92
	s_nop 0
	global_load_lds_dwordx4 v[88:89], off
	v_lshl_add_u64 v[88:89], s[86:87], 0, v[182:183]
	s_add_i32 m0, s92, 0x2000
	s_nop 0
	global_load_lds_dwordx4 v[88:89], off
	v_lshl_add_u64 v[88:89], v[230:231], 0, s[12:13]
	s_mov_b32 m0, s72
	s_nop 0
	global_load_lds_dwordx4 v[88:89], off
	v_lshl_add_u64 v[88:89], v[232:233], 0, s[12:13]
	s_mov_b32 m0, s73
	s_nop 0
	global_load_lds_dwordx4 v[88:89], off
	s_waitcnt vmcnt(8)
	s_waitcnt lgkmcnt(0)
	s_barrier
	s_setprio 1
	s_waitcnt lgkmcnt(0)
	v_mfma_f32_16x16x32_f16 v[88:91], v[52:55], v[84:87], v[96:99]
	v_mfma_f32_16x16x32_f16 v[96:99], v[56:59], v[100:103], v[88:91]
	v_mfma_f32_16x16x32_f16 v[88:91], v[60:63], v[84:87], v[92:95]
	v_mfma_f32_16x16x32_f16 v[80:83], v[52:55], v[136:139], v[80:83]
	v_mfma_f32_16x16x32_f16 v[76:79], v[60:63], v[136:139], v[76:79]
	v_mfma_f32_16x16x32_f16 v[28:31], v[52:55], v[206:209], v[28:31]
	v_mfma_f32_16x16x32_f16 v[24:27], v[60:63], v[206:209], v[24:27]
	v_mfma_f32_16x16x32_f16 v[12:15], v[52:55], v[216:219], v[12:15]
	v_mfma_f32_16x16x32_f16 v[8:11], v[60:63], v[216:219], v[8:11]
	v_mfma_f32_16x16x32_f16 v[92:95], v[64:67], v[100:103], v[88:91]
	v_mfma_f32_16x16x32_f16 v[80:83], v[56:59], v[202:205], v[80:83]
	v_mfma_f32_16x16x32_f16 v[76:79], v[64:67], v[202:205], v[76:79]
	v_mfma_f32_16x16x32_f16 v[28:31], v[56:59], v[212:215], v[28:31]
	v_mfma_f32_16x16x32_f16 v[24:27], v[64:67], v[212:215], v[24:27]
	v_mfma_f32_16x16x32_f16 v[12:15], v[56:59], v[220:223], v[12:15]
	v_mfma_f32_16x16x32_f16 v[8:11], v[64:67], v[220:223], v[8:11]
	s_setprio 0
	s_setprio 1
	v_mfma_f32_16x16x32_f16 v[40:43], v[68:71], v[84:87], v[40:43]
	v_mfma_f32_16x16x32_f16 v[88:91], v[72:75], v[100:103], v[40:43]
	v_mfma_f32_16x16x32_f16 v[40:43], v[172:175], v[84:87], v[44:47]
	v_mfma_f32_16x16x32_f16 v[84:87], v[198:201], v[100:103], v[40:43]
	v_mfma_f32_16x16x32_f16 v[40:43], v[68:71], v[136:139], v[48:51]
	v_mfma_f32_16x16x32_f16 v[36:39], v[172:175], v[136:139], v[36:39]
	v_mfma_f32_16x16x32_f16 v[20:23], v[68:71], v[206:209], v[20:23]
	v_mfma_f32_16x16x32_f16 v[16:19], v[172:175], v[206:209], v[16:19]
	v_mfma_f32_16x16x32_f16 v[4:7], v[68:71], v[216:219], v[4:7]
	v_mfma_f32_16x16x32_f16 v[0:3], v[172:175], v[216:219], v[0:3]
	v_mfma_f32_16x16x32_f16 v[52:55], v[72:75], v[202:205], v[40:43]
	v_mfma_f32_16x16x32_f16 v[36:39], v[198:201], v[202:205], v[36:39]
	v_mfma_f32_16x16x32_f16 v[20:23], v[72:75], v[212:215], v[20:23]
	v_mfma_f32_16x16x32_f16 v[16:19], v[198:201], v[212:215], v[16:19]
	v_mfma_f32_16x16x32_f16 v[4:7], v[72:75], v[220:223], v[4:7]
	v_mfma_f32_16x16x32_f16 v[0:3], v[198:201], v[220:223], v[0:3]
	s_add_i32 s83, s83, 2
	s_add_u32 s46, s46, 0x100
	s_addc_u32 s47, s47, 0
	s_add_u32 s67, s67, 0x100
	s_addc_u32 s75, s75, 0
	s_cmp_gt_u32 s83, 13
	s_setprio 0
	s_barrier
	s_cbranch_scc1 .LBB0_1929

.LBB0_2374:
	v_add_u32_e32 v137, s70, v159
	ds_read_b128 v[146:149], v137
	ds_read_b128 v[162:165], v137 offset:1024
	ds_read_b128 v[166:169], v137 offset:2048
	ds_read_b128 v[170:173], v137 offset:3072
	v_add_u32_e32 v137, s71, v159
	ds_read_b128 v[174:177], v137
	ds_read_b128 v[178:181], v137 offset:1024
	ds_read_b128 v[182:185], v137 offset:2048
	ds_read_b128 v[186:189], v137 offset:3072
	s_add_u32 s40, s46, 0xfffc0080
	s_addc_u32 s41, s47, -1
	s_cmp_eq_u32 s81, 12
	s_cselect_b32 s75, s61, s41
	s_cselect_b32 s74, s73, s40
	s_cselect_b32 s41, s37, s80
	s_cselect_b32 s40, s78, s79
	v_lshl_add_u64 v[210:211], s[46:47], 0, v[138:139]
	s_add_i32 m0, s67, 0xc000
	ds_read_b128 v[190:193], v161
	ds_read_b128 v[194:197], v161 offset:1024
	ds_read_b128 v[198:201], v161 offset:2048
	ds_read_b128 v[202:205], v161 offset:3072
	ds_read_b128 v[206:209], v161 offset:4096
	ds_read_b128 v[212:215], v161 offset:5120
	ds_read_b128 v[216:219], v161 offset:6144
	ds_read_b128 v[220:223], v161 offset:7168
	global_load_lds_dwordx4 v[210:211], off
	v_lshl_add_u64 v[210:211], s[46:47], 0, v[140:141]
	s_add_i32 m0, s67, 0xe000
	s_nop 0
	global_load_lds_dwordx4 v[210:211], off
	s_waitcnt vmcnt(8)
	s_waitcnt lgkmcnt(0)
	s_barrier
	s_setprio 1
	s_waitcnt lgkmcnt(0)
	v_mfma_f32_16x16x32_bf16 v[64:67], v[146:149], v[190:193], v[64:67]
	v_mfma_f32_16x16x32_bf16 v[68:71], v[166:169], v[190:193], v[68:71]
	v_mfma_f32_16x16x32_bf16 v[48:51], v[146:149], v[198:201], v[48:51]
	v_mfma_f32_16x16x32_bf16 v[52:55], v[166:169], v[198:201], v[52:55]
	v_mfma_f32_16x16x32_bf16 v[40:43], v[146:149], v[206:209], v[40:43]
	v_mfma_f32_16x16x32_bf16 v[44:47], v[166:169], v[206:209], v[44:47]
	v_mfma_f32_16x16x32_bf16 v[32:35], v[146:149], v[216:219], v[32:35]
	v_mfma_f32_16x16x32_bf16 v[36:39], v[166:169], v[216:219], v[36:39]
	v_mfma_f32_16x16x32_bf16 v[64:67], v[162:165], v[194:197], v[64:67]
	v_mfma_f32_16x16x32_bf16 v[68:71], v[170:173], v[194:197], v[68:71]
	v_mfma_f32_16x16x32_bf16 v[48:51], v[162:165], v[202:205], v[48:51]
	v_mfma_f32_16x16x32_bf16 v[52:55], v[170:173], v[202:205], v[52:55]
	v_mfma_f32_16x16x32_bf16 v[40:43], v[162:165], v[212:215], v[40:43]
	v_mfma_f32_16x16x32_bf16 v[44:47], v[170:173], v[212:215], v[44:47]
	v_mfma_f32_16x16x32_bf16 v[32:35], v[162:165], v[220:223], v[32:35]
	v_mfma_f32_16x16x32_bf16 v[36:39], v[170:173], v[220:223], v[36:39]
	s_setprio 0
	s_setprio 1
	v_mfma_f32_16x16x32_bf16 v[120:123], v[174:177], v[190:193], v[120:123]
	v_mfma_f32_16x16x32_bf16 v[124:127], v[182:185], v[190:193], v[124:127]
	v_mfma_f32_16x16x32_bf16 v[112:115], v[174:177], v[198:201], v[112:115]
	v_mfma_f32_16x16x32_bf16 v[116:119], v[182:185], v[198:201], v[116:119]
	v_mfma_f32_16x16x32_bf16 v[104:107], v[174:177], v[206:209], v[104:107]
	v_mfma_f32_16x16x32_bf16 v[108:111], v[182:185], v[206:209], v[108:111]
	v_mfma_f32_16x16x32_bf16 v[96:99], v[174:177], v[216:219], v[96:99]
	v_mfma_f32_16x16x32_bf16 v[100:103], v[182:185], v[216:219], v[100:103]
	v_mfma_f32_16x16x32_bf16 v[120:123], v[178:181], v[194:197], v[120:123]
	v_mfma_f32_16x16x32_bf16 v[124:127], v[186:189], v[194:197], v[124:127]
	v_mfma_f32_16x16x32_bf16 v[112:115], v[178:181], v[202:205], v[112:115]
	v_mfma_f32_16x16x32_bf16 v[116:119], v[186:189], v[202:205], v[116:119]
	v_mfma_f32_16x16x32_bf16 v[104:107], v[178:181], v[212:215], v[104:107]
	v_mfma_f32_16x16x32_bf16 v[108:111], v[186:189], v[212:215], v[108:111]
	v_mfma_f32_16x16x32_bf16 v[96:99], v[178:181], v[220:223], v[96:99]
	v_mfma_f32_16x16x32_bf16 v[100:103], v[186:189], v[220:223], v[100:103]
	s_setprio 0
	s_barrier
	s_add_i32 s84, s70, s9
	v_lshl_add_u64 v[210:211], s[40:41], 0, v[130:131]
	s_mov_b32 m0, s84
	ds_read_b128 v[190:193], v161 offset:16384
	ds_read_b128 v[194:197], v161 offset:17408
	ds_read_b128 v[198:201], v161 offset:18432
	ds_read_b128 v[202:205], v161 offset:19456
	ds_read_b128 v[206:209], v161 offset:20480
	ds_read_b128 v[212:215], v161 offset:21504
	ds_read_b128 v[216:219], v161 offset:22528
	ds_read_b128 v[220:223], v161 offset:23552
	global_load_lds_dwordx4 v[210:211], off
	s_add_i32 m0, s84, 0x2000
	s_add_u32 s84, s40, 0x40000
	v_lshl_add_u64 v[224:225], s[40:41], 0, v[134:135]
	s_addc_u32 s85, s41, 0
	s_add_i32 s86, s71, s9
	global_load_lds_dwordx4 v[224:225], off
	v_lshl_add_u64 v[226:227], s[84:85], 0, v[130:131]
	s_mov_b32 m0, s86
	v_lshl_add_u64 v[228:229], s[74:75], 0, v[132:133]
	global_load_lds_dwordx4 v[226:227], off
	v_lshl_add_u64 v[226:227], s[84:85], 0, v[134:135]
	s_add_i32 m0, s86, 0x2000
	s_nop 0
	global_load_lds_dwordx4 v[226:227], off
	v_lshl_add_u64 v[226:227], s[74:75], 0, v[128:129]
	s_mov_b32 m0, s67
	s_nop 0
	global_load_lds_dwordx4 v[226:227], off
	s_mov_b32 m0, s68
	s_nop 0
	global_load_lds_dwordx4 v[228:229], off
	s_waitcnt vmcnt(8)
	s_waitcnt lgkmcnt(0)
	s_barrier
	s_setprio 1
	s_waitcnt lgkmcnt(0)
	v_mfma_f32_16x16x32_bf16 v[24:27], v[146:149], v[190:193], v[24:27]
	v_mfma_f32_16x16x32_bf16 v[28:31], v[166:169], v[190:193], v[28:31]
	v_mfma_f32_16x16x32_bf16 v[16:19], v[146:149], v[198:201], v[16:19]
	v_mfma_f32_16x16x32_bf16 v[20:23], v[166:169], v[198:201], v[20:23]
	v_mfma_f32_16x16x32_bf16 v[8:11], v[146:149], v[206:209], v[8:11]
	v_mfma_f32_16x16x32_bf16 v[12:15], v[166:169], v[206:209], v[12:15]
	v_mfma_f32_16x16x32_bf16 v[0:3], v[146:149], v[216:219], v[0:3]
	v_mfma_f32_16x16x32_bf16 v[4:7], v[166:169], v[216:219], v[4:7]
	v_mfma_f32_16x16x32_bf16 v[24:27], v[162:165], v[194:197], v[24:27]
	v_mfma_f32_16x16x32_bf16 v[28:31], v[170:173], v[194:197], v[28:31]
	v_mfma_f32_16x16x32_bf16 v[16:19], v[162:165], v[202:205], v[16:19]
	v_mfma_f32_16x16x32_bf16 v[20:23], v[170:173], v[202:205], v[20:23]
	v_mfma_f32_16x16x32_bf16 v[8:11], v[162:165], v[212:215], v[8:11]
	v_mfma_f32_16x16x32_bf16 v[12:15], v[170:173], v[212:215], v[12:15]
	v_mfma_f32_16x16x32_bf16 v[0:3], v[162:165], v[220:223], v[0:3]
	v_mfma_f32_16x16x32_bf16 v[4:7], v[170:173], v[220:223], v[4:7]
	s_setprio 0
	s_setprio 1
	v_mfma_f32_16x16x32_bf16 v[80:83], v[174:177], v[190:193], v[80:83]
	v_mfma_f32_16x16x32_bf16 v[84:87], v[182:185], v[190:193], v[84:87]
	v_mfma_f32_16x16x32_bf16 v[88:91], v[174:177], v[198:201], v[88:91]
	v_mfma_f32_16x16x32_bf16 v[92:95], v[182:185], v[198:201], v[92:95]
	v_mfma_f32_16x16x32_bf16 v[72:75], v[174:177], v[206:209], v[72:75]
	v_mfma_f32_16x16x32_bf16 v[76:79], v[182:185], v[206:209], v[76:79]
	v_mfma_f32_16x16x32_bf16 v[56:59], v[174:177], v[216:219], v[56:59]
	v_mfma_f32_16x16x32_bf16 v[60:63], v[182:185], v[216:219], v[60:63]
	v_mfma_f32_16x16x32_bf16 v[80:83], v[178:181], v[194:197], v[80:83]
	v_mfma_f32_16x16x32_bf16 v[84:87], v[186:189], v[194:197], v[84:87]
	v_mfma_f32_16x16x32_bf16 v[88:91], v[178:181], v[202:205], v[88:91]
	v_mfma_f32_16x16x32_bf16 v[92:95], v[186:189], v[202:205], v[92:95]
	v_mfma_f32_16x16x32_bf16 v[72:75], v[178:181], v[212:215], v[72:75]
	v_mfma_f32_16x16x32_bf16 v[76:79], v[186:189], v[212:215], v[76:79]
	v_mfma_f32_16x16x32_bf16 v[56:59], v[178:181], v[220:223], v[56:59]
	v_mfma_f32_16x16x32_bf16 v[60:63], v[186:189], v[220:223], v[60:63]
	s_setprio 0
	s_barrier
	s_add_i32 s84, 0, 0x18000
	v_add_u32_e32 v137, s84, v159
	s_add_i32 s85, 0, 0x1c000
	ds_read_b128 v[146:149], v137
	ds_read_b128 v[162:165], v137 offset:1024
	ds_read_b128 v[166:169], v137 offset:2048
	ds_read_b128 v[170:173], v137 offset:3072
	v_add_u32_e32 v137, s85, v159
	ds_read_b128 v[174:177], v137
	ds_read_b128 v[178:181], v137 offset:1024
	ds_read_b128 v[182:185], v137 offset:2048
	ds_read_b128 v[186:189], v137 offset:3072
	s_add_u32 s74, s74, 0x40000
	s_addc_u32 s75, s75, 0
	s_mov_b32 m0, s69
	v_lshl_add_u64 v[230:231], s[74:75], 0, v[128:129]
	ds_read_b128 v[190:193], v161 offset:32768
	ds_read_b128 v[194:197], v161 offset:33792
	ds_read_b128 v[198:201], v161 offset:34816
	ds_read_b128 v[202:205], v161 offset:35840
	ds_read_b128 v[206:209], v161 offset:36864
	ds_read_b128 v[212:215], v161 offset:37888
	ds_read_b128 v[216:219], v161 offset:38912
	ds_read_b128 v[220:223], v161 offset:39936
	global_load_lds_dwordx4 v[230:231], off
	v_lshl_add_u64 v[230:231], s[74:75], 0, v[132:133]
	s_mov_b32 m0, s90
	s_nop 0
	global_load_lds_dwordx4 v[230:231], off
	s_waitcnt vmcnt(8)
	s_waitcnt lgkmcnt(0)
	s_barrier
	s_setprio 1
	s_waitcnt lgkmcnt(0)
	v_mfma_f32_16x16x32_bf16 v[64:67], v[146:149], v[190:193], v[64:67]
	v_mfma_f32_16x16x32_bf16 v[68:71], v[166:169], v[190:193], v[68:71]
	v_mfma_f32_16x16x32_bf16 v[48:51], v[146:149], v[198:201], v[48:51]
	v_mfma_f32_16x16x32_bf16 v[52:55], v[166:169], v[198:201], v[52:55]
	v_mfma_f32_16x16x32_bf16 v[40:43], v[146:149], v[206:209], v[40:43]
	v_mfma_f32_16x16x32_bf16 v[44:47], v[166:169], v[206:209], v[44:47]
	v_mfma_f32_16x16x32_bf16 v[32:35], v[146:149], v[216:219], v[32:35]
	v_mfma_f32_16x16x32_bf16 v[36:39], v[166:169], v[216:219], v[36:39]
	v_mfma_f32_16x16x32_bf16 v[64:67], v[162:165], v[194:197], v[64:67]
	v_mfma_f32_16x16x32_bf16 v[68:71], v[170:173], v[194:197], v[68:71]
	v_mfma_f32_16x16x32_bf16 v[48:51], v[162:165], v[202:205], v[48:51]
	v_mfma_f32_16x16x32_bf16 v[52:55], v[170:173], v[202:205], v[52:55]
	v_mfma_f32_16x16x32_bf16 v[40:43], v[162:165], v[212:215], v[40:43]
	v_mfma_f32_16x16x32_bf16 v[44:47], v[170:173], v[212:215], v[44:47]
	v_mfma_f32_16x16x32_bf16 v[32:35], v[162:165], v[220:223], v[32:35]
	v_mfma_f32_16x16x32_bf16 v[36:39], v[170:173], v[220:223], v[36:39]
	s_setprio 0
	s_setprio 1
	v_mfma_f32_16x16x32_bf16 v[120:123], v[174:177], v[190:193], v[120:123]
	v_mfma_f32_16x16x32_bf16 v[124:127], v[182:185], v[190:193], v[124:127]
	v_mfma_f32_16x16x32_bf16 v[112:115], v[174:177], v[198:201], v[112:115]
	v_mfma_f32_16x16x32_bf16 v[116:119], v[182:185], v[198:201], v[116:119]
	v_mfma_f32_16x16x32_bf16 v[104:107], v[174:177], v[206:209], v[104:107]
	v_mfma_f32_16x16x32_bf16 v[108:111], v[182:185], v[206:209], v[108:111]
	v_mfma_f32_16x16x32_bf16 v[96:99], v[174:177], v[216:219], v[96:99]
	v_mfma_f32_16x16x32_bf16 v[100:103], v[182:185], v[216:219], v[100:103]
	v_mfma_f32_16x16x32_bf16 v[120:123], v[178:181], v[194:197], v[120:123]
	v_mfma_f32_16x16x32_bf16 v[124:127], v[186:189], v[194:197], v[124:127]
	v_mfma_f32_16x16x32_bf16 v[112:115], v[178:181], v[202:205], v[112:115]
	v_mfma_f32_16x16x32_bf16 v[116:119], v[186:189], v[202:205], v[116:119]
	v_mfma_f32_16x16x32_bf16 v[104:107], v[178:181], v[212:215], v[104:107]
	v_mfma_f32_16x16x32_bf16 v[108:111], v[186:189], v[212:215], v[108:111]
	v_mfma_f32_16x16x32_bf16 v[96:99], v[178:181], v[220:223], v[96:99]
	v_mfma_f32_16x16x32_bf16 v[100:103], v[186:189], v[220:223], v[100:103]
	s_setprio 0
	s_barrier
	s_add_i32 s74, s84, s9
	v_lshl_add_u64 v[210:211], v[210:211], 0, s[14:15]
	s_mov_b32 m0, s74
	ds_read_b128 v[190:193], v161 offset:49152
	ds_read_b128 v[194:197], v161 offset:50176
	ds_read_b128 v[198:201], v161 offset:51200
	ds_read_b128 v[202:205], v161 offset:52224
	ds_read_b128 v[206:209], v161 offset:53248
	ds_read_b128 v[212:215], v161 offset:54272
	ds_read_b128 v[216:219], v161 offset:55296
	ds_read_b128 v[220:223], v161 offset:56320
	global_load_lds_dwordx4 v[210:211], off
	s_add_i32 m0, s74, 0x2000
	s_add_u32 s40, s40, 0x40080
	v_lshl_add_u64 v[210:211], v[224:225], 0, s[14:15]
	s_addc_u32 s41, s41, 0
	s_add_i32 s74, s85, s9
	global_load_lds_dwordx4 v[210:211], off
	v_lshl_add_u64 v[210:211], s[40:41], 0, v[130:131]
	s_mov_b32 m0, s74
	s_nop 0
	global_load_lds_dwordx4 v[210:211], off
	v_lshl_add_u64 v[210:211], s[40:41], 0, v[134:135]
	s_add_i32 m0, s74, 0x2000
	s_nop 0
	global_load_lds_dwordx4 v[210:211], off
	v_lshl_add_u64 v[210:211], v[226:227], 0, s[14:15]
	s_mov_b32 m0, s64
	s_nop 0
	global_load_lds_dwordx4 v[210:211], off
	v_lshl_add_u64 v[210:211], v[228:229], 0, s[14:15]
	s_mov_b32 m0, s65
	s_nop 0
	global_load_lds_dwordx4 v[210:211], off
	s_waitcnt vmcnt(8)
	s_waitcnt lgkmcnt(0)
	s_barrier
	s_setprio 1
	s_waitcnt lgkmcnt(0)
	v_mfma_f32_16x16x32_bf16 v[24:27], v[146:149], v[190:193], v[24:27]
	v_mfma_f32_16x16x32_bf16 v[28:31], v[166:169], v[190:193], v[28:31]
	v_mfma_f32_16x16x32_bf16 v[16:19], v[146:149], v[198:201], v[16:19]
	v_mfma_f32_16x16x32_bf16 v[20:23], v[166:169], v[198:201], v[20:23]
	v_mfma_f32_16x16x32_bf16 v[8:11], v[146:149], v[206:209], v[8:11]
	v_mfma_f32_16x16x32_bf16 v[12:15], v[166:169], v[206:209], v[12:15]
	v_mfma_f32_16x16x32_bf16 v[0:3], v[146:149], v[216:219], v[0:3]
	v_mfma_f32_16x16x32_bf16 v[4:7], v[166:169], v[216:219], v[4:7]
	v_mfma_f32_16x16x32_bf16 v[24:27], v[162:165], v[194:197], v[24:27]
	v_mfma_f32_16x16x32_bf16 v[28:31], v[170:173], v[194:197], v[28:31]
	v_mfma_f32_16x16x32_bf16 v[16:19], v[162:165], v[202:205], v[16:19]
	v_mfma_f32_16x16x32_bf16 v[20:23], v[170:173], v[202:205], v[20:23]
	v_mfma_f32_16x16x32_bf16 v[8:11], v[162:165], v[212:215], v[8:11]
	v_mfma_f32_16x16x32_bf16 v[12:15], v[170:173], v[212:215], v[12:15]
	v_mfma_f32_16x16x32_bf16 v[0:3], v[162:165], v[220:223], v[0:3]
	v_mfma_f32_16x16x32_bf16 v[4:7], v[170:173], v[220:223], v[4:7]
	s_setprio 0
	s_setprio 1
	v_mfma_f32_16x16x32_bf16 v[80:83], v[174:177], v[190:193], v[80:83]
	v_mfma_f32_16x16x32_bf16 v[84:87], v[182:185], v[190:193], v[84:87]
	v_mfma_f32_16x16x32_bf16 v[88:91], v[174:177], v[198:201], v[88:91]
	v_mfma_f32_16x16x32_bf16 v[92:95], v[182:185], v[198:201], v[92:95]
	v_mfma_f32_16x16x32_bf16 v[72:75], v[174:177], v[206:209], v[72:75]
	v_mfma_f32_16x16x32_bf16 v[76:79], v[182:185], v[206:209], v[76:79]
	v_mfma_f32_16x16x32_bf16 v[56:59], v[174:177], v[216:219], v[56:59]
	v_mfma_f32_16x16x32_bf16 v[60:63], v[182:185], v[216:219], v[60:63]
	v_mfma_f32_16x16x32_bf16 v[80:83], v[178:181], v[194:197], v[80:83]
	v_mfma_f32_16x16x32_bf16 v[84:87], v[186:189], v[194:197], v[84:87]
	v_mfma_f32_16x16x32_bf16 v[88:91], v[178:181], v[202:205], v[88:91]
	v_mfma_f32_16x16x32_bf16 v[92:95], v[186:189], v[202:205], v[92:95]
	v_mfma_f32_16x16x32_bf16 v[72:75], v[178:181], v[212:215], v[72:75]
	v_mfma_f32_16x16x32_bf16 v[76:79], v[186:189], v[212:215], v[76:79]
	v_mfma_f32_16x16x32_bf16 v[56:59], v[178:181], v[220:223], v[56:59]
	v_mfma_f32_16x16x32_bf16 v[60:63], v[186:189], v[220:223], v[60:63]
	s_add_i32 s81, s81, 2
	s_add_u32 s46, s46, 0x100
	s_addc_u32 s47, s47, 0
	s_add_u32 s79, s79, 0x100
	s_addc_u32 s80, s80, 0
	s_cmp_gt_u32 s81, 13
	s_setprio 0
	s_barrier
	s_cbranch_scc0 .LBB0_2374
	s_and_b64 vcc, exec, s[34:35]
	s_cbranch_vccz .LBB0_2377
	s_barrier

.Lrlx26b_done:
	s_mov_b32 s99, 0
	s_waitcnt lgkmcnt(0)
	s_barrier
	s_setprio 1
	s_waitcnt lgkmcnt(0)
	v_mfma_f32_16x16x32_f16 v[96:99], v[40:43], v[144:147], v[96:99]
	v_mfma_f32_16x16x32_f16 v[92:95], v[48:51], v[144:147], v[92:95]
	v_mfma_f32_16x16x32_f16 v[80:83], v[40:43], v[172:175], v[80:83]
	v_mfma_f32_16x16x32_f16 v[76:79], v[48:51], v[172:175], v[76:79]
	v_mfma_f32_16x16x32_f16 v[28:31], v[40:43], v[202:205], v[28:31]
	v_mfma_f32_16x16x32_f16 v[24:27], v[48:51], v[202:205], v[24:27]
	v_mfma_f32_16x16x32_f16 v[12:15], v[40:43], v[212:215], v[12:15]
	v_mfma_f32_16x16x32_f16 v[8:11], v[48:51], v[212:215], v[8:11]
	v_mfma_f32_16x16x32_f16 v[96:99], v[44:47], v[156:159], v[96:99]
	v_mfma_f32_16x16x32_f16 v[92:95], v[56:59], v[156:159], v[92:95]
	v_mfma_f32_16x16x32_f16 v[80:83], v[44:47], v[198:201], v[80:83]
	v_mfma_f32_16x16x32_f16 v[76:79], v[56:59], v[198:201], v[76:79]
	v_mfma_f32_16x16x32_f16 v[28:31], v[44:47], v[206:209], v[28:31]
	v_mfma_f32_16x16x32_f16 v[24:27], v[56:59], v[206:209], v[24:27]
	v_mfma_f32_16x16x32_f16 v[12:15], v[44:47], v[216:219], v[12:15]
	v_mfma_f32_16x16x32_f16 v[8:11], v[56:59], v[216:219], v[8:11]
	s_setprio 0
	s_setprio 1
	v_mfma_f32_16x16x32_f16 v[36:39], v[68:71], v[172:175], v[36:39]
	v_mfma_f32_16x16x32_f16 v[20:23], v[60:63], v[202:205], v[20:23]
	v_mfma_f32_16x16x32_f16 v[16:19], v[68:71], v[202:205], v[16:19]
	v_mfma_f32_16x16x32_f16 v[4:7], v[60:63], v[212:215], v[4:7]
	v_mfma_f32_16x16x32_f16 v[0:3], v[68:71], v[212:215], v[0:3]
	v_mfma_f32_16x16x32_f16 v[40:43], v[60:63], v[144:147], v[88:91]
	v_mfma_f32_16x16x32_f16 v[44:47], v[68:71], v[144:147], v[84:87]
	v_mfma_f32_16x16x32_f16 v[48:51], v[60:63], v[172:175], v[52:55]
	v_mfma_f32_16x16x32_f16 v[36:39], v[72:75], v[198:201], v[36:39]
	v_mfma_f32_16x16x32_f16 v[20:23], v[64:67], v[206:209], v[20:23]
	v_mfma_f32_16x16x32_f16 v[16:19], v[72:75], v[206:209], v[16:19]
	v_mfma_f32_16x16x32_f16 v[4:7], v[64:67], v[216:219], v[4:7]
	v_mfma_f32_16x16x32_f16 v[0:3], v[72:75], v[216:219], v[0:3]
	v_mfma_f32_16x16x32_f16 v[40:43], v[64:67], v[156:159], v[40:43]
	v_mfma_f32_16x16x32_f16 v[44:47], v[72:75], v[156:159], v[44:47]
	v_mfma_f32_16x16x32_f16 v[48:51], v[64:67], v[198:201], v[48:51]
	s_setprio 0
	s_barrier
	s_add_i32 s82, 0, 0x18000
	s_add_i32 s83, 0, 0x1c000
	v_add_u32_e32 v64, s82, v194
	v_add_u32_e32 v84, s83, v194
	ds_read_b128 v[52:55], v64
	ds_read_b128 v[56:59], v64 offset:1024
	ds_read_b128 v[60:63], v64 offset:2048
	ds_read_b128 v[64:67], v64 offset:3072
	ds_read_b128 v[68:71], v84
	ds_read_b128 v[72:75], v84 offset:1024
	ds_read_b128 v[172:175], v84 offset:2048
	ds_read_b128 v[198:201], v84 offset:3072
	s_add_u32 s54, s54, 0x40000
	s_addc_u32 s55, s55, 0
	s_mov_b32 m0, s64
	v_lshl_add_u64 v[144:145], s[54:55], 0, v[176:177]
	ds_read_b128 v[84:87], v196 offset:32768
	ds_read_b128 v[88:91], v196 offset:33792
	ds_read_b128 v[202:205], v196 offset:34816
	ds_read_b128 v[206:209], v196 offset:35840
	ds_read_b128 v[212:215], v196 offset:36864
	ds_read_b128 v[216:219], v196 offset:37888
	ds_read_b128 v[220:223], v196 offset:38912
	ds_read_b128 v[224:227], v196 offset:39936
	global_load_lds_dwordx4 v[144:145], off
	v_lshl_add_u64 v[144:145], s[54:55], 0, v[180:181]
	s_mov_b32 m0, s65
	s_nop 0
	global_load_lds_dwordx4 v[144:145], off
	s_waitcnt vmcnt(8)
	s_waitcnt lgkmcnt(0)
	s_barrier
	s_setprio 1
	s_waitcnt lgkmcnt(0)
	v_mfma_f32_16x16x32_f16 v[144:147], v[52:55], v[84:87], v[168:171]
	v_mfma_f32_16x16x32_f16 v[168:171], v[56:59], v[88:91], v[144:147]
	v_mfma_f32_16x16x32_f16 v[144:147], v[60:63], v[84:87], v[164:167]
	v_mfma_f32_16x16x32_f16 v[164:167], v[64:67], v[88:91], v[144:147]
	v_mfma_f32_16x16x32_f16 v[144:147], v[52:55], v[202:205], v[152:155]
	v_mfma_f32_16x16x32_f16 v[152:155], v[56:59], v[206:209], v[144:147]
	v_mfma_f32_16x16x32_f16 v[144:147], v[60:63], v[202:205], v[148:151]
	v_mfma_f32_16x16x32_f16 v[132:135], v[52:55], v[212:215], v[132:135]
	v_mfma_f32_16x16x32_f16 v[128:131], v[60:63], v[212:215], v[128:131]
	v_mfma_f32_16x16x32_f16 v[116:119], v[52:55], v[220:223], v[116:119]
	v_mfma_f32_16x16x32_f16 v[112:115], v[60:63], v[220:223], v[112:115]
	v_mfma_f32_16x16x32_f16 v[148:151], v[64:67], v[206:209], v[144:147]
	v_mfma_f32_16x16x32_f16 v[132:135], v[56:59], v[216:219], v[132:135]
	v_mfma_f32_16x16x32_f16 v[128:131], v[64:67], v[216:219], v[128:131]
	v_mfma_f32_16x16x32_f16 v[116:119], v[56:59], v[224:227], v[116:119]
	v_mfma_f32_16x16x32_f16 v[112:115], v[64:67], v[224:227], v[112:115]
	s_setprio 0
	s_setprio 1
	v_mfma_f32_16x16x32_f16 v[144:147], v[68:71], v[84:87], v[160:163]
	v_mfma_f32_16x16x32_f16 v[84:87], v[172:175], v[84:87], v[100:103]
	v_mfma_f32_16x16x32_f16 v[156:159], v[198:201], v[88:91], v[84:87]
	v_mfma_f32_16x16x32_f16 v[84:87], v[68:71], v[202:205], v[136:139]
	v_mfma_f32_16x16x32_f16 v[160:163], v[72:75], v[88:91], v[144:147]
	v_mfma_f32_16x16x32_f16 v[144:147], v[72:75], v[206:209], v[84:87]
	v_mfma_f32_16x16x32_f16 v[84:87], v[172:175], v[202:205], v[140:143]
	v_mfma_f32_16x16x32_f16 v[140:143], v[198:201], v[206:209], v[84:87]
	v_mfma_f32_16x16x32_f16 v[84:87], v[68:71], v[212:215], v[124:127]
	v_mfma_f32_16x16x32_f16 v[124:127], v[72:75], v[216:219], v[84:87]
	v_mfma_f32_16x16x32_f16 v[84:87], v[172:175], v[212:215], v[120:123]
	v_mfma_f32_16x16x32_f16 v[120:123], v[198:201], v[216:219], v[84:87]
	v_mfma_f32_16x16x32_f16 v[84:87], v[68:71], v[220:223], v[108:111]
	v_mfma_f32_16x16x32_f16 v[108:111], v[72:75], v[224:227], v[84:87]
	v_mfma_f32_16x16x32_f16 v[84:87], v[172:175], v[220:223], v[104:107]
	v_mfma_f32_16x16x32_f16 v[104:107], v[198:201], v[224:227], v[84:87]
	s_setprio 0
	s_barrier
	s_add_i32 s54, s82, s66
	v_lshl_add_u64 v[88:89], v[210:211], 0, s[12:13]
	s_mov_b32 m0, s54
	s_nop 1
	ds_read_b128 v[84:87], v196 offset:49152
	ds_read_b128 v[100:103], v196 offset:50176
	ds_read_b128 v[136:139], v196 offset:51200
	ds_read_b128 v[202:205], v196 offset:52224
	ds_read_b128 v[206:209], v196 offset:53248
	ds_read_b128 v[212:215], v196 offset:54272
	ds_read_b128 v[216:219], v196 offset:55296
	ds_read_b128 v[220:223], v196 offset:56320
	global_load_lds_dwordx4 v[88:89], off
	s_add_i32 m0, s54, 0x2000
	s_add_u32 s52, s52, 0x40080
	v_lshl_add_u64 v[88:89], v[228:229], 0, s[12:13]
	s_addc_u32 s53, s53, 0
	s_add_i32 s54, s83, s66
	global_load_lds_dwordx4 v[88:89], off
	v_lshl_add_u64 v[88:89], s[52:53], 0, v[178:179]
	s_mov_b32 m0, s54
	s_nop 0
	global_load_lds_dwordx4 v[88:89], off
	v_lshl_add_u64 v[88:89], s[52:53], 0, v[182:183]
	s_add_i32 m0, s54, 0x2000
	s_nop 0
	global_load_lds_dwordx4 v[88:89], off
	v_lshl_add_u64 v[88:89], v[230:231], 0, s[12:13]
	s_mov_b32 m0, s70
	s_nop 0
	global_load_lds_dwordx4 v[88:89], off
	v_lshl_add_u64 v[88:89], v[232:233], 0, s[12:13]
	s_mov_b32 m0, s71
	s_nop 0
	global_load_lds_dwordx4 v[88:89], off
	s_waitcnt vmcnt(8)
	s_waitcnt lgkmcnt(0)
	s_barrier
	s_setprio 1
	s_waitcnt lgkmcnt(0)
	v_mfma_f32_16x16x32_f16 v[88:91], v[52:55], v[84:87], v[96:99]
	v_mfma_f32_16x16x32_f16 v[96:99], v[56:59], v[100:103], v[88:91]
	v_mfma_f32_16x16x32_f16 v[88:91], v[60:63], v[84:87], v[92:95]
	v_mfma_f32_16x16x32_f16 v[80:83], v[52:55], v[136:139], v[80:83]
	v_mfma_f32_16x16x32_f16 v[76:79], v[60:63], v[136:139], v[76:79]
	v_mfma_f32_16x16x32_f16 v[28:31], v[52:55], v[206:209], v[28:31]
	v_mfma_f32_16x16x32_f16 v[24:27], v[60:63], v[206:209], v[24:27]
	v_mfma_f32_16x16x32_f16 v[12:15], v[52:55], v[216:219], v[12:15]
	v_mfma_f32_16x16x32_f16 v[8:11], v[60:63], v[216:219], v[8:11]
	v_mfma_f32_16x16x32_f16 v[92:95], v[64:67], v[100:103], v[88:91]
	v_mfma_f32_16x16x32_f16 v[80:83], v[56:59], v[202:205], v[80:83]
	v_mfma_f32_16x16x32_f16 v[76:79], v[64:67], v[202:205], v[76:79]
	v_mfma_f32_16x16x32_f16 v[28:31], v[56:59], v[212:215], v[28:31]
	v_mfma_f32_16x16x32_f16 v[24:27], v[64:67], v[212:215], v[24:27]
	v_mfma_f32_16x16x32_f16 v[12:15], v[56:59], v[220:223], v[12:15]
	v_mfma_f32_16x16x32_f16 v[8:11], v[64:67], v[220:223], v[8:11]
	s_setprio 0
	s_setprio 1
	v_mfma_f32_16x16x32_f16 v[40:43], v[68:71], v[84:87], v[40:43]
	v_mfma_f32_16x16x32_f16 v[88:91], v[72:75], v[100:103], v[40:43]
	v_mfma_f32_16x16x32_f16 v[40:43], v[172:175], v[84:87], v[44:47]
	v_mfma_f32_16x16x32_f16 v[84:87], v[198:201], v[100:103], v[40:43]
	v_mfma_f32_16x16x32_f16 v[40:43], v[68:71], v[136:139], v[48:51]
	v_mfma_f32_16x16x32_f16 v[36:39], v[172:175], v[136:139], v[36:39]
	v_mfma_f32_16x16x32_f16 v[20:23], v[68:71], v[206:209], v[20:23]
	v_mfma_f32_16x16x32_f16 v[16:19], v[172:175], v[206:209], v[16:19]
	v_mfma_f32_16x16x32_f16 v[4:7], v[68:71], v[216:219], v[4:7]
	v_mfma_f32_16x16x32_f16 v[0:3], v[172:175], v[216:219], v[0:3]
	v_mfma_f32_16x16x32_f16 v[52:55], v[72:75], v[202:205], v[40:43]
	v_mfma_f32_16x16x32_f16 v[36:39], v[198:201], v[202:205], v[36:39]
	v_mfma_f32_16x16x32_f16 v[20:23], v[72:75], v[212:215], v[20:23]
	v_mfma_f32_16x16x32_f16 v[16:19], v[198:201], v[212:215], v[16:19]
	v_mfma_f32_16x16x32_f16 v[4:7], v[72:75], v[220:223], v[4:7]
	v_mfma_f32_16x16x32_f16 v[0:3], v[198:201], v[220:223], v[0:3]
	s_add_i32 s81, s81, 2
	s_add_u32 s46, s46, 0x100
	s_addc_u32 s47, s47, 0
	s_add_u32 s49, s49, 0x100
	s_addc_u32 s80, s80, 0
	s_cmp_gt_u32 s81, 13
	s_setprio 0
	s_barrier
	s_cbranch_scc1 .LBB0_2793

.Lrlx29p0b_done:
	s_mov_b32 s99, 0
	s_waitcnt lgkmcnt(0)
	s_barrier
	s_setprio 1
	s_waitcnt lgkmcnt(0)
	v_mfma_f32_16x16x32_bf16 v[60:63], v[144:147], v[184:187], v[60:63]
	v_mfma_f32_16x16x32_bf16 v[56:59], v[160:163], v[184:187], v[56:59]
	v_mfma_f32_16x16x32_bf16 v[48:51], v[144:147], v[192:195], v[48:51]
	v_mfma_f32_16x16x32_bf16 v[40:43], v[160:163], v[192:195], v[40:43]
	v_mfma_f32_16x16x32_bf16 v[32:35], v[144:147], v[200:203], v[32:35]
	v_mfma_f32_16x16x32_bf16 v[24:27], v[160:163], v[200:203], v[24:27]
	v_mfma_f32_16x16x32_bf16 v[16:19], v[144:147], v[212:215], v[16:19]
	v_mfma_f32_16x16x32_bf16 v[8:11], v[160:163], v[212:215], v[8:11]
	v_mfma_f32_16x16x32_bf16 v[60:63], v[156:159], v[188:191], v[60:63]
	v_mfma_f32_16x16x32_bf16 v[56:59], v[164:167], v[188:191], v[56:59]
	v_mfma_f32_16x16x32_bf16 v[48:51], v[156:159], v[196:199], v[48:51]
	v_mfma_f32_16x16x32_bf16 v[40:43], v[164:167], v[196:199], v[40:43]
	v_mfma_f32_16x16x32_bf16 v[32:35], v[156:159], v[204:207], v[32:35]
	v_mfma_f32_16x16x32_bf16 v[24:27], v[164:167], v[204:207], v[24:27]
	v_mfma_f32_16x16x32_bf16 v[16:19], v[156:159], v[216:219], v[16:19]
	v_mfma_f32_16x16x32_bf16 v[8:11], v[164:167], v[216:219], v[8:11]
	s_setprio 0
	s_setprio 1
	v_mfma_f32_16x16x32_bf16 v[52:55], v[168:171], v[184:187], v[52:55]
	v_mfma_f32_16x16x32_bf16 v[44:47], v[176:179], v[184:187], v[44:47]
	v_mfma_f32_16x16x32_bf16 v[36:39], v[168:171], v[192:195], v[36:39]
	v_mfma_f32_16x16x32_bf16 v[28:31], v[176:179], v[192:195], v[28:31]
	v_mfma_f32_16x16x32_bf16 v[20:23], v[168:171], v[200:203], v[20:23]
	v_mfma_f32_16x16x32_bf16 v[12:15], v[176:179], v[200:203], v[12:15]
	v_mfma_f32_16x16x32_bf16 v[4:7], v[168:171], v[212:215], v[4:7]
	v_mfma_f32_16x16x32_bf16 v[0:3], v[176:179], v[212:215], v[0:3]
	v_mfma_f32_16x16x32_bf16 v[52:55], v[172:175], v[188:191], v[52:55]
	v_mfma_f32_16x16x32_bf16 v[44:47], v[180:183], v[188:191], v[44:47]
	v_mfma_f32_16x16x32_bf16 v[36:39], v[172:175], v[196:199], v[36:39]
	v_mfma_f32_16x16x32_bf16 v[28:31], v[180:183], v[196:199], v[28:31]
	v_mfma_f32_16x16x32_bf16 v[20:23], v[172:175], v[204:207], v[20:23]
	v_mfma_f32_16x16x32_bf16 v[12:15], v[180:183], v[204:207], v[12:15]
	v_mfma_f32_16x16x32_bf16 v[4:7], v[172:175], v[216:219], v[4:7]
	v_mfma_f32_16x16x32_bf16 v[0:3], v[180:183], v[216:219], v[0:3]
	s_setprio 0
	s_barrier
	s_add_i32 s65, 0, 0x18000
	s_add_i32 s66, 0, 0x1c000
	v_add_u32_e32 v164, s65, v152
	v_add_u32_e32 v180, s66, v152
	ds_read_b128 v[144:147], v164
	ds_read_b128 v[156:159], v164 offset:1024
	ds_read_b128 v[160:163], v164 offset:2048
	ds_read_b128 v[164:167], v164 offset:3072
	ds_read_b128 v[168:171], v180
	ds_read_b128 v[172:175], v180 offset:1024
	ds_read_b128 v[176:179], v180 offset:2048
	ds_read_b128 v[180:183], v180 offset:3072
	s_add_u32 s34, s34, 0x20000
	s_addc_u32 s35, s35, 0
	s_mov_b32 m0, s40
	v_lshl_add_u64 v[222:223], s[34:35], 0, v[128:129]
	ds_read_b128 v[184:187], v155 offset:32768
	ds_read_b128 v[188:191], v155 offset:33792
	ds_read_b128 v[192:195], v155 offset:34816
	ds_read_b128 v[196:199], v155 offset:35840
	ds_read_b128 v[200:203], v155 offset:36864
	ds_read_b128 v[204:207], v155 offset:37888
	ds_read_b128 v[212:215], v155 offset:38912
	ds_read_b128 v[216:219], v155 offset:39936
	global_load_lds_dwordx4 v[222:223], off
	v_lshl_add_u64 v[222:223], s[34:35], 0, v[132:133]
	s_mov_b32 m0, s41
	s_nop 0
	global_load_lds_dwordx4 v[222:223], off
	s_waitcnt vmcnt(8)
	s_waitcnt lgkmcnt(0)
	s_barrier
	s_setprio 1
	s_waitcnt lgkmcnt(0)
	v_mfma_f32_16x16x32_bf16 v[124:127], v[144:147], v[184:187], v[124:127]
	v_mfma_f32_16x16x32_bf16 v[120:123], v[160:163], v[184:187], v[120:123]
	v_mfma_f32_16x16x32_bf16 v[116:119], v[144:147], v[192:195], v[116:119]
	v_mfma_f32_16x16x32_bf16 v[108:111], v[160:163], v[192:195], v[108:111]
	v_mfma_f32_16x16x32_bf16 v[96:99], v[144:147], v[200:203], v[96:99]
	v_mfma_f32_16x16x32_bf16 v[88:91], v[160:163], v[200:203], v[88:91]
	v_mfma_f32_16x16x32_bf16 v[80:83], v[144:147], v[212:215], v[80:83]
	v_mfma_f32_16x16x32_bf16 v[72:75], v[160:163], v[212:215], v[72:75]
	v_mfma_f32_16x16x32_bf16 v[124:127], v[156:159], v[188:191], v[124:127]
	v_mfma_f32_16x16x32_bf16 v[120:123], v[164:167], v[188:191], v[120:123]
	v_mfma_f32_16x16x32_bf16 v[116:119], v[156:159], v[196:199], v[116:119]
	v_mfma_f32_16x16x32_bf16 v[108:111], v[164:167], v[196:199], v[108:111]
	v_mfma_f32_16x16x32_bf16 v[96:99], v[156:159], v[204:207], v[96:99]
	v_mfma_f32_16x16x32_bf16 v[88:91], v[164:167], v[204:207], v[88:91]
	v_mfma_f32_16x16x32_bf16 v[80:83], v[156:159], v[216:219], v[80:83]
	v_mfma_f32_16x16x32_bf16 v[72:75], v[164:167], v[216:219], v[72:75]
	s_setprio 0
	s_setprio 1
	v_mfma_f32_16x16x32_bf16 v[112:115], v[168:171], v[184:187], v[112:115]
	v_mfma_f32_16x16x32_bf16 v[104:107], v[176:179], v[184:187], v[104:107]
	v_mfma_f32_16x16x32_bf16 v[100:103], v[168:171], v[192:195], v[100:103]
	v_mfma_f32_16x16x32_bf16 v[92:95], v[176:179], v[192:195], v[92:95]
	v_mfma_f32_16x16x32_bf16 v[84:87], v[168:171], v[200:203], v[84:87]
	v_mfma_f32_16x16x32_bf16 v[76:79], v[176:179], v[200:203], v[76:79]
	v_mfma_f32_16x16x32_bf16 v[68:71], v[168:171], v[212:215], v[68:71]
	v_mfma_f32_16x16x32_bf16 v[64:67], v[176:179], v[212:215], v[64:67]
	v_mfma_f32_16x16x32_bf16 v[112:115], v[172:175], v[188:191], v[112:115]
	v_mfma_f32_16x16x32_bf16 v[104:107], v[180:183], v[188:191], v[104:107]
	v_mfma_f32_16x16x32_bf16 v[100:103], v[172:175], v[196:199], v[100:103]
	v_mfma_f32_16x16x32_bf16 v[92:95], v[180:183], v[196:199], v[92:95]
	v_mfma_f32_16x16x32_bf16 v[84:87], v[172:175], v[204:207], v[84:87]
	v_mfma_f32_16x16x32_bf16 v[76:79], v[180:183], v[204:207], v[76:79]
	v_mfma_f32_16x16x32_bf16 v[68:71], v[172:175], v[216:219], v[68:71]
	v_mfma_f32_16x16x32_bf16 v[64:67], v[180:183], v[216:219], v[64:67]
	s_setprio 0
	s_barrier
	s_add_i32 s34, s65, s36
	v_lshl_add_u64 v[148:149], v[148:149], 0, s[4:5]
	s_mov_b32 m0, s34
	ds_read_b128 v[184:187], v155 offset:49152
	ds_read_b128 v[188:191], v155 offset:50176
	ds_read_b128 v[192:195], v155 offset:51200
	ds_read_b128 v[196:199], v155 offset:52224
	ds_read_b128 v[200:203], v155 offset:53248
	ds_read_b128 v[204:207], v155 offset:54272
	ds_read_b128 v[212:215], v155 offset:55296
	ds_read_b128 v[216:219], v155 offset:56320
	global_load_lds_dwordx4 v[148:149], off
	s_add_i32 m0, s34, 0x2000
	s_add_u32 s26, s26, 0x20080
	v_lshl_add_u64 v[148:149], v[208:209], 0, s[4:5]
	s_addc_u32 s27, s27, 0
	s_add_i32 s34, s66, s36
	global_load_lds_dwordx4 v[148:149], off
	v_lshl_add_u64 v[148:149], s[26:27], 0, v[130:131]
	s_mov_b32 m0, s34
	s_nop 0
	global_load_lds_dwordx4 v[148:149], off
	v_lshl_add_u64 v[148:149], s[26:27], 0, v[134:135]
	s_add_i32 m0, s34, 0x2000
	s_nop 0
	global_load_lds_dwordx4 v[148:149], off
	v_lshl_add_u64 v[148:149], v[210:211], 0, s[4:5]
	s_mov_b32 m0, s49
	s_nop 0
	global_load_lds_dwordx4 v[148:149], off
	v_lshl_add_u64 v[148:149], v[220:221], 0, s[4:5]
	s_mov_b32 m0, s50
	s_nop 0
	global_load_lds_dwordx4 v[148:149], off
	s_waitcnt vmcnt(8)
	s_waitcnt lgkmcnt(0)
	s_barrier
	s_setprio 1
	s_waitcnt lgkmcnt(0)
	v_mfma_f32_16x16x32_bf16 v[60:63], v[144:147], v[184:187], v[60:63]
	v_mfma_f32_16x16x32_bf16 v[56:59], v[160:163], v[184:187], v[56:59]
	v_mfma_f32_16x16x32_bf16 v[48:51], v[144:147], v[192:195], v[48:51]
	v_mfma_f32_16x16x32_bf16 v[40:43], v[160:163], v[192:195], v[40:43]
	v_mfma_f32_16x16x32_bf16 v[32:35], v[144:147], v[200:203], v[32:35]
	v_mfma_f32_16x16x32_bf16 v[24:27], v[160:163], v[200:203], v[24:27]
	v_mfma_f32_16x16x32_bf16 v[16:19], v[144:147], v[212:215], v[16:19]
	v_mfma_f32_16x16x32_bf16 v[8:11], v[160:163], v[212:215], v[8:11]
	v_mfma_f32_16x16x32_bf16 v[60:63], v[156:159], v[188:191], v[60:63]
	v_mfma_f32_16x16x32_bf16 v[56:59], v[164:167], v[188:191], v[56:59]
	v_mfma_f32_16x16x32_bf16 v[48:51], v[156:159], v[196:199], v[48:51]
	v_mfma_f32_16x16x32_bf16 v[40:43], v[164:167], v[196:199], v[40:43]
	v_mfma_f32_16x16x32_bf16 v[32:35], v[156:159], v[204:207], v[32:35]
	v_mfma_f32_16x16x32_bf16 v[24:27], v[164:167], v[204:207], v[24:27]
	v_mfma_f32_16x16x32_bf16 v[16:19], v[156:159], v[216:219], v[16:19]
	v_mfma_f32_16x16x32_bf16 v[8:11], v[164:167], v[216:219], v[8:11]
	s_setprio 0
	s_setprio 1
	v_mfma_f32_16x16x32_bf16 v[52:55], v[168:171], v[184:187], v[52:55]
	v_mfma_f32_16x16x32_bf16 v[44:47], v[176:179], v[184:187], v[44:47]
	v_mfma_f32_16x16x32_bf16 v[36:39], v[168:171], v[192:195], v[36:39]
	v_mfma_f32_16x16x32_bf16 v[28:31], v[176:179], v[192:195], v[28:31]
	v_mfma_f32_16x16x32_bf16 v[20:23], v[168:171], v[200:203], v[20:23]
	v_mfma_f32_16x16x32_bf16 v[12:15], v[176:179], v[200:203], v[12:15]
	v_mfma_f32_16x16x32_bf16 v[4:7], v[168:171], v[212:215], v[4:7]
	v_mfma_f32_16x16x32_bf16 v[0:3], v[176:179], v[212:215], v[0:3]
	v_mfma_f32_16x16x32_bf16 v[52:55], v[172:175], v[188:191], v[52:55]
	v_mfma_f32_16x16x32_bf16 v[44:47], v[180:183], v[188:191], v[44:47]
	v_mfma_f32_16x16x32_bf16 v[36:39], v[172:175], v[196:199], v[36:39]
	v_mfma_f32_16x16x32_bf16 v[28:31], v[180:183], v[196:199], v[28:31]
	v_mfma_f32_16x16x32_bf16 v[20:23], v[172:175], v[204:207], v[20:23]
	v_mfma_f32_16x16x32_bf16 v[12:15], v[180:183], v[204:207], v[12:15]
	v_mfma_f32_16x16x32_bf16 v[4:7], v[172:175], v[216:219], v[4:7]
	v_mfma_f32_16x16x32_bf16 v[0:3], v[180:183], v[216:219], v[0:3]
	s_add_i32 s64, s64, 2
	s_add_u32 s24, s24, 0x100
	s_addc_u32 s25, s25, 0
	s_add_u32 s60, s60, 0x100
	s_addc_u32 s61, s61, 0
	s_cmp_gt_u32 s64, 5
	s_setprio 0
	s_barrier
	s_cbranch_scc0 .LBB0_3138
	s_and_b64 vcc, exec, s[8:9]
	s_cbranch_vccz .LBB0_3141
	s_barrier

.LBB0_3238:
	v_add_u32_e32 v137, s64, v163
	ds_read_b128 v[146:149], v137
	ds_read_b128 v[150:153], v137 offset:1024
	ds_read_b128 v[166:169], v137 offset:2048
	ds_read_b128 v[170:173], v137 offset:3072
	v_add_u32_e32 v137, s65, v163
	ds_read_b128 v[174:177], v137
	ds_read_b128 v[178:181], v137 offset:1024
	ds_read_b128 v[182:185], v137 offset:2048
	ds_read_b128 v[186:189], v137 offset:3072
	s_add_u32 s40, s48, 0xfffc0080
	s_addc_u32 s41, s49, -1
	s_cmp_eq_u32 s70, 12
	s_cselect_b32 s51, s25, s41
	s_cselect_b32 s50, s37, s40
	s_cselect_b32 s41, s23, s69
	s_cselect_b32 s40, s67, s68
	v_lshl_add_u64 v[210:211], s[48:49], 0, v[138:139]
	s_add_i32 m0, s47, 0xc000
	ds_read_b128 v[190:193], v165
	ds_read_b128 v[194:197], v165 offset:1024
	ds_read_b128 v[198:201], v165 offset:2048
	ds_read_b128 v[202:205], v165 offset:3072
	ds_read_b128 v[206:209], v165 offset:4096
	ds_read_b128 v[212:215], v165 offset:5120
	ds_read_b128 v[216:219], v165 offset:6144
	ds_read_b128 v[220:223], v165 offset:7168
	global_load_lds_dwordx4 v[210:211], off
	v_lshl_add_u64 v[210:211], s[48:49], 0, v[140:141]
	s_add_i32 m0, s47, 0xe000
	s_nop 0
	global_load_lds_dwordx4 v[210:211], off
	s_waitcnt vmcnt(8)
	s_waitcnt lgkmcnt(0)
	s_barrier
	s_setprio 1
	s_waitcnt lgkmcnt(0)
	v_mfma_f32_16x16x32_bf16 v[56:59], v[146:149], v[190:193], v[56:59]
	v_mfma_f32_16x16x32_bf16 v[60:63], v[166:169], v[190:193], v[60:63]
	v_mfma_f32_16x16x32_bf16 v[48:51], v[146:149], v[198:201], v[48:51]
	v_mfma_f32_16x16x32_bf16 v[52:55], v[166:169], v[198:201], v[52:55]
	v_mfma_f32_16x16x32_bf16 v[40:43], v[146:149], v[206:209], v[40:43]
	v_mfma_f32_16x16x32_bf16 v[44:47], v[166:169], v[206:209], v[44:47]
	v_mfma_f32_16x16x32_bf16 v[32:35], v[146:149], v[216:219], v[32:35]
	v_mfma_f32_16x16x32_bf16 v[36:39], v[166:169], v[216:219], v[36:39]
	v_mfma_f32_16x16x32_bf16 v[56:59], v[150:153], v[194:197], v[56:59]
	v_mfma_f32_16x16x32_bf16 v[60:63], v[170:173], v[194:197], v[60:63]
	v_mfma_f32_16x16x32_bf16 v[48:51], v[150:153], v[202:205], v[48:51]
	v_mfma_f32_16x16x32_bf16 v[52:55], v[170:173], v[202:205], v[52:55]
	v_mfma_f32_16x16x32_bf16 v[40:43], v[150:153], v[212:215], v[40:43]
	v_mfma_f32_16x16x32_bf16 v[44:47], v[170:173], v[212:215], v[44:47]
	v_mfma_f32_16x16x32_bf16 v[32:35], v[150:153], v[220:223], v[32:35]
	v_mfma_f32_16x16x32_bf16 v[36:39], v[170:173], v[220:223], v[36:39]
	s_setprio 0
	s_setprio 1
	v_mfma_f32_16x16x32_bf16 v[120:123], v[174:177], v[190:193], v[120:123]
	v_mfma_f32_16x16x32_bf16 v[124:127], v[182:185], v[190:193], v[124:127]
	v_mfma_f32_16x16x32_bf16 v[112:115], v[174:177], v[198:201], v[112:115]
	v_mfma_f32_16x16x32_bf16 v[116:119], v[182:185], v[198:201], v[116:119]
	v_mfma_f32_16x16x32_bf16 v[104:107], v[174:177], v[206:209], v[104:107]
	v_mfma_f32_16x16x32_bf16 v[108:111], v[182:185], v[206:209], v[108:111]
	v_mfma_f32_16x16x32_bf16 v[88:91], v[174:177], v[216:219], v[88:91]
	v_mfma_f32_16x16x32_bf16 v[92:95], v[182:185], v[216:219], v[92:95]
	v_mfma_f32_16x16x32_bf16 v[120:123], v[178:181], v[194:197], v[120:123]
	v_mfma_f32_16x16x32_bf16 v[124:127], v[186:189], v[194:197], v[124:127]
	v_mfma_f32_16x16x32_bf16 v[112:115], v[178:181], v[202:205], v[112:115]
	v_mfma_f32_16x16x32_bf16 v[116:119], v[186:189], v[202:205], v[116:119]
	v_mfma_f32_16x16x32_bf16 v[104:107], v[178:181], v[212:215], v[104:107]
	v_mfma_f32_16x16x32_bf16 v[108:111], v[186:189], v[212:215], v[108:111]
	v_mfma_f32_16x16x32_bf16 v[88:91], v[178:181], v[220:223], v[88:91]
	v_mfma_f32_16x16x32_bf16 v[92:95], v[186:189], v[220:223], v[92:95]
	s_setprio 0
	s_barrier
	s_add_i32 s71, s64, s13
	v_lshl_add_u64 v[210:211], s[40:41], 0, v[130:131]
	s_mov_b32 m0, s71
	ds_read_b128 v[190:193], v165 offset:16384
	ds_read_b128 v[194:197], v165 offset:17408
	ds_read_b128 v[198:201], v165 offset:18432
	ds_read_b128 v[202:205], v165 offset:19456
	ds_read_b128 v[206:209], v165 offset:20480
	ds_read_b128 v[212:215], v165 offset:21504
	ds_read_b128 v[216:219], v165 offset:22528
	ds_read_b128 v[220:223], v165 offset:23552
	global_load_lds_dwordx4 v[210:211], off
	s_add_i32 m0, s71, 0x2000
	s_add_u32 s72, s40, 0x40000
	v_lshl_add_u64 v[224:225], s[40:41], 0, v[134:135]
	s_addc_u32 s73, s41, 0
	s_add_i32 s71, s65, s13
	global_load_lds_dwordx4 v[224:225], off
	v_lshl_add_u64 v[226:227], s[72:73], 0, v[130:131]
	s_mov_b32 m0, s71
	v_lshl_add_u64 v[228:229], s[50:51], 0, v[132:133]
	global_load_lds_dwordx4 v[226:227], off
	v_lshl_add_u64 v[226:227], s[72:73], 0, v[134:135]
	s_add_i32 m0, s71, 0x2000
	s_nop 0
	global_load_lds_dwordx4 v[226:227], off
	v_lshl_add_u64 v[226:227], s[50:51], 0, v[128:129]
	s_mov_b32 m0, s47
	s_nop 0
	global_load_lds_dwordx4 v[226:227], off
	s_mov_b32 m0, s53
	s_nop 0
	global_load_lds_dwordx4 v[228:229], off
	s_waitcnt vmcnt(8)
	s_waitcnt lgkmcnt(0)
	s_barrier
	s_setprio 1
	s_waitcnt lgkmcnt(0)
	v_mfma_f32_16x16x32_bf16 v[24:27], v[146:149], v[190:193], v[24:27]
	v_mfma_f32_16x16x32_bf16 v[28:31], v[166:169], v[190:193], v[28:31]
	v_mfma_f32_16x16x32_bf16 v[16:19], v[146:149], v[198:201], v[16:19]
	v_mfma_f32_16x16x32_bf16 v[20:23], v[166:169], v[198:201], v[20:23]
	v_mfma_f32_16x16x32_bf16 v[8:11], v[146:149], v[206:209], v[8:11]
	v_mfma_f32_16x16x32_bf16 v[12:15], v[166:169], v[206:209], v[12:15]
	v_mfma_f32_16x16x32_bf16 v[0:3], v[146:149], v[216:219], v[0:3]
	v_mfma_f32_16x16x32_bf16 v[4:7], v[166:169], v[216:219], v[4:7]
	v_mfma_f32_16x16x32_bf16 v[24:27], v[150:153], v[194:197], v[24:27]
	v_mfma_f32_16x16x32_bf16 v[28:31], v[170:173], v[194:197], v[28:31]
	v_mfma_f32_16x16x32_bf16 v[16:19], v[150:153], v[202:205], v[16:19]
	v_mfma_f32_16x16x32_bf16 v[20:23], v[170:173], v[202:205], v[20:23]
	v_mfma_f32_16x16x32_bf16 v[8:11], v[150:153], v[212:215], v[8:11]
	v_mfma_f32_16x16x32_bf16 v[12:15], v[170:173], v[212:215], v[12:15]
	v_mfma_f32_16x16x32_bf16 v[0:3], v[150:153], v[220:223], v[0:3]
	v_mfma_f32_16x16x32_bf16 v[4:7], v[170:173], v[220:223], v[4:7]
	s_setprio 0
	s_setprio 1
	v_mfma_f32_16x16x32_bf16 v[72:75], v[174:177], v[190:193], v[72:75]
	v_mfma_f32_16x16x32_bf16 v[80:83], v[182:185], v[190:193], v[80:83]
	v_mfma_f32_16x16x32_bf16 v[96:99], v[174:177], v[198:201], v[96:99]
	v_mfma_f32_16x16x32_bf16 v[100:103], v[182:185], v[198:201], v[100:103]
	v_mfma_f32_16x16x32_bf16 v[76:79], v[174:177], v[206:209], v[76:79]
	v_mfma_f32_16x16x32_bf16 v[84:87], v[182:185], v[206:209], v[84:87]
	v_mfma_f32_16x16x32_bf16 v[64:67], v[174:177], v[216:219], v[64:67]
	v_mfma_f32_16x16x32_bf16 v[68:71], v[182:185], v[216:219], v[68:71]
	v_mfma_f32_16x16x32_bf16 v[72:75], v[178:181], v[194:197], v[72:75]
	v_mfma_f32_16x16x32_bf16 v[80:83], v[186:189], v[194:197], v[80:83]
	v_mfma_f32_16x16x32_bf16 v[96:99], v[178:181], v[202:205], v[96:99]
	v_mfma_f32_16x16x32_bf16 v[100:103], v[186:189], v[202:205], v[100:103]
	v_mfma_f32_16x16x32_bf16 v[76:79], v[178:181], v[212:215], v[76:79]
	v_mfma_f32_16x16x32_bf16 v[84:87], v[186:189], v[212:215], v[84:87]
	v_mfma_f32_16x16x32_bf16 v[64:67], v[178:181], v[220:223], v[64:67]
	v_mfma_f32_16x16x32_bf16 v[68:71], v[186:189], v[220:223], v[68:71]
	s_setprio 0
	s_barrier
	s_add_i32 s71, 0, 0x18000
	v_add_u32_e32 v137, s71, v163
	s_add_i32 s72, 0, 0x1c000
	ds_read_b128 v[146:149], v137
	ds_read_b128 v[150:153], v137 offset:1024
	ds_read_b128 v[166:169], v137 offset:2048
	ds_read_b128 v[170:173], v137 offset:3072
	v_add_u32_e32 v137, s72, v163
	ds_read_b128 v[174:177], v137
	ds_read_b128 v[178:181], v137 offset:1024
	ds_read_b128 v[182:185], v137 offset:2048
	ds_read_b128 v[186:189], v137 offset:3072
	s_add_u32 s50, s50, 0x40000
	s_addc_u32 s51, s51, 0
	s_mov_b32 m0, s54
	v_lshl_add_u64 v[230:231], s[50:51], 0, v[128:129]
	ds_read_b128 v[190:193], v165 offset:32768
	ds_read_b128 v[194:197], v165 offset:33792
	ds_read_b128 v[198:201], v165 offset:34816
	ds_read_b128 v[202:205], v165 offset:35840
	ds_read_b128 v[206:209], v165 offset:36864
	ds_read_b128 v[212:215], v165 offset:37888
	ds_read_b128 v[216:219], v165 offset:38912
	ds_read_b128 v[220:223], v165 offset:39936
	global_load_lds_dwordx4 v[230:231], off
	v_lshl_add_u64 v[230:231], s[50:51], 0, v[132:133]
	s_mov_b32 m0, s55
	s_nop 0
	global_load_lds_dwordx4 v[230:231], off
	s_waitcnt vmcnt(8)
	s_waitcnt lgkmcnt(0)
	s_barrier
	s_setprio 1
	s_waitcnt lgkmcnt(0)
	v_mfma_f32_16x16x32_bf16 v[56:59], v[146:149], v[190:193], v[56:59]
	v_mfma_f32_16x16x32_bf16 v[60:63], v[166:169], v[190:193], v[60:63]
	v_mfma_f32_16x16x32_bf16 v[48:51], v[146:149], v[198:201], v[48:51]
	v_mfma_f32_16x16x32_bf16 v[52:55], v[166:169], v[198:201], v[52:55]
	v_mfma_f32_16x16x32_bf16 v[40:43], v[146:149], v[206:209], v[40:43]
	v_mfma_f32_16x16x32_bf16 v[44:47], v[166:169], v[206:209], v[44:47]
	v_mfma_f32_16x16x32_bf16 v[32:35], v[146:149], v[216:219], v[32:35]
	v_mfma_f32_16x16x32_bf16 v[36:39], v[166:169], v[216:219], v[36:39]
	v_mfma_f32_16x16x32_bf16 v[56:59], v[150:153], v[194:197], v[56:59]
	v_mfma_f32_16x16x32_bf16 v[60:63], v[170:173], v[194:197], v[60:63]
	v_mfma_f32_16x16x32_bf16 v[48:51], v[150:153], v[202:205], v[48:51]
	v_mfma_f32_16x16x32_bf16 v[52:55], v[170:173], v[202:205], v[52:55]
	v_mfma_f32_16x16x32_bf16 v[40:43], v[150:153], v[212:215], v[40:43]
	v_mfma_f32_16x16x32_bf16 v[44:47], v[170:173], v[212:215], v[44:47]
	v_mfma_f32_16x16x32_bf16 v[32:35], v[150:153], v[220:223], v[32:35]
	v_mfma_f32_16x16x32_bf16 v[36:39], v[170:173], v[220:223], v[36:39]
	s_setprio 0
	s_setprio 1
	v_mfma_f32_16x16x32_bf16 v[120:123], v[174:177], v[190:193], v[120:123]
	v_mfma_f32_16x16x32_bf16 v[124:127], v[182:185], v[190:193], v[124:127]
	v_mfma_f32_16x16x32_bf16 v[112:115], v[174:177], v[198:201], v[112:115]
	v_mfma_f32_16x16x32_bf16 v[116:119], v[182:185], v[198:201], v[116:119]
	v_mfma_f32_16x16x32_bf16 v[104:107], v[174:177], v[206:209], v[104:107]
	v_mfma_f32_16x16x32_bf16 v[108:111], v[182:185], v[206:209], v[108:111]
	v_mfma_f32_16x16x32_bf16 v[88:91], v[174:177], v[216:219], v[88:91]
	v_mfma_f32_16x16x32_bf16 v[92:95], v[182:185], v[216:219], v[92:95]
	v_mfma_f32_16x16x32_bf16 v[120:123], v[178:181], v[194:197], v[120:123]
	v_mfma_f32_16x16x32_bf16 v[124:127], v[186:189], v[194:197], v[124:127]
	v_mfma_f32_16x16x32_bf16 v[112:115], v[178:181], v[202:205], v[112:115]
	v_mfma_f32_16x16x32_bf16 v[116:119], v[186:189], v[202:205], v[116:119]
	v_mfma_f32_16x16x32_bf16 v[104:107], v[178:181], v[212:215], v[104:107]
	v_mfma_f32_16x16x32_bf16 v[108:111], v[186:189], v[212:215], v[108:111]
	v_mfma_f32_16x16x32_bf16 v[88:91], v[178:181], v[220:223], v[88:91]
	v_mfma_f32_16x16x32_bf16 v[92:95], v[186:189], v[220:223], v[92:95]
	s_setprio 0
	s_barrier
	s_add_i32 s50, s71, s13
	v_lshl_add_u64 v[210:211], v[210:211], 0, s[16:17]
	s_mov_b32 m0, s50
	ds_read_b128 v[190:193], v165 offset:49152
	ds_read_b128 v[194:197], v165 offset:50176
	ds_read_b128 v[198:201], v165 offset:51200
	ds_read_b128 v[202:205], v165 offset:52224
	ds_read_b128 v[206:209], v165 offset:53248
	ds_read_b128 v[212:215], v165 offset:54272
	ds_read_b128 v[216:219], v165 offset:55296
	ds_read_b128 v[220:223], v165 offset:56320
	global_load_lds_dwordx4 v[210:211], off
	s_add_i32 m0, s50, 0x2000
	s_add_u32 s40, s40, 0x40080
	v_lshl_add_u64 v[210:211], v[224:225], 0, s[16:17]
	s_addc_u32 s41, s41, 0
	s_add_i32 s50, s72, s13
	global_load_lds_dwordx4 v[210:211], off
	v_lshl_add_u64 v[210:211], s[40:41], 0, v[130:131]
	s_mov_b32 m0, s50
	s_nop 0
	global_load_lds_dwordx4 v[210:211], off
	v_lshl_add_u64 v[210:211], s[40:41], 0, v[134:135]
	s_add_i32 m0, s50, 0x2000
	s_nop 0
	global_load_lds_dwordx4 v[210:211], off
	v_lshl_add_u64 v[210:211], v[226:227], 0, s[16:17]
	s_mov_b32 m0, s60
	s_nop 0
	global_load_lds_dwordx4 v[210:211], off
	v_lshl_add_u64 v[210:211], v[228:229], 0, s[16:17]
	s_mov_b32 m0, s61
	s_nop 0
	global_load_lds_dwordx4 v[210:211], off
	s_waitcnt vmcnt(8)
	s_waitcnt lgkmcnt(0)
	s_barrier
	s_setprio 1
	s_waitcnt lgkmcnt(0)
	v_mfma_f32_16x16x32_bf16 v[24:27], v[146:149], v[190:193], v[24:27]
	v_mfma_f32_16x16x32_bf16 v[28:31], v[166:169], v[190:193], v[28:31]
	v_mfma_f32_16x16x32_bf16 v[16:19], v[146:149], v[198:201], v[16:19]
	v_mfma_f32_16x16x32_bf16 v[20:23], v[166:169], v[198:201], v[20:23]
	v_mfma_f32_16x16x32_bf16 v[8:11], v[146:149], v[206:209], v[8:11]
	v_mfma_f32_16x16x32_bf16 v[12:15], v[166:169], v[206:209], v[12:15]
	v_mfma_f32_16x16x32_bf16 v[0:3], v[146:149], v[216:219], v[0:3]
	v_mfma_f32_16x16x32_bf16 v[4:7], v[166:169], v[216:219], v[4:7]
	v_mfma_f32_16x16x32_bf16 v[24:27], v[150:153], v[194:197], v[24:27]
	v_mfma_f32_16x16x32_bf16 v[28:31], v[170:173], v[194:197], v[28:31]
	v_mfma_f32_16x16x32_bf16 v[16:19], v[150:153], v[202:205], v[16:19]
	v_mfma_f32_16x16x32_bf16 v[20:23], v[170:173], v[202:205], v[20:23]
	v_mfma_f32_16x16x32_bf16 v[8:11], v[150:153], v[212:215], v[8:11]
	v_mfma_f32_16x16x32_bf16 v[12:15], v[170:173], v[212:215], v[12:15]
	v_mfma_f32_16x16x32_bf16 v[0:3], v[150:153], v[220:223], v[0:3]
	v_mfma_f32_16x16x32_bf16 v[4:7], v[170:173], v[220:223], v[4:7]
	s_setprio 0
	s_setprio 1
	v_mfma_f32_16x16x32_bf16 v[72:75], v[174:177], v[190:193], v[72:75]
	v_mfma_f32_16x16x32_bf16 v[80:83], v[182:185], v[190:193], v[80:83]
	v_mfma_f32_16x16x32_bf16 v[96:99], v[174:177], v[198:201], v[96:99]
	v_mfma_f32_16x16x32_bf16 v[100:103], v[182:185], v[198:201], v[100:103]
	v_mfma_f32_16x16x32_bf16 v[76:79], v[174:177], v[206:209], v[76:79]
	v_mfma_f32_16x16x32_bf16 v[84:87], v[182:185], v[206:209], v[84:87]
	v_mfma_f32_16x16x32_bf16 v[64:67], v[174:177], v[216:219], v[64:67]
	v_mfma_f32_16x16x32_bf16 v[68:71], v[182:185], v[216:219], v[68:71]
	v_mfma_f32_16x16x32_bf16 v[72:75], v[178:181], v[194:197], v[72:75]
	v_mfma_f32_16x16x32_bf16 v[80:83], v[186:189], v[194:197], v[80:83]
	v_mfma_f32_16x16x32_bf16 v[96:99], v[178:181], v[202:205], v[96:99]
	v_mfma_f32_16x16x32_bf16 v[100:103], v[186:189], v[202:205], v[100:103]
	v_mfma_f32_16x16x32_bf16 v[76:79], v[178:181], v[212:215], v[76:79]
	v_mfma_f32_16x16x32_bf16 v[84:87], v[186:189], v[212:215], v[84:87]
	v_mfma_f32_16x16x32_bf16 v[64:67], v[178:181], v[220:223], v[64:67]
	v_mfma_f32_16x16x32_bf16 v[68:71], v[186:189], v[220:223], v[68:71]
	s_add_i32 s70, s70, 2
	s_add_u32 s48, s48, 0x100
	s_addc_u32 s49, s49, 0
	s_add_u32 s68, s68, 0x100
	s_addc_u32 s69, s69, 0
	s_cmp_gt_u32 s70, 13
	s_setprio 0
	s_barrier
	s_cbranch_scc0 .LBB0_3238
	s_and_b64 vcc, exec, s[18:19]
	s_cbranch_vccz .LBB0_3241
	s_barrier

.Lrlx31b_done:
	s_mov_b32 s99, 0
	s_waitcnt lgkmcnt(0)
	s_barrier
	s_setprio 1
	s_waitcnt lgkmcnt(0)
	v_mfma_f32_16x16x32_f16 v[60:63], v[108:111], v[188:191], v[60:63]
	v_mfma_f32_16x16x32_f16 v[52:55], v[120:123], v[188:191], v[52:55]
	v_mfma_f32_16x16x32_f16 v[44:47], v[108:111], v[196:199], v[44:47]
	v_mfma_f32_16x16x32_f16 v[36:39], v[120:123], v[196:199], v[36:39]
	v_mfma_f32_16x16x32_f16 v[28:31], v[108:111], v[204:207], v[28:31]
	v_mfma_f32_16x16x32_f16 v[20:23], v[120:123], v[204:207], v[20:23]
	v_mfma_f32_16x16x32_f16 v[12:15], v[108:111], v[216:219], v[12:15]
	v_mfma_f32_16x16x32_f16 v[4:7], v[120:123], v[216:219], v[4:7]
	v_mfma_f32_16x16x32_f16 v[60:63], v[112:115], v[192:195], v[60:63]
	v_mfma_f32_16x16x32_f16 v[52:55], v[128:131], v[192:195], v[52:55]
	v_mfma_f32_16x16x32_f16 v[44:47], v[112:115], v[200:203], v[44:47]
	v_mfma_f32_16x16x32_f16 v[36:39], v[128:131], v[200:203], v[36:39]
	v_mfma_f32_16x16x32_f16 v[28:31], v[112:115], v[212:215], v[28:31]
	v_mfma_f32_16x16x32_f16 v[20:23], v[128:131], v[212:215], v[20:23]
	v_mfma_f32_16x16x32_f16 v[12:15], v[112:115], v[220:223], v[12:15]
	v_mfma_f32_16x16x32_f16 v[4:7], v[128:131], v[220:223], v[4:7]
	s_setprio 0
	s_setprio 1
	v_mfma_f32_16x16x32_f16 v[56:59], v[148:151], v[188:191], v[56:59]
	v_mfma_f32_16x16x32_f16 v[48:51], v[156:159], v[188:191], v[48:51]
	v_mfma_f32_16x16x32_f16 v[40:43], v[148:151], v[196:199], v[40:43]
	v_mfma_f32_16x16x32_f16 v[32:35], v[156:159], v[196:199], v[32:35]
	v_mfma_f32_16x16x32_f16 v[24:27], v[148:151], v[204:207], v[24:27]
	v_mfma_f32_16x16x32_f16 v[16:19], v[156:159], v[204:207], v[16:19]
	v_mfma_f32_16x16x32_f16 v[8:11], v[148:151], v[216:219], v[8:11]
	v_mfma_f32_16x16x32_f16 v[0:3], v[156:159], v[216:219], v[0:3]
	v_mfma_f32_16x16x32_f16 v[56:59], v[152:155], v[192:195], v[56:59]
	v_mfma_f32_16x16x32_f16 v[48:51], v[176:179], v[192:195], v[48:51]
	v_mfma_f32_16x16x32_f16 v[40:43], v[152:155], v[200:203], v[40:43]
	v_mfma_f32_16x16x32_f16 v[32:35], v[176:179], v[200:203], v[32:35]
	v_mfma_f32_16x16x32_f16 v[24:27], v[152:155], v[212:215], v[24:27]
	v_mfma_f32_16x16x32_f16 v[16:19], v[176:179], v[212:215], v[16:19]
	v_mfma_f32_16x16x32_f16 v[8:11], v[152:155], v[220:223], v[8:11]
	v_mfma_f32_16x16x32_f16 v[0:3], v[176:179], v[220:223], v[0:3]
	s_setprio 0
	s_barrier
	s_add_i32 s80, 0, 0x18000
	s_add_i32 s81, 0, 0x1c000
	v_add_u32_e32 v128, s80, v184
	v_add_u32_e32 v176, s81, v184
	ds_read_b128 v[108:111], v128
	ds_read_b128 v[112:115], v128 offset:1024
	ds_read_b128 v[120:123], v128 offset:2048
	ds_read_b128 v[128:131], v128 offset:3072
	ds_read_b128 v[148:151], v176
	ds_read_b128 v[152:155], v176 offset:1024
	ds_read_b128 v[156:159], v176 offset:2048
	ds_read_b128 v[176:179], v176 offset:3072
	s_add_u32 s40, s40, 0x40000
	s_addc_u32 s41, s41, 0
	s_mov_b32 m0, s52
	v_lshl_add_u64 v[226:227], s[40:41], 0, v[166:167]
	ds_read_b128 v[188:191], v186 offset:32768
	ds_read_b128 v[192:195], v186 offset:33792
	ds_read_b128 v[196:199], v186 offset:34816
	ds_read_b128 v[200:203], v186 offset:35840
	ds_read_b128 v[204:207], v186 offset:36864
	ds_read_b128 v[212:215], v186 offset:37888
	ds_read_b128 v[216:219], v186 offset:38912
	ds_read_b128 v[220:223], v186 offset:39936
	global_load_lds_dwordx4 v[226:227], off
	v_lshl_add_u64 v[226:227], s[40:41], 0, v[162:163]
	s_mov_b32 m0, s53
	s_nop 0
	global_load_lds_dwordx4 v[226:227], off
	s_waitcnt vmcnt(8)
	s_waitcnt lgkmcnt(0)
	s_barrier
	s_setprio 1
	s_waitcnt lgkmcnt(0)
	v_mfma_f32_16x16x32_f16 v[144:147], v[108:111], v[188:191], v[144:147]
	v_mfma_f32_16x16x32_f16 v[136:139], v[120:123], v[188:191], v[136:139]
	v_mfma_f32_16x16x32_f16 v[124:127], v[108:111], v[196:199], v[124:127]
	v_mfma_f32_16x16x32_f16 v[100:103], v[120:123], v[196:199], v[100:103]
	v_mfma_f32_16x16x32_f16 v[92:95], v[108:111], v[204:207], v[92:95]
	v_mfma_f32_16x16x32_f16 v[84:87], v[120:123], v[204:207], v[84:87]
	v_mfma_f32_16x16x32_f16 v[76:79], v[108:111], v[216:219], v[76:79]
	v_mfma_f32_16x16x32_f16 v[68:71], v[120:123], v[216:219], v[68:71]
	v_mfma_f32_16x16x32_f16 v[144:147], v[112:115], v[192:195], v[144:147]
	v_mfma_f32_16x16x32_f16 v[136:139], v[128:131], v[192:195], v[136:139]
	v_mfma_f32_16x16x32_f16 v[124:127], v[112:115], v[200:203], v[124:127]
	v_mfma_f32_16x16x32_f16 v[100:103], v[128:131], v[200:203], v[100:103]
	v_mfma_f32_16x16x32_f16 v[92:95], v[112:115], v[212:215], v[92:95]
	v_mfma_f32_16x16x32_f16 v[84:87], v[128:131], v[212:215], v[84:87]
	v_mfma_f32_16x16x32_f16 v[76:79], v[112:115], v[220:223], v[76:79]
	v_mfma_f32_16x16x32_f16 v[68:71], v[128:131], v[220:223], v[68:71]
	s_setprio 0
	s_setprio 1
	v_mfma_f32_16x16x32_f16 v[140:143], v[148:151], v[188:191], v[140:143]
	v_mfma_f32_16x16x32_f16 v[132:135], v[156:159], v[188:191], v[132:135]
	v_mfma_f32_16x16x32_f16 v[116:119], v[148:151], v[196:199], v[116:119]
	v_mfma_f32_16x16x32_f16 v[96:99], v[156:159], v[196:199], v[96:99]
	v_mfma_f32_16x16x32_f16 v[88:91], v[148:151], v[204:207], v[88:91]
	v_mfma_f32_16x16x32_f16 v[80:83], v[156:159], v[204:207], v[80:83]
	v_mfma_f32_16x16x32_f16 v[72:75], v[148:151], v[216:219], v[72:75]
	v_mfma_f32_16x16x32_f16 v[64:67], v[156:159], v[216:219], v[64:67]
	v_mfma_f32_16x16x32_f16 v[140:143], v[152:155], v[192:195], v[140:143]
	v_mfma_f32_16x16x32_f16 v[132:135], v[176:179], v[192:195], v[132:135]
	v_mfma_f32_16x16x32_f16 v[116:119], v[152:155], v[200:203], v[116:119]
	v_mfma_f32_16x16x32_f16 v[96:99], v[176:179], v[200:203], v[96:99]
	v_mfma_f32_16x16x32_f16 v[88:91], v[152:155], v[212:215], v[88:91]
	v_mfma_f32_16x16x32_f16 v[80:83], v[176:179], v[212:215], v[80:83]
	v_mfma_f32_16x16x32_f16 v[72:75], v[152:155], v[220:223], v[72:75]
	v_mfma_f32_16x16x32_f16 v[64:67], v[176:179], v[220:223], v[64:67]
	s_setprio 0
	s_barrier
	s_add_i32 s40, s80, s49
	v_lshl_add_u64 v[180:181], v[180:181], 0, s[10:11]
	s_mov_b32 m0, s40
	ds_read_b128 v[188:191], v186 offset:49152
	ds_read_b128 v[192:195], v186 offset:50176
	ds_read_b128 v[196:199], v186 offset:51200
	ds_read_b128 v[200:203], v186 offset:52224
	ds_read_b128 v[204:207], v186 offset:53248
	ds_read_b128 v[212:215], v186 offset:54272
	ds_read_b128 v[216:219], v186 offset:55296
	ds_read_b128 v[220:223], v186 offset:56320
	global_load_lds_dwordx4 v[180:181], off
	s_add_i32 m0, s40, 0x2000
	s_add_u32 s36, s36, 0x40080
	v_lshl_add_u64 v[180:181], v[208:209], 0, s[10:11]
	s_addc_u32 s37, s37, 0
	s_add_i32 s40, s81, s49
	global_load_lds_dwordx4 v[180:181], off
	v_lshl_add_u64 v[180:181], s[36:37], 0, v[164:165]
	s_mov_b32 m0, s40
	s_nop 0
	global_load_lds_dwordx4 v[180:181], off
	v_lshl_add_u64 v[180:181], s[36:37], 0, v[160:161]
	s_add_i32 m0, s40, 0x2000
	s_nop 0
	global_load_lds_dwordx4 v[180:181], off
	v_lshl_add_u64 v[180:181], v[210:211], 0, s[10:11]
	s_mov_b32 m0, s61
	s_nop 0
	global_load_lds_dwordx4 v[180:181], off
	v_lshl_add_u64 v[180:181], v[224:225], 0, s[10:11]
	s_mov_b32 m0, s64
	s_nop 0
	global_load_lds_dwordx4 v[180:181], off
	s_waitcnt vmcnt(8)
	s_waitcnt lgkmcnt(0)
	s_barrier
	s_setprio 1
	s_waitcnt lgkmcnt(0)
	v_mfma_f32_16x16x32_f16 v[60:63], v[108:111], v[188:191], v[60:63]
	v_mfma_f32_16x16x32_f16 v[52:55], v[120:123], v[188:191], v[52:55]
	v_mfma_f32_16x16x32_f16 v[44:47], v[108:111], v[196:199], v[44:47]
	v_mfma_f32_16x16x32_f16 v[36:39], v[120:123], v[196:199], v[36:39]
	v_mfma_f32_16x16x32_f16 v[28:31], v[108:111], v[204:207], v[28:31]
	v_mfma_f32_16x16x32_f16 v[20:23], v[120:123], v[204:207], v[20:23]
	v_mfma_f32_16x16x32_f16 v[12:15], v[108:111], v[216:219], v[12:15]
	v_mfma_f32_16x16x32_f16 v[4:7], v[120:123], v[216:219], v[4:7]
	v_mfma_f32_16x16x32_f16 v[60:63], v[112:115], v[192:195], v[60:63]
	v_mfma_f32_16x16x32_f16 v[52:55], v[128:131], v[192:195], v[52:55]
	v_mfma_f32_16x16x32_f16 v[44:47], v[112:115], v[200:203], v[44:47]
	v_mfma_f32_16x16x32_f16 v[36:39], v[128:131], v[200:203], v[36:39]
	v_mfma_f32_16x16x32_f16 v[28:31], v[112:115], v[212:215], v[28:31]
	v_mfma_f32_16x16x32_f16 v[20:23], v[128:131], v[212:215], v[20:23]
	v_mfma_f32_16x16x32_f16 v[12:15], v[112:115], v[220:223], v[12:15]
	v_mfma_f32_16x16x32_f16 v[4:7], v[128:131], v[220:223], v[4:7]
	s_setprio 0
	s_setprio 1
	v_mfma_f32_16x16x32_f16 v[56:59], v[148:151], v[188:191], v[56:59]
	v_mfma_f32_16x16x32_f16 v[48:51], v[156:159], v[188:191], v[48:51]
	v_mfma_f32_16x16x32_f16 v[40:43], v[148:151], v[196:199], v[40:43]
	v_mfma_f32_16x16x32_f16 v[32:35], v[156:159], v[196:199], v[32:35]
	v_mfma_f32_16x16x32_f16 v[24:27], v[148:151], v[204:207], v[24:27]
	v_mfma_f32_16x16x32_f16 v[16:19], v[156:159], v[204:207], v[16:19]
	v_mfma_f32_16x16x32_f16 v[8:11], v[148:151], v[216:219], v[8:11]
	v_mfma_f32_16x16x32_f16 v[0:3], v[156:159], v[216:219], v[0:3]
	v_mfma_f32_16x16x32_f16 v[56:59], v[152:155], v[192:195], v[56:59]
	v_mfma_f32_16x16x32_f16 v[48:51], v[176:179], v[192:195], v[48:51]
	v_mfma_f32_16x16x32_f16 v[40:43], v[152:155], v[200:203], v[40:43]
	v_mfma_f32_16x16x32_f16 v[32:35], v[176:179], v[200:203], v[32:35]
	v_mfma_f32_16x16x32_f16 v[24:27], v[152:155], v[212:215], v[24:27]
	v_mfma_f32_16x16x32_f16 v[16:19], v[176:179], v[212:215], v[16:19]
	v_mfma_f32_16x16x32_f16 v[8:11], v[152:155], v[220:223], v[8:11]
	v_mfma_f32_16x16x32_f16 v[0:3], v[176:179], v[220:223], v[0:3]
	s_add_i32 s79, s79, 2
	s_add_u32 s34, s34, 0x100
	s_addc_u32 s35, s35, 0
	s_add_u32 s75, s75, 0x100
	s_addc_u32 s78, s78, 0
	s_cmp_gt_u32 s79, 13
	s_setprio 0
	s_barrier
	s_cbranch_scc1 .LBB0_3334
